# speedup vs baseline: 1.0248x; 1.0006x over previous
; #define PG8_STAGE(bufoff, gbase, voff) do { _Pragma("unroll") for (int _i = 0; _i < 2; ++_i) \
;         __builtin_amdgcn_global_load_lds((const unsigned*)((const char*)(gbase) + (voff)[_i]), (LAS unsigned*)(lds + (bufoff) + ldsw + _i * 8192), 16, 0, 0); } while (0)
; #define PG8_LDA(dst, b, h) do { _Pragma("unroll") for (int m = 0; m < 4; ++m) _Pragma("unroll") for (int k = 0; k < 2; ++k) dst[m][k] = *(const LAS bf16x8*)(lds + PG8_SA(b, h) + aoff + m * 2048 + k * 1024); } while (0)
; #define PG8_LDB(dst, b, h) do { _Pragma("unroll") for (int n = 0; n < 2; ++n) _Pragma("unroll") for (int k = 0; k < 2; ++k) dst[n][k] = *(const LAS bf16x8*)(lds + PG8_SB(b, h) + boff + n * 2048 + k * 1024); } while (0)
; #define PG8_MMA(ai, bj, At, Bt) do { __builtin_amdgcn_s_setprio(1); _Pragma("unroll") for (int m = 0; m < 4; ++m) _Pragma("unroll") for (int n = 0; n < 2; ++n) _Pragma("unroll") for (int k = 0; k < 2; ++k) \
;         acc[ai][bj][m][n] = __builtin_amdgcn_mfma_f32_16x16x32_bf16(Bt[n][k], At[m][k], acc[ai][bj][m][n], 0, 0, 0); __builtin_amdgcn_s_setprio(0); } while (0)
; #define PG8_WAIT_V(n) asm volatile("s_waitcnt vmcnt(" #n ")" ::: "memory")
; #define PG8_WAIT_L(n) asm volatile("s_waitcnt lgkmcnt(" #n ")" ::: "memory")
; #define PG8_BAR __builtin_amdgcn_s_barrier()
; #define PG8_SCHED __builtin_amdgcn_sched_barrier(0)
;     ...
;             PG8_LDB(B0, 0, 0); PG8_SCHED; PG8_LDA(At, 0, 0); PG8_STAGE(PG8_SA(1, 1), a1 + hstep, voffA);
;             PG8_WAIT_L(8); PG8_BAR; PG8_WAIT_L(0); PG8_MMA(0, 0, At, B0); PG8_BAR; PG8_SCHED;
;             PG8_LDB(B1, 0, 1); PG8_STAGE(PG8_SB(0, 0), b2, voffB);
;             PG8_BAR; PG8_WAIT_L(0); PG8_MMA(0, 1, At, B1); PG8_BAR;
;             PG8_LDA(At, 0, 1); PG8_STAGE(PG8_SA(0, 0), a2, voffA);
;             PG8_BAR; PG8_WAIT_L(0); PG8_MMA(1, 0, At, B0); PG8_BAR; PG8_SCHED;
;             PG8_STAGE(PG8_SB(0, 1), b2 + hstep, voffB);
;             PG8_WAIT_V(6); PG8_BAR; PG8_MMA(1, 1, At, B1); PG8_BAR;
.LBB0_120:
	s_add_i32 s44, s2, 2
	s_add_u32 s10, s8, 0x100
	s_addc_u32 s11, s9, 0
	s_add_i32 s35, 0, 0x10000
	v_add_u32_e32 v156, s35, v145
	ds_read_b128 v[140:143], v156
	ds_read_b128 v[148:151], v156 offset:1024
	ds_read_b128 v[152:155], v156 offset:2048
	ds_read_b128 v[156:159], v156 offset:3072
	s_cmp_eq_u32 s41, s2
	s_cselect_b32 s2, s6, s10
	s_cselect_b32 s3, s7, s11
	s_cselect_b32 s13, s19, s43
	s_cselect_b32 s12, s18, s42
	v_lshl_add_u64 v[192:193], s[8:9], 0, v[136:137]
	s_add_i32 m0, s21, 0xc000
	ds_read_b128 v[160:163], v147
	ds_read_b128 v[164:167], v147 offset:1024
	ds_read_b128 v[168:171], v147 offset:2048
	ds_read_b128 v[172:175], v147 offset:3072
	ds_read_b128 v[176:179], v147 offset:4096
	ds_read_b128 v[180:183], v147 offset:5120
	ds_read_b128 v[184:187], v147 offset:6144
	ds_read_b128 v[188:191], v147 offset:7168
	global_load_lds_dwordx4 v[192:193], off
	v_lshl_add_u64 v[192:193], s[8:9], 0, v[138:139]
	s_add_i32 m0, s21, 0xe000
	s_nop 0
	global_load_lds_dwordx4 v[192:193], off
	s_waitcnt lgkmcnt(8)
	s_barrier
	s_waitcnt lgkmcnt(0)
	v_mfma_f32_16x16x32_bf16 v[126:129], v[140:143], v[160:163], v[126:129]
	v_mfma_f32_16x16x32_bf16 v[122:125], v[152:155], v[160:163], v[122:125]
	v_mfma_f32_16x16x32_bf16 v[110:113], v[140:143], v[168:171], v[110:113]
	v_mfma_f32_16x16x32_bf16 v[106:109], v[152:155], v[168:171], v[106:109]
	v_mfma_f32_16x16x32_bf16 v[94:97], v[140:143], v[176:179], v[94:97]
	v_mfma_f32_16x16x32_bf16 v[90:93], v[152:155], v[176:179], v[90:93]
	v_mfma_f32_16x16x32_bf16 v[78:81], v[140:143], v[184:187], v[78:81]
	v_mfma_f32_16x16x32_bf16 v[74:77], v[152:155], v[184:187], v[74:77]
	v_mfma_f32_16x16x32_bf16 v[126:129], v[148:151], v[164:167], v[126:129]
	v_mfma_f32_16x16x32_bf16 v[122:125], v[156:159], v[164:167], v[122:125]
	v_mfma_f32_16x16x32_bf16 v[110:113], v[148:151], v[172:175], v[110:113]
	v_mfma_f32_16x16x32_bf16 v[106:109], v[156:159], v[172:175], v[106:109]
	v_mfma_f32_16x16x32_bf16 v[94:97], v[148:151], v[180:183], v[94:97]
	v_mfma_f32_16x16x32_bf16 v[90:93], v[156:159], v[180:183], v[90:93]
	v_mfma_f32_16x16x32_bf16 v[78:81], v[148:151], v[188:191], v[78:81]
	v_mfma_f32_16x16x32_bf16 v[74:77], v[156:159], v[188:191], v[74:77]
	s_barrier
	s_add_i32 s45, 0, 0x14000
	v_add_u32_e32 v208, s45, v145
	s_add_i32 s8, s35, s20
	ds_read_b128 v[192:195], v208
	ds_read_b128 v[196:199], v208 offset:1024
	ds_read_b128 v[220:223], v208 offset:2048
	ds_read_b128 v[224:227], v208 offset:3072
	v_lshl_add_u64 v[208:209], s[12:13], 0, v[64:65]
	s_mov_b32 m0, s8
	v_lshl_add_u64 v[210:211], s[12:13], 0, v[134:135]
	global_load_lds_dwordx4 v[208:209], off
	s_add_i32 m0, s8, 0x2000
	s_nop 0
	global_load_lds_dwordx4 v[210:211], off
	s_barrier
	s_waitcnt lgkmcnt(0)
	v_mfma_f32_16x16x32_bf16 v[118:121], v[192:195], v[160:163], v[118:121]
	v_mfma_f32_16x16x32_bf16 v[114:117], v[220:223], v[160:163], v[114:117]
	v_mfma_f32_16x16x32_bf16 v[102:105], v[192:195], v[168:171], v[102:105]
	v_mfma_f32_16x16x32_bf16 v[98:101], v[220:223], v[168:171], v[98:101]
	v_mfma_f32_16x16x32_bf16 v[86:89], v[192:195], v[176:179], v[86:89]
	v_mfma_f32_16x16x32_bf16 v[82:85], v[220:223], v[176:179], v[82:85]
	v_mfma_f32_16x16x32_bf16 v[70:73], v[192:195], v[184:187], v[70:73]
	v_mfma_f32_16x16x32_bf16 v[66:69], v[220:223], v[184:187], v[66:69]
	v_mfma_f32_16x16x32_bf16 v[118:121], v[196:199], v[164:167], v[118:121]
	v_mfma_f32_16x16x32_bf16 v[114:117], v[224:227], v[164:167], v[114:117]
	v_mfma_f32_16x16x32_bf16 v[102:105], v[196:199], v[172:175], v[102:105]
	v_mfma_f32_16x16x32_bf16 v[98:101], v[224:227], v[172:175], v[98:101]
	v_mfma_f32_16x16x32_bf16 v[86:89], v[196:199], v[180:183], v[86:89]
	v_mfma_f32_16x16x32_bf16 v[82:85], v[224:227], v[180:183], v[82:85]
	v_mfma_f32_16x16x32_bf16 v[70:73], v[196:199], v[188:191], v[70:73]
	v_mfma_f32_16x16x32_bf16 v[66:69], v[224:227], v[188:191], v[66:69]
	s_mov_b32 m0, s21
	v_lshl_add_u64 v[212:213], s[2:3], 0, v[130:131]
	s_barrier
	ds_read_b128 v[160:163], v147 offset:16384
	ds_read_b128 v[164:167], v147 offset:17408
	ds_read_b128 v[168:171], v147 offset:18432
	ds_read_b128 v[172:175], v147 offset:19456
	ds_read_b128 v[176:179], v147 offset:20480
	ds_read_b128 v[180:183], v147 offset:21504
	ds_read_b128 v[184:187], v147 offset:22528
	ds_read_b128 v[188:191], v147 offset:23552
	global_load_lds_dwordx4 v[212:213], off
	v_lshl_add_u64 v[214:215], s[2:3], 0, v[132:133]
	s_mov_b32 m0, s22
	s_nop 0
	global_load_lds_dwordx4 v[214:215], off
	s_barrier
	s_waitcnt lgkmcnt(0)
	v_mfma_f32_16x16x32_bf16 v[60:63], v[140:143], v[160:163], v[60:63]
	v_mfma_f32_16x16x32_bf16 v[56:59], v[152:155], v[160:163], v[56:59]
	v_mfma_f32_16x16x32_bf16 v[44:47], v[140:143], v[168:171], v[44:47]
	v_mfma_f32_16x16x32_bf16 v[40:43], v[152:155], v[168:171], v[40:43]
	v_mfma_f32_16x16x32_bf16 v[28:31], v[140:143], v[176:179], v[28:31]
	v_mfma_f32_16x16x32_bf16 v[24:27], v[152:155], v[176:179], v[24:27]
	v_mfma_f32_16x16x32_bf16 v[12:15], v[140:143], v[184:187], v[12:15]
	v_mfma_f32_16x16x32_bf16 v[8:11], v[152:155], v[184:187], v[8:11]
	v_mfma_f32_16x16x32_bf16 v[60:63], v[148:151], v[164:167], v[60:63]
	v_mfma_f32_16x16x32_bf16 v[56:59], v[156:159], v[164:167], v[56:59]
	v_mfma_f32_16x16x32_bf16 v[44:47], v[148:151], v[172:175], v[44:47]
	v_mfma_f32_16x16x32_bf16 v[40:43], v[156:159], v[172:175], v[40:43]
	v_mfma_f32_16x16x32_bf16 v[28:31], v[148:151], v[180:183], v[28:31]
	v_mfma_f32_16x16x32_bf16 v[24:27], v[156:159], v[180:183], v[24:27]
	v_mfma_f32_16x16x32_bf16 v[12:15], v[148:151], v[188:191], v[12:15]
	v_mfma_f32_16x16x32_bf16 v[8:11], v[156:159], v[188:191], v[8:11]
	s_barrier
; #define PG8_STAGE(bufoff, gbase, voff) do { _Pragma("unroll") for (int _i = 0; _i < 2; ++_i) \
;         __builtin_amdgcn_global_load_lds((const unsigned*)((const char*)(gbase) + (voff)[_i]), (LAS unsigned*)(lds + (bufoff) + ldsw + _i * 8192), 16, 0, 0); } while (0)
; #define PG8_LDA(dst, b, h) do { _Pragma("unroll") for (int m = 0; m < 4; ++m) _Pragma("unroll") for (int k = 0; k < 2; ++k) dst[m][k] = *(const LAS bf16x8*)(lds + PG8_SA(b, h) + aoff + m * 2048 + k * 1024); } while (0)
; #define PG8_LDB(dst, b, h) do { _Pragma("unroll") for (int n = 0; n < 2; ++n) _Pragma("unroll") for (int k = 0; k < 2; ++k) dst[n][k] = *(const LAS bf16x8*)(lds + PG8_SB(b, h) + boff + n * 2048 + k * 1024); } while (0)
; #define PG8_MMA(ai, bj, At, Bt) do { __builtin_amdgcn_s_setprio(1); _Pragma("unroll") for (int m = 0; m < 4; ++m) _Pragma("unroll") for (int n = 0; n < 2; ++n) _Pragma("unroll") for (int k = 0; k < 2; ++k) \
;         acc[ai][bj][m][n] = __builtin_amdgcn_mfma_f32_16x16x32_bf16(Bt[n][k], At[m][k], acc[ai][bj][m][n], 0, 0, 0); __builtin_amdgcn_s_setprio(0); } while (0)
; #define PG8_WAIT_V(n) asm volatile("s_waitcnt vmcnt(" #n ")" ::: "memory")
; #define PG8_WAIT_L(n) asm volatile("s_waitcnt lgkmcnt(" #n ")" ::: "memory")
; #define PG8_BAR __builtin_amdgcn_s_barrier()
; #define PG8_SCHED __builtin_amdgcn_sched_barrier(0)
;     ...
;             PG8_STAGE(PG8_SB(0, 1), b2 + hstep, voffB);
;             PG8_WAIT_V(6); PG8_BAR; PG8_MMA(1, 1, At, B1); PG8_BAR;
;             PG8_LDB(B0, 1, 0); PG8_SCHED; PG8_LDA(At, 1, 0); PG8_STAGE(PG8_SA(0, 1), a2 + hstep, voffA);
;             PG8_WAIT_L(8); PG8_BAR; PG8_WAIT_L(0); PG8_MMA(0, 0, At, B0); PG8_BAR; PG8_SCHED;
;             PG8_LDB(B1, 1, 1); PG8_STAGE(PG8_SB(1, 0), b3, voffB);
;             PG8_BAR; PG8_WAIT_L(0); PG8_MMA(0, 1, At, B1); PG8_BAR;
;             PG8_LDA(At, 1, 1); PG8_STAGE(PG8_SA(1, 0), a3, voffA);
;             PG8_BAR; PG8_WAIT_L(0); PG8_MMA(1, 0, At, B0); PG8_BAR; PG8_SCHED;
;             PG8_STAGE(PG8_SB(1, 1), b3 + hstep, voffB);
	s_add_u32 s8, s12, 0x84000
	s_addc_u32 s9, s13, 0
	s_add_i32 s35, s45, s20
	v_lshl_add_u64 v[140:141], s[8:9], 0, v[64:65]
	s_mov_b32 m0, s35
	s_nop 0
	global_load_lds_dwordx4 v[140:141], off
	v_lshl_add_u64 v[140:141], s[8:9], 0, v[134:135]
	s_add_i32 m0, s35, 0x2000
	s_nop 0
	global_load_lds_dwordx4 v[140:141], off
	s_waitcnt vmcnt(6)
	s_barrier
	v_mfma_f32_16x16x32_bf16 v[52:55], v[192:195], v[160:163], v[52:55]
	v_mfma_f32_16x16x32_bf16 v[48:51], v[220:223], v[160:163], v[48:51]
	v_mfma_f32_16x16x32_bf16 v[36:39], v[192:195], v[168:171], v[36:39]
	v_mfma_f32_16x16x32_bf16 v[32:35], v[220:223], v[168:171], v[32:35]
	v_mfma_f32_16x16x32_bf16 v[20:23], v[192:195], v[176:179], v[20:23]
	v_mfma_f32_16x16x32_bf16 v[16:19], v[220:223], v[176:179], v[16:19]
	v_mfma_f32_16x16x32_bf16 v[4:7], v[192:195], v[184:187], v[4:7]
	v_mfma_f32_16x16x32_bf16 v[0:3], v[220:223], v[184:187], v[0:3]
	v_mfma_f32_16x16x32_bf16 v[52:55], v[196:199], v[164:167], v[52:55]
	v_mfma_f32_16x16x32_bf16 v[48:51], v[224:227], v[164:167], v[48:51]
	v_mfma_f32_16x16x32_bf16 v[36:39], v[196:199], v[172:175], v[36:39]
	v_mfma_f32_16x16x32_bf16 v[32:35], v[224:227], v[172:175], v[32:35]
	v_mfma_f32_16x16x32_bf16 v[20:23], v[196:199], v[180:183], v[20:23]
	v_mfma_f32_16x16x32_bf16 v[16:19], v[224:227], v[180:183], v[16:19]
	v_mfma_f32_16x16x32_bf16 v[4:7], v[196:199], v[188:191], v[4:7]
	v_mfma_f32_16x16x32_bf16 v[0:3], v[224:227], v[188:191], v[0:3]
	s_add_i32 s8, 0, 0x18000
	v_add_u32_e32 v156, s8, v145
	s_barrier
	ds_read_b128 v[140:143], v156
	ds_read_b128 v[148:151], v156 offset:1024
	ds_read_b128 v[152:155], v156 offset:2048
	ds_read_b128 v[156:159], v156 offset:3072
	s_add_u32 s2, s2, 0x84000
	s_addc_u32 s3, s3, 0
	s_mov_b32 m0, s23
	v_lshl_add_u64 v[192:193], s[2:3], 0, v[130:131]
	ds_read_b128 v[160:163], v147 offset:32768
	ds_read_b128 v[164:167], v147 offset:33792
	ds_read_b128 v[168:171], v147 offset:34816
	ds_read_b128 v[172:175], v147 offset:35840
	ds_read_b128 v[176:179], v147 offset:36864
	ds_read_b128 v[180:183], v147 offset:37888
	ds_read_b128 v[184:187], v147 offset:38912
	ds_read_b128 v[188:191], v147 offset:39936
	global_load_lds_dwordx4 v[192:193], off
	v_lshl_add_u64 v[192:193], s[2:3], 0, v[132:133]
	s_mov_b32 m0, s24
	s_nop 0
	global_load_lds_dwordx4 v[192:193], off
	s_waitcnt lgkmcnt(8)
	s_barrier
	s_waitcnt lgkmcnt(0)
	v_mfma_f32_16x16x32_bf16 v[126:129], v[140:143], v[160:163], v[126:129]
	v_mfma_f32_16x16x32_bf16 v[122:125], v[152:155], v[160:163], v[122:125]
	v_mfma_f32_16x16x32_bf16 v[110:113], v[140:143], v[168:171], v[110:113]
	v_mfma_f32_16x16x32_bf16 v[106:109], v[152:155], v[168:171], v[106:109]
	v_mfma_f32_16x16x32_bf16 v[94:97], v[140:143], v[176:179], v[94:97]
	v_mfma_f32_16x16x32_bf16 v[90:93], v[152:155], v[176:179], v[90:93]
	v_mfma_f32_16x16x32_bf16 v[78:81], v[140:143], v[184:187], v[78:81]
	v_mfma_f32_16x16x32_bf16 v[74:77], v[152:155], v[184:187], v[74:77]
	v_mfma_f32_16x16x32_bf16 v[126:129], v[148:151], v[164:167], v[126:129]
	v_mfma_f32_16x16x32_bf16 v[122:125], v[156:159], v[164:167], v[122:125]
	v_mfma_f32_16x16x32_bf16 v[110:113], v[148:151], v[172:175], v[110:113]
	v_mfma_f32_16x16x32_bf16 v[106:109], v[156:159], v[172:175], v[106:109]
	v_mfma_f32_16x16x32_bf16 v[94:97], v[148:151], v[180:183], v[94:97]
	v_mfma_f32_16x16x32_bf16 v[90:93], v[156:159], v[180:183], v[90:93]
	v_mfma_f32_16x16x32_bf16 v[78:81], v[148:151], v[188:191], v[78:81]
	v_mfma_f32_16x16x32_bf16 v[74:77], v[156:159], v[188:191], v[74:77]
	s_barrier
	s_add_i32 s9, 0, 0x1c000
	s_add_i32 s2, s8, s20
	v_add_u32_e32 v219, s9, v145
	v_lshl_add_u64 v[208:209], v[208:209], 0, s[16:17]
	s_mov_b32 m0, s2
	ds_read_b128 v[192:195], v219
	ds_read_b128 v[196:199], v219 offset:1024
	ds_read_b128 v[220:223], v219 offset:2048
	ds_read_b128 v[224:227], v219 offset:3072
	global_load_lds_dwordx4 v[208:209], off
	v_lshl_add_u64 v[208:209], v[210:211], 0, s[16:17]
	s_add_i32 m0, s2, 0x2000
	s_nop 0
	global_load_lds_dwordx4 v[208:209], off
	s_barrier
	s_waitcnt lgkmcnt(0)
	v_mfma_f32_16x16x32_bf16 v[118:121], v[192:195], v[160:163], v[118:121]
	v_mfma_f32_16x16x32_bf16 v[114:117], v[220:223], v[160:163], v[114:117]
	v_mfma_f32_16x16x32_bf16 v[102:105], v[192:195], v[168:171], v[102:105]
	v_mfma_f32_16x16x32_bf16 v[98:101], v[220:223], v[168:171], v[98:101]
	v_mfma_f32_16x16x32_bf16 v[86:89], v[192:195], v[176:179], v[86:89]
	v_mfma_f32_16x16x32_bf16 v[82:85], v[220:223], v[176:179], v[82:85]
	v_mfma_f32_16x16x32_bf16 v[70:73], v[192:195], v[184:187], v[70:73]
	v_mfma_f32_16x16x32_bf16 v[66:69], v[220:223], v[184:187], v[66:69]
	v_mfma_f32_16x16x32_bf16 v[118:121], v[196:199], v[164:167], v[118:121]
	v_mfma_f32_16x16x32_bf16 v[114:117], v[224:227], v[164:167], v[114:117]
	v_mfma_f32_16x16x32_bf16 v[102:105], v[196:199], v[172:175], v[102:105]
	v_mfma_f32_16x16x32_bf16 v[98:101], v[224:227], v[172:175], v[98:101]
	v_mfma_f32_16x16x32_bf16 v[86:89], v[196:199], v[180:183], v[86:89]
	v_mfma_f32_16x16x32_bf16 v[82:85], v[224:227], v[180:183], v[82:85]
	v_mfma_f32_16x16x32_bf16 v[70:73], v[196:199], v[188:191], v[70:73]
	v_mfma_f32_16x16x32_bf16 v[66:69], v[224:227], v[188:191], v[66:69]
	s_mov_b32 m0, s25
	v_lshl_add_u64 v[208:209], v[212:213], 0, s[16:17]
	s_barrier
	ds_read_b128 v[160:163], v147 offset:49152
	ds_read_b128 v[164:167], v147 offset:50176
	ds_read_b128 v[168:171], v147 offset:51200
	ds_read_b128 v[172:175], v147 offset:52224
	ds_read_b128 v[176:179], v147 offset:53248
	ds_read_b128 v[180:183], v147 offset:54272
	ds_read_b128 v[184:187], v147 offset:55296
	ds_read_b128 v[188:191], v147 offset:56320
	global_load_lds_dwordx4 v[208:209], off
	v_lshl_add_u64 v[208:209], v[214:215], 0, s[16:17]
	s_mov_b32 m0, s26
	s_nop 0
	global_load_lds_dwordx4 v[208:209], off
	s_barrier
; __device__ __forceinline__ unsigned cvt_pk_bf16(float lo, float hi) { unsigned r; asm volatile("v_cvt_pk_bf16_f32 %0, %1, %2" : "=v"(r) : "v"(lo), "v"(hi)); return r; }
; #define PG8_STAGE(bufoff, gbase, voff) do { _Pragma("unroll") for (int _i = 0; _i < 2; ++_i) \
;         __builtin_amdgcn_global_load_lds((const unsigned*)((const char*)(gbase) + (voff)[_i]), (LAS unsigned*)(lds + (bufoff) + ldsw + _i * 8192), 16, 0, 0); } while (0)
; #define PG8_MMA(ai, bj, At, Bt) do { __builtin_amdgcn_s_setprio(1); _Pragma("unroll") for (int m = 0; m < 4; ++m) _Pragma("unroll") for (int n = 0; n < 2; ++n) _Pragma("unroll") for (int k = 0; k < 2; ++k) \
;         acc[ai][bj][m][n] = __builtin_amdgcn_mfma_f32_16x16x32_bf16(Bt[n][k], At[m][k], acc[ai][bj][m][n], 0, 0, 0); __builtin_amdgcn_s_setprio(0); } while (0)
; #define PG8_WAIT_V(n) asm volatile("s_waitcnt vmcnt(" #n ")" ::: "memory")
; #define PG8_WAIT_L(n) asm volatile("s_waitcnt lgkmcnt(" #n ")" ::: "memory")
; #define PG8_BAR __builtin_amdgcn_s_barrier()
; #define PG8_SCHED __builtin_amdgcn_sched_barrier(0)
;     __device__ __forceinline__ void operator()(const f32x4 (&acc)[2][2][4][2], const Unit& u, int wr, int wc, int fr, int fq) const {
;         const int row0 = u.pm * BM + wr * 64 + fr, col0 = u.pn * BM + wc * 32 + 8 * fq;
; #pragma unroll
;         for (int ai = 0; ai < 2; ++ai)
; #pragma unroll
;             for (int m = 0; m < 4; ++m) { bf16_t* rowp = O + (size_t)(row0 + ai * HALF + m * 16) * LDF + col0;
; #pragma unroll
;                 for (int bj = 0; bj < 2; ++bj) { f32x4 v0 = acc[ai][bj][m][0], v1 = acc[ai][bj][m][1];
; #pragma unroll
;                     for (int j = 0; j < 4; ++j) { const float a = fmaxf(v0[j], 0.f), b = fmaxf(v1[j], 0.f); v0[j] = a * a; v1[j] = b * b; }
;                     u32x4 w; w.x = cvt_pk_bf16(v0[0], v0[1]); w.y = cvt_pk_bf16(v0[2], v0[3]); w.z = cvt_pk_bf16(v1[0], v1[1]); w.w = cvt_pk_bf16(v1[2], v1[3]);
;                     *(u32x4*)(rowp + bj * HALF) = w; } }
;     ...
;             PG8_BAR; PG8_WAIT_L(0); PG8_MMA(1, 0, At, B0); PG8_BAR; PG8_SCHED;
;             PG8_STAGE(PG8_SB(1, 1), b3 + hstep, voffB);
;             PG8_WAIT_V(6); PG8_BAR; PG8_MMA(1, 1, At, B1); PG8_BAR;
;         }
	s_waitcnt lgkmcnt(0)
	v_mfma_f32_16x16x32_bf16 v[60:63], v[140:143], v[160:163], v[60:63]
	v_mfma_f32_16x16x32_bf16 v[56:59], v[152:155], v[160:163], v[56:59]
	v_mfma_f32_16x16x32_bf16 v[44:47], v[140:143], v[168:171], v[44:47]
	v_mfma_f32_16x16x32_bf16 v[40:43], v[152:155], v[168:171], v[40:43]
	v_mfma_f32_16x16x32_bf16 v[28:31], v[140:143], v[176:179], v[28:31]
	v_mfma_f32_16x16x32_bf16 v[24:27], v[152:155], v[176:179], v[24:27]
	v_mfma_f32_16x16x32_bf16 v[12:15], v[140:143], v[184:187], v[12:15]
	v_mfma_f32_16x16x32_bf16 v[8:11], v[152:155], v[184:187], v[8:11]
	v_mfma_f32_16x16x32_bf16 v[60:63], v[148:151], v[164:167], v[60:63]
	v_mfma_f32_16x16x32_bf16 v[56:59], v[156:159], v[164:167], v[56:59]
	v_mfma_f32_16x16x32_bf16 v[44:47], v[148:151], v[172:175], v[44:47]
	v_mfma_f32_16x16x32_bf16 v[40:43], v[156:159], v[172:175], v[40:43]
	v_mfma_f32_16x16x32_bf16 v[28:31], v[148:151], v[180:183], v[28:31]
	v_mfma_f32_16x16x32_bf16 v[24:27], v[156:159], v[180:183], v[24:27]
	v_mfma_f32_16x16x32_bf16 v[12:15], v[148:151], v[188:191], v[12:15]
	v_mfma_f32_16x16x32_bf16 v[8:11], v[156:159], v[188:191], v[8:11]
	s_barrier
	s_add_u32 s2, s12, 0x84080
	s_addc_u32 s3, s13, 0
	s_add_i32 s8, s9, s20
	v_lshl_add_u64 v[140:141], s[2:3], 0, v[64:65]
	s_mov_b32 m0, s8
	s_nop 0
	global_load_lds_dwordx4 v[140:141], off
	v_lshl_add_u64 v[140:141], s[2:3], 0, v[134:135]
	s_add_i32 m0, s8, 0x2000
	s_nop 0
	global_load_lds_dwordx4 v[140:141], off
	s_waitcnt vmcnt(6)
	s_barrier
	v_mfma_f32_16x16x32_bf16 v[52:55], v[192:195], v[160:163], v[52:55]
	v_mfma_f32_16x16x32_bf16 v[48:51], v[220:223], v[160:163], v[48:51]
	v_mfma_f32_16x16x32_bf16 v[36:39], v[192:195], v[168:171], v[36:39]
	v_mfma_f32_16x16x32_bf16 v[32:35], v[220:223], v[168:171], v[32:35]
	v_mfma_f32_16x16x32_bf16 v[20:23], v[192:195], v[176:179], v[20:23]
	v_mfma_f32_16x16x32_bf16 v[16:19], v[220:223], v[176:179], v[16:19]
	v_mfma_f32_16x16x32_bf16 v[4:7], v[192:195], v[184:187], v[4:7]
	v_mfma_f32_16x16x32_bf16 v[0:3], v[220:223], v[184:187], v[0:3]
	v_mfma_f32_16x16x32_bf16 v[52:55], v[196:199], v[164:167], v[52:55]
	v_mfma_f32_16x16x32_bf16 v[48:51], v[224:227], v[164:167], v[48:51]
	v_mfma_f32_16x16x32_bf16 v[36:39], v[196:199], v[172:175], v[36:39]
	v_mfma_f32_16x16x32_bf16 v[32:35], v[224:227], v[172:175], v[32:35]
	v_mfma_f32_16x16x32_bf16 v[20:23], v[196:199], v[180:183], v[20:23]
	v_mfma_f32_16x16x32_bf16 v[16:19], v[224:227], v[180:183], v[16:19]
	v_mfma_f32_16x16x32_bf16 v[4:7], v[196:199], v[188:191], v[4:7]
	v_mfma_f32_16x16x32_bf16 v[0:3], v[224:227], v[188:191], v[0:3]
	s_add_u32 s42, s42, 0x100
	s_addc_u32 s43, s43, 0
	s_cmp_ge_u32 s44, s40
	s_mov_b64 s[8:9], s[10:11]
	s_mov_b32 s2, s44
	s_barrier
	s_cbranch_scc0 .LBB0_120
	v_max_f32_e32 v122, 0, v122
	v_lshl_or_b32 v142, s37, 8, v146
	v_mul_f32_e32 v151, v122, v122
	v_max_f32_e32 v122, v127, v127
	v_max_f32_e32 v123, 0, v123
	v_max_f32_e32 v124, 0, v124
	v_lshl_add_u32 v150, s38, 8, v144
	v_ashrrev_i32_e32 v143, 31, v142
	v_mov_b64_e32 v[140:141], s[80:81]
	s_movk_i32 s8, 0x4080
	v_max_f32_e32 v122, 0, v122
	v_mul_f32_e32 v127, v123, v123
	v_max_f32_e32 v123, v128, v128
	v_mul_f32_e32 v128, v124, v124
	v_max_f32_e32 v124, v129, v129
	v_mad_i64_i32 v[148:149], s[2:3], v150, s8, v[140:141]
	v_lshlrev_b64 v[142:143], 1, v[142:143]
	v_max_f32_e32 v126, 0, v126
	v_mul_f32_e32 v122, v122, v122
	v_max_f32_e32 v123, 0, v123
	v_max_f32_e32 v124, 0, v124
	v_max_f32_e32 v125, 0, v125
	v_lshl_add_u64 v[148:149], v[148:149], 0, v[142:143]
	v_mul_f32_e32 v126, v126, v126
	v_mul_f32_e32 v123, v123, v123
	v_mul_f32_e32 v124, v124, v124
	v_mul_f32_e32 v125, v125, v125
	v_cvt_pk_bf16_f32 v122, v126, v122
	v_max_f32_e32 v114, 0, v114
	v_max_f32_e32 v115, 0, v115
	v_max_f32_e32 v116, 0, v116
	v_cvt_pk_bf16_f32 v123, v123, v124
	v_cvt_pk_bf16_f32 v124, v151, v127
	v_cvt_pk_bf16_f32 v125, v128, v125
	global_store_dwordx4 v[148:149], v[122:125], off
	s_nop 1
	v_mul_f32_e32 v122, v114, v114
	v_max_f32_e32 v114, v119, v119
	v_mul_f32_e32 v119, v115, v115
	v_max_f32_e32 v115, v120, v120
	v_mul_f32_e32 v120, v116, v116
	v_max_f32_e32 v116, v121, v121
	v_max_f32_e32 v114, 0, v114
	v_max_f32_e32 v115, 0, v115
	v_max_f32_e32 v116, 0, v116
	v_max_f32_e32 v118, 0, v118
	v_mul_f32_e32 v114, v114, v114
	v_mul_f32_e32 v115, v115, v115
	v_max_f32_e32 v117, 0, v117
	v_mul_f32_e32 v116, v116, v116
	v_mul_f32_e32 v118, v118, v118
	v_mul_f32_e32 v117, v117, v117
	v_cvt_pk_bf16_f32 v114, v118, v114
	v_cvt_pk_bf16_f32 v115, v115, v116
	v_cvt_pk_bf16_f32 v116, v122, v119
	v_max_f32_e32 v106, 0, v106
	v_cvt_pk_bf16_f32 v117, v120, v117
	global_store_dwordx4 v[148:149], v[114:117], off offset:256
	s_nop 1
	v_max_f32_e32 v107, 0, v107
	v_max_f32_e32 v108, 0, v108
	v_mul_f32_e32 v116, v106, v106
	v_max_f32_e32 v106, v111, v111
	v_or_b32_e32 v114, 16, v150
	v_max_f32_e32 v106, 0, v106
	v_mul_f32_e32 v111, v107, v107
	v_max_f32_e32 v107, v112, v112
	v_mul_f32_e32 v112, v108, v108
	v_max_f32_e32 v108, v113, v113
	v_mad_i64_i32 v[114:115], s[2:3], v114, s8, v[140:141]
	v_max_f32_e32 v110, 0, v110
	v_mul_f32_e32 v106, v106, v106
	v_max_f32_e32 v107, 0, v107
	v_max_f32_e32 v108, 0, v108
	v_max_f32_e32 v109, 0, v109
	v_lshl_add_u64 v[114:115], v[114:115], 0, v[142:143]
	v_mul_f32_e32 v110, v110, v110
	v_mul_f32_e32 v107, v107, v107
	v_mul_f32_e32 v108, v108, v108
	v_mul_f32_e32 v109, v109, v109
	v_cvt_pk_bf16_f32 v106, v110, v106
	v_max_f32_e32 v98, 0, v98
	v_max_f32_e32 v99, 0, v99
	v_max_f32_e32 v100, 0, v100
	v_cvt_pk_bf16_f32 v107, v107, v108
	v_cvt_pk_bf16_f32 v108, v116, v111
	v_cvt_pk_bf16_f32 v109, v112, v109
	global_store_dwordx4 v[114:115], v[106:109], off
	s_nop 1
; __device__ __forceinline__ unsigned cvt_pk_bf16(float lo, float hi) { unsigned r; asm volatile("v_cvt_pk_bf16_f32 %0, %1, %2" : "=v"(r) : "v"(lo), "v"(hi)); return r; }
;     __device__ __forceinline__ void operator()(const f32x4 (&acc)[2][2][4][2], const Unit& u, int wr, int wc, int fr, int fq) const {
;         const int row0 = u.pm * BM + wr * 64 + fr, col0 = u.pn * BM + wc * 32 + 8 * fq;
; #pragma unroll
;         for (int ai = 0; ai < 2; ++ai)
; #pragma unroll
;             for (int m = 0; m < 4; ++m) { bf16_t* rowp = O + (size_t)(row0 + ai * HALF + m * 16) * LDF + col0;
; #pragma unroll
;                 for (int bj = 0; bj < 2; ++bj) { f32x4 v0 = acc[ai][bj][m][0], v1 = acc[ai][bj][m][1];
; #pragma unroll
;                     for (int j = 0; j < 4; ++j) { const float a = fmaxf(v0[j], 0.f), b = fmaxf(v1[j], 0.f); v0[j] = a * a; v1[j] = b * b; }
;                     u32x4 w; w.x = cvt_pk_bf16(v0[0], v0[1]); w.y = cvt_pk_bf16(v0[2], v0[3]); w.z = cvt_pk_bf16(v1[0], v1[1]); w.w = cvt_pk_bf16(v1[2], v1[3]);
;                     *(u32x4*)(rowp + bj * HALF) = w; } }
	v_mul_f32_e32 v106, v98, v98
	v_max_f32_e32 v98, v103, v103
	v_mul_f32_e32 v103, v99, v99
	v_max_f32_e32 v99, v104, v104
	v_mul_f32_e32 v104, v100, v100
	v_max_f32_e32 v100, v105, v105
	v_max_f32_e32 v98, 0, v98
	v_max_f32_e32 v99, 0, v99
	v_max_f32_e32 v100, 0, v100
	v_max_f32_e32 v102, 0, v102
	v_mul_f32_e32 v98, v98, v98
	v_mul_f32_e32 v99, v99, v99
	v_max_f32_e32 v101, 0, v101
	v_mul_f32_e32 v100, v100, v100
	v_mul_f32_e32 v102, v102, v102
	v_mul_f32_e32 v101, v101, v101
	v_cvt_pk_bf16_f32 v98, v102, v98
	v_cvt_pk_bf16_f32 v99, v99, v100
	v_cvt_pk_bf16_f32 v100, v106, v103
	v_max_f32_e32 v90, 0, v90
	v_cvt_pk_bf16_f32 v101, v104, v101
	global_store_dwordx4 v[114:115], v[98:101], off offset:256
	s_nop 1
	v_max_f32_e32 v91, 0, v91
	v_max_f32_e32 v92, 0, v92
	v_mul_f32_e32 v100, v90, v90
	v_max_f32_e32 v90, v95, v95
	v_or_b32_e32 v98, 32, v150
	v_max_f32_e32 v90, 0, v90
	v_mul_f32_e32 v95, v91, v91
	v_max_f32_e32 v91, v96, v96
	v_mul_f32_e32 v96, v92, v92
	v_max_f32_e32 v92, v97, v97
	v_mad_i64_i32 v[98:99], s[2:3], v98, s8, v[140:141]
	v_max_f32_e32 v94, 0, v94
	v_mul_f32_e32 v90, v90, v90
	v_max_f32_e32 v91, 0, v91
	v_max_f32_e32 v92, 0, v92
	v_max_f32_e32 v93, 0, v93
	v_lshl_add_u64 v[98:99], v[98:99], 0, v[142:143]
	v_mul_f32_e32 v94, v94, v94
	v_mul_f32_e32 v91, v91, v91
	v_mul_f32_e32 v92, v92, v92
	v_mul_f32_e32 v93, v93, v93
	v_cvt_pk_bf16_f32 v90, v94, v90
	v_max_f32_e32 v82, 0, v82
	v_max_f32_e32 v83, 0, v83
	v_max_f32_e32 v84, 0, v84
	v_cvt_pk_bf16_f32 v91, v91, v92
	v_cvt_pk_bf16_f32 v92, v100, v95
	v_cvt_pk_bf16_f32 v93, v96, v93
	global_store_dwordx4 v[98:99], v[90:93], off
	s_nop 1
	v_mul_f32_e32 v90, v82, v82
	v_max_f32_e32 v82, v87, v87
	v_mul_f32_e32 v87, v83, v83
	v_max_f32_e32 v83, v88, v88
	v_mul_f32_e32 v88, v84, v84
	v_max_f32_e32 v84, v89, v89
	v_max_f32_e32 v82, 0, v82
	v_max_f32_e32 v83, 0, v83
	v_max_f32_e32 v84, 0, v84
	v_max_f32_e32 v86, 0, v86
	v_mul_f32_e32 v82, v82, v82
	v_mul_f32_e32 v83, v83, v83
	v_max_f32_e32 v85, 0, v85
	v_mul_f32_e32 v84, v84, v84
	v_mul_f32_e32 v86, v86, v86
	v_mul_f32_e32 v85, v85, v85
	v_cvt_pk_bf16_f32 v82, v86, v82
	v_cvt_pk_bf16_f32 v83, v83, v84
	v_cvt_pk_bf16_f32 v84, v90, v87
	v_max_f32_e32 v74, 0, v74
	v_cvt_pk_bf16_f32 v85, v88, v85
	global_store_dwordx4 v[98:99], v[82:85], off offset:256
	s_nop 1
	v_max_f32_e32 v75, 0, v75
	v_max_f32_e32 v76, 0, v76
	v_mul_f32_e32 v84, v74, v74
	v_max_f32_e32 v74, v79, v79
	v_or_b32_e32 v82, 48, v150
	v_max_f32_e32 v74, 0, v74
	v_mul_f32_e32 v79, v75, v75
	v_max_f32_e32 v75, v80, v80
	v_mul_f32_e32 v80, v76, v76
	v_max_f32_e32 v76, v81, v81
	v_mad_i64_i32 v[82:83], s[2:3], v82, s8, v[140:141]
	v_max_f32_e32 v78, 0, v78
	v_mul_f32_e32 v74, v74, v74
	v_max_f32_e32 v75, 0, v75
	v_max_f32_e32 v76, 0, v76
	v_max_f32_e32 v77, 0, v77
	v_lshl_add_u64 v[82:83], v[82:83], 0, v[142:143]
	v_mul_f32_e32 v78, v78, v78
	v_mul_f32_e32 v75, v75, v75
	v_mul_f32_e32 v76, v76, v76
	v_mul_f32_e32 v77, v77, v77
	v_cvt_pk_bf16_f32 v74, v78, v74
	v_max_f32_e32 v66, 0, v66
	v_max_f32_e32 v67, 0, v67
	v_max_f32_e32 v68, 0, v68
	v_cvt_pk_bf16_f32 v75, v75, v76
	v_cvt_pk_bf16_f32 v76, v84, v79
	v_cvt_pk_bf16_f32 v77, v80, v77
	global_store_dwordx4 v[82:83], v[74:77], off
	s_nop 1
	v_mul_f32_e32 v74, v66, v66
	v_max_f32_e32 v66, v71, v71
	v_mul_f32_e32 v71, v67, v67
	v_max_f32_e32 v67, v72, v72
	v_mul_f32_e32 v72, v68, v68
	v_max_f32_e32 v68, v73, v73
	v_max_f32_e32 v66, 0, v66
	v_max_f32_e32 v67, 0, v67
	v_max_f32_e32 v68, 0, v68
	v_max_f32_e32 v70, 0, v70
	v_mul_f32_e32 v66, v66, v66
	v_mul_f32_e32 v67, v67, v67
	v_max_f32_e32 v69, 0, v69
	v_mul_f32_e32 v68, v68, v68
	v_mul_f32_e32 v70, v70, v70
	v_mul_f32_e32 v69, v69, v69
	v_cvt_pk_bf16_f32 v66, v70, v66
	v_cvt_pk_bf16_f32 v67, v67, v68
	v_cvt_pk_bf16_f32 v68, v74, v71
	v_max_f32_e32 v56, 0, v56
	v_cvt_pk_bf16_f32 v69, v72, v69
	global_store_dwordx4 v[82:83], v[66:69], off offset:256
	s_nop 1
	v_max_f32_e32 v57, 0, v57
	v_max_f32_e32 v58, 0, v58
	v_mul_f32_e32 v68, v56, v56
	v_max_f32_e32 v56, v61, v61
	v_add_u32_e32 v66, 0x80, v150
	v_max_f32_e32 v56, 0, v56
	v_mul_f32_e32 v61, v57, v57
	v_max_f32_e32 v57, v62, v62
	v_mul_f32_e32 v62, v58, v58
	v_max_f32_e32 v58, v63, v63
	v_mad_i64_i32 v[66:67], s[2:3], v66, s8, v[140:141]
	v_max_f32_e32 v60, 0, v60
	v_mul_f32_e32 v56, v56, v56
	v_max_f32_e32 v57, 0, v57
	v_max_f32_e32 v58, 0, v58
	v_max_f32_e32 v59, 0, v59
	v_lshl_add_u64 v[66:67], v[66:67], 0, v[142:143]
	v_mul_f32_e32 v60, v60, v60
	v_mul_f32_e32 v57, v57, v57
	v_mul_f32_e32 v58, v58, v58
	v_mul_f32_e32 v59, v59, v59
	v_cvt_pk_bf16_f32 v56, v60, v56
	v_max_f32_e32 v48, 0, v48
	v_max_f32_e32 v49, 0, v49
	v_max_f32_e32 v50, 0, v50
	v_cvt_pk_bf16_f32 v57, v57, v58
	v_cvt_pk_bf16_f32 v58, v68, v61
	v_cvt_pk_bf16_f32 v59, v62, v59
	global_store_dwordx4 v[66:67], v[56:59], off
	s_nop 1
	v_mul_f32_e32 v56, v48, v48
	v_max_f32_e32 v48, v53, v53
	v_mul_f32_e32 v53, v49, v49
	v_max_f32_e32 v49, v54, v54
	v_mul_f32_e32 v54, v50, v50
	v_max_f32_e32 v50, v55, v55
	v_max_f32_e32 v48, 0, v48
	v_max_f32_e32 v49, 0, v49
	v_max_f32_e32 v50, 0, v50
	v_max_f32_e32 v52, 0, v52
	v_mul_f32_e32 v48, v48, v48
	v_mul_f32_e32 v49, v49, v49
	v_max_f32_e32 v51, 0, v51
	v_mul_f32_e32 v50, v50, v50
	v_mul_f32_e32 v52, v52, v52
	v_mul_f32_e32 v51, v51, v51
	v_cvt_pk_bf16_f32 v48, v52, v48
; __device__ __forceinline__ unsigned cvt_pk_bf16(float lo, float hi) { unsigned r; asm volatile("v_cvt_pk_bf16_f32 %0, %1, %2" : "=v"(r) : "v"(lo), "v"(hi)); return r; }
; #define PG8_WAIT_V(n) asm volatile("s_waitcnt vmcnt(" #n ")" ::: "memory")
; #define PG8_BAR __builtin_amdgcn_s_barrier()
;     __device__ __forceinline__ void operator()(const f32x4 (&acc)[2][2][4][2], const Unit& u, int wr, int wc, int fr, int fq) const {
;     ...
;             for (int m = 0; m < 4; ++m) { bf16_t* rowp = O + (size_t)(row0 + ai * HALF + m * 16) * LDF + col0;
; #pragma unroll
;                 for (int bj = 0; bj < 2; ++bj) { f32x4 v0 = acc[ai][bj][m][0], v1 = acc[ai][bj][m][1];
; #pragma unroll
;                     for (int j = 0; j < 4; ++j) { const float a = fmaxf(v0[j], 0.f), b = fmaxf(v1[j], 0.f); v0[j] = a * a; v1[j] = b * b; }
;                     u32x4 w; w.x = cvt_pk_bf16(v0[0], v0[1]); w.y = cvt_pk_bf16(v0[2], v0[3]); w.z = cvt_pk_bf16(v1[0], v1[1]); w.w = cvt_pk_bf16(v1[2], v1[3]);
;                     *(u32x4*)(rowp + bj * HALF) = w; } }
;     ...
;         cur = nxt; cA = nA; cB = nB; ++ui;
;     }
;     PG8_WAIT_V(0);
;     if (wr == 0) PG8_BAR;
	v_cvt_pk_bf16_f32 v49, v49, v50
	v_cvt_pk_bf16_f32 v50, v56, v53
	v_max_f32_e32 v40, 0, v40
	v_cvt_pk_bf16_f32 v51, v54, v51
	global_store_dwordx4 v[66:67], v[48:51], off offset:256
	s_nop 1
	v_max_f32_e32 v41, 0, v41
	v_max_f32_e32 v42, 0, v42
	v_mul_f32_e32 v50, v40, v40
	v_max_f32_e32 v40, v45, v45
	v_add_u32_e32 v48, 0x90, v150
	v_max_f32_e32 v40, 0, v40
	v_mul_f32_e32 v45, v41, v41
	v_max_f32_e32 v41, v46, v46
	v_mul_f32_e32 v46, v42, v42
	v_max_f32_e32 v42, v47, v47
	v_mad_i64_i32 v[48:49], s[2:3], v48, s8, v[140:141]
	v_max_f32_e32 v44, 0, v44
	v_mul_f32_e32 v40, v40, v40
	v_max_f32_e32 v41, 0, v41
	v_max_f32_e32 v42, 0, v42
	v_max_f32_e32 v43, 0, v43
	v_lshl_add_u64 v[48:49], v[48:49], 0, v[142:143]
	v_mul_f32_e32 v44, v44, v44
	v_mul_f32_e32 v41, v41, v41
	v_mul_f32_e32 v42, v42, v42
	v_mul_f32_e32 v43, v43, v43
	v_cvt_pk_bf16_f32 v40, v44, v40
	v_max_f32_e32 v32, 0, v32
	v_max_f32_e32 v33, 0, v33
	v_max_f32_e32 v34, 0, v34
	v_cvt_pk_bf16_f32 v41, v41, v42
	v_cvt_pk_bf16_f32 v42, v50, v45
	v_cvt_pk_bf16_f32 v43, v46, v43
	global_store_dwordx4 v[48:49], v[40:43], off
	s_nop 1
	v_mul_f32_e32 v40, v32, v32
	v_max_f32_e32 v32, v37, v37
	v_mul_f32_e32 v37, v33, v33
	v_max_f32_e32 v33, v38, v38
	v_mul_f32_e32 v38, v34, v34
	v_max_f32_e32 v34, v39, v39
	v_max_f32_e32 v32, 0, v32
	v_max_f32_e32 v33, 0, v33
	v_max_f32_e32 v34, 0, v34
	v_max_f32_e32 v36, 0, v36
	v_mul_f32_e32 v32, v32, v32
	v_mul_f32_e32 v33, v33, v33
	v_max_f32_e32 v35, 0, v35
	v_mul_f32_e32 v34, v34, v34
	v_mul_f32_e32 v36, v36, v36
	v_mul_f32_e32 v35, v35, v35
	v_cvt_pk_bf16_f32 v32, v36, v32
	v_cvt_pk_bf16_f32 v33, v33, v34
	v_cvt_pk_bf16_f32 v34, v40, v37
	v_max_f32_e32 v24, 0, v24
	v_cvt_pk_bf16_f32 v35, v38, v35
	global_store_dwordx4 v[48:49], v[32:35], off offset:256
	s_nop 1
	v_max_f32_e32 v25, 0, v25
	v_max_f32_e32 v26, 0, v26
	v_mul_f32_e32 v34, v24, v24
	v_max_f32_e32 v24, v29, v29
	v_add_u32_e32 v32, 0xa0, v150
	v_max_f32_e32 v24, 0, v24
	v_mul_f32_e32 v29, v25, v25
	v_max_f32_e32 v25, v30, v30
	v_mul_f32_e32 v30, v26, v26
	v_max_f32_e32 v26, v31, v31
	v_mad_i64_i32 v[32:33], s[2:3], v32, s8, v[140:141]
	v_max_f32_e32 v28, 0, v28
	v_mul_f32_e32 v24, v24, v24
	v_max_f32_e32 v25, 0, v25
	v_max_f32_e32 v26, 0, v26
	v_max_f32_e32 v27, 0, v27
	v_lshl_add_u64 v[32:33], v[32:33], 0, v[142:143]
	v_mul_f32_e32 v28, v28, v28
	v_mul_f32_e32 v25, v25, v25
	v_mul_f32_e32 v26, v26, v26
	v_mul_f32_e32 v27, v27, v27
	v_cvt_pk_bf16_f32 v24, v28, v24
	v_max_f32_e32 v16, 0, v16
	v_max_f32_e32 v17, 0, v17
	v_max_f32_e32 v18, 0, v18
	v_cvt_pk_bf16_f32 v25, v25, v26
	v_cvt_pk_bf16_f32 v26, v34, v29
	v_cvt_pk_bf16_f32 v27, v30, v27
	global_store_dwordx4 v[32:33], v[24:27], off
	s_nop 1
	v_mul_f32_e32 v24, v16, v16
	v_max_f32_e32 v16, v21, v21
	v_mul_f32_e32 v21, v17, v17
	v_max_f32_e32 v17, v22, v22
	v_mul_f32_e32 v22, v18, v18
	v_max_f32_e32 v18, v23, v23
	v_max_f32_e32 v16, 0, v16
	v_max_f32_e32 v17, 0, v17
	v_max_f32_e32 v18, 0, v18
	v_max_f32_e32 v20, 0, v20
	v_mul_f32_e32 v16, v16, v16
	v_mul_f32_e32 v17, v17, v17
	v_max_f32_e32 v19, 0, v19
	v_mul_f32_e32 v18, v18, v18
	v_mul_f32_e32 v20, v20, v20
	v_mul_f32_e32 v19, v19, v19
	v_cvt_pk_bf16_f32 v16, v20, v16
	v_cvt_pk_bf16_f32 v17, v17, v18
	v_cvt_pk_bf16_f32 v18, v24, v21
	v_max_f32_e32 v8, 0, v8
	v_cvt_pk_bf16_f32 v19, v22, v19
	global_store_dwordx4 v[32:33], v[16:19], off offset:256
	s_nop 1
	v_max_f32_e32 v9, 0, v9
	v_max_f32_e32 v10, 0, v10
	v_mul_f32_e32 v18, v8, v8
	v_max_f32_e32 v8, v13, v13
	v_add_u32_e32 v16, 0xb0, v150
	v_max_f32_e32 v8, 0, v8
	v_mul_f32_e32 v13, v9, v9
	v_max_f32_e32 v9, v14, v14
	v_mul_f32_e32 v14, v10, v10
	v_max_f32_e32 v10, v15, v15
	v_mad_i64_i32 v[16:17], s[2:3], v16, s8, v[140:141]
	v_max_f32_e32 v12, 0, v12
	v_mul_f32_e32 v8, v8, v8
	v_max_f32_e32 v9, 0, v9
	v_max_f32_e32 v10, 0, v10
	v_max_f32_e32 v11, 0, v11
	v_lshl_add_u64 v[16:17], v[16:17], 0, v[142:143]
	v_mul_f32_e32 v12, v12, v12
	v_mul_f32_e32 v9, v9, v9
	v_mul_f32_e32 v10, v10, v10
	v_mul_f32_e32 v11, v11, v11
	v_cvt_pk_bf16_f32 v8, v12, v8
	v_max_f32_e32 v0, 0, v0
	v_max_f32_e32 v1, 0, v1
	v_max_f32_e32 v2, 0, v2
	v_cvt_pk_bf16_f32 v9, v9, v10
	v_cvt_pk_bf16_f32 v10, v18, v13
	v_cvt_pk_bf16_f32 v11, v14, v11
	global_store_dwordx4 v[16:17], v[8:11], off
	s_nop 1
	v_mul_f32_e32 v8, v0, v0
	v_max_f32_e32 v0, v5, v5
	v_mul_f32_e32 v5, v1, v1
	v_max_f32_e32 v1, v6, v6
	v_mul_f32_e32 v6, v2, v2
	v_max_f32_e32 v2, v7, v7
	v_max_f32_e32 v0, 0, v0
	v_max_f32_e32 v1, 0, v1
	v_max_f32_e32 v2, 0, v2
	v_max_f32_e32 v3, 0, v3
	v_max_f32_e32 v4, 0, v4
	v_mul_f32_e32 v0, v0, v0
	v_mul_f32_e32 v1, v1, v1
	v_mul_f32_e32 v2, v2, v2
	v_mul_f32_e32 v3, v3, v3
	s_and_b64 vcc, exec, s[4:5]
	s_mov_b32 s38, s34
	s_mov_b32 s37, s36
	s_mov_b32 s40, s39
	s_mov_b64 s[10:11], s[18:19]
	s_mov_b64 s[8:9], s[6:7]
	s_mov_b32 s18, s33
	v_readlane_b32 s35, v251, 41
	v_mul_f32_e32 v4, v4, v4
	v_cvt_pk_bf16_f32 v0, v4, v0
	v_cvt_pk_bf16_f32 v1, v1, v2
	v_cvt_pk_bf16_f32 v2, v8, v5
	v_cvt_pk_bf16_f32 v3, v6, v3
	global_store_dwordx4 v[16:17], v[0:3], off offset:256
	s_nop 1
	s_cbranch_vccz .LBB0_96
	s_waitcnt vmcnt(0)
	v_readlane_b32 s40, v251, 24
	v_readlane_b32 s28, v252, 58
	s_cmpk_gt_u32 s15, 0xff
	s_movk_i32 s27, 0x1000
	v_readlane_b32 s41, v251, 25
	v_readlane_b32 s29, v252, 59
	s_cbranch_scc1 .LBB0_124
	s_barrier

; #define PG8_STAGE(bufoff, gbase, voff) do { _Pragma("unroll") for (int _i = 0; _i < 2; ++_i) \
;         __builtin_amdgcn_global_load_lds((const unsigned*)((const char*)(gbase) + (voff)[_i]), (LAS unsigned*)(lds + (bufoff) + ldsw + _i * 8192), 16, 0, 0); } while (0)
; #define PG8_LDA(dst, b, h) do { _Pragma("unroll") for (int m = 0; m < 4; ++m) _Pragma("unroll") for (int k = 0; k < 2; ++k) dst[m][k] = *(const LAS bf16x8*)(lds + PG8_SA(b, h) + aoff + m * 2048 + k * 1024); } while (0)
; #define PG8_LDB(dst, b, h) do { _Pragma("unroll") for (int n = 0; n < 2; ++n) _Pragma("unroll") for (int k = 0; k < 2; ++k) dst[n][k] = *(const LAS bf16x8*)(lds + PG8_SB(b, h) + boff + n * 2048 + k * 1024); } while (0)
; #define PG8_MMA(ai, bj, At, Bt) do { __builtin_amdgcn_s_setprio(1); _Pragma("unroll") for (int m = 0; m < 4; ++m) _Pragma("unroll") for (int n = 0; n < 2; ++n) _Pragma("unroll") for (int k = 0; k < 2; ++k) \
;         acc[ai][bj][m][n] = __builtin_amdgcn_mfma_f32_16x16x32_bf16(Bt[n][k], At[m][k], acc[ai][bj][m][n], 0, 0, 0); __builtin_amdgcn_s_setprio(0); } while (0)
; #define PG8_WAIT_L(n) asm volatile("s_waitcnt lgkmcnt(" #n ")" ::: "memory")
; #define PG8_BAR __builtin_amdgcn_s_barrier()
; #define PG8_SCHED __builtin_amdgcn_sched_barrier(0)
;     ...
;             const char* a1 = cA + (size_t)(t + 1) * kstep;
;             const char* a2 = last ? nA : cA + (size_t)(t + 2) * kstep; const char* b2 = last ? nB : cB + (size_t)(t + 2) * kstep;
;             const char* a3 = a2 + kstep; const char* b3 = b2 + kstep;
;             PG8_LDB(B0, 0, 0); PG8_SCHED; PG8_LDA(At, 0, 0); PG8_STAGE(PG8_SA(1, 1), a1 + hstep, voffA);
;             PG8_WAIT_L(8); PG8_BAR; PG8_WAIT_L(0); PG8_MMA(0, 0, At, B0); PG8_BAR; PG8_SCHED;
;             PG8_LDB(B1, 0, 1); PG8_STAGE(PG8_SB(0, 0), b2, voffB);
;             PG8_BAR; PG8_WAIT_L(0); PG8_MMA(0, 1, At, B1); PG8_BAR;
;             PG8_LDA(At, 0, 1); PG8_STAGE(PG8_SA(0, 0), a2, voffA);
;             PG8_BAR; PG8_WAIT_L(0); PG8_MMA(1, 0, At, B0); PG8_BAR; PG8_SCHED;
.LBB0_146:
	s_add_u32 s2, s8, 0xe515c080
	s_addc_u32 s3, s9, -1
	s_cmp_lg_u32 s27, 28
	s_cselect_b32 s10, s2, 0
	s_cselect_b32 s11, s3, 0
	s_add_u32 s2, s6, s10
	s_addc_u32 s3, s7, s11
	s_add_i32 s28, 0, 0x10000
	v_add_u32_e32 v156, s28, v142
	ds_read_b128 v[144:147], v156
	ds_read_b128 v[148:151], v156 offset:1024
	ds_read_b128 v[152:155], v156 offset:2048
	ds_read_b128 v[156:159], v156 offset:3072
	s_add_u32 s10, s4, s10
	s_addc_u32 s11, s5, s11
	v_lshl_add_u64 v[192:193], v[136:137], 0, s[8:9]
	s_add_i32 m0, s20, 0xc000
	ds_read_b128 v[160:163], v143
	ds_read_b128 v[164:167], v143 offset:1024
	ds_read_b128 v[168:171], v143 offset:2048
	ds_read_b128 v[172:175], v143 offset:3072
	ds_read_b128 v[176:179], v143 offset:4096
	ds_read_b128 v[180:183], v143 offset:5120
	ds_read_b128 v[184:187], v143 offset:6144
	ds_read_b128 v[188:191], v143 offset:7168
	global_load_lds_dwordx4 v[192:193], off
	v_lshl_add_u64 v[192:193], v[138:139], 0, s[8:9]
	s_add_i32 m0, s20, 0xe000
	s_nop 0
	global_load_lds_dwordx4 v[192:193], off
	s_waitcnt lgkmcnt(8)
	s_barrier
	s_waitcnt lgkmcnt(0)
	v_mfma_f32_16x16x32_bf16 v[126:129], v[144:147], v[160:163], v[126:129]
	v_mfma_f32_16x16x32_bf16 v[122:125], v[152:155], v[160:163], v[122:125]
	v_mfma_f32_16x16x32_bf16 v[110:113], v[144:147], v[168:171], v[110:113]
	v_mfma_f32_16x16x32_bf16 v[106:109], v[152:155], v[168:171], v[106:109]
	v_mfma_f32_16x16x32_bf16 v[94:97], v[144:147], v[176:179], v[94:97]
	v_mfma_f32_16x16x32_bf16 v[90:93], v[152:155], v[176:179], v[90:93]
	v_mfma_f32_16x16x32_bf16 v[78:81], v[144:147], v[184:187], v[78:81]
	v_mfma_f32_16x16x32_bf16 v[74:77], v[152:155], v[184:187], v[74:77]
	v_mfma_f32_16x16x32_bf16 v[126:129], v[148:151], v[164:167], v[126:129]
	v_mfma_f32_16x16x32_bf16 v[122:125], v[156:159], v[164:167], v[122:125]
	v_mfma_f32_16x16x32_bf16 v[110:113], v[148:151], v[172:175], v[110:113]
	v_mfma_f32_16x16x32_bf16 v[106:109], v[156:159], v[172:175], v[106:109]
	v_mfma_f32_16x16x32_bf16 v[94:97], v[148:151], v[180:183], v[94:97]
	v_mfma_f32_16x16x32_bf16 v[90:93], v[156:159], v[180:183], v[90:93]
	v_mfma_f32_16x16x32_bf16 v[78:81], v[148:151], v[188:191], v[78:81]
	v_mfma_f32_16x16x32_bf16 v[74:77], v[156:159], v[188:191], v[74:77]
	s_barrier
	s_add_i32 s31, 0, 0x14000
	s_add_i32 s28, s28, s15
	v_add_u32_e32 v208, s31, v142
	v_lshl_add_u64 v[228:229], s[10:11], 0, v[64:65]
	s_mov_b32 m0, s28
	ds_read_b128 v[192:195], v208
	ds_read_b128 v[196:199], v208 offset:1024
	ds_read_b128 v[220:223], v208 offset:2048
	ds_read_b128 v[224:227], v208 offset:3072
	global_load_lds_dwordx4 v[228:229], off
	v_lshl_add_u64 v[230:231], s[10:11], 0, v[130:131]
	s_add_i32 m0, s28, 0x2000
	s_nop 0
	global_load_lds_dwordx4 v[230:231], off
	s_barrier
	s_waitcnt lgkmcnt(0)
	v_mfma_f32_16x16x32_bf16 v[118:121], v[192:195], v[160:163], v[118:121]
	v_mfma_f32_16x16x32_bf16 v[114:117], v[220:223], v[160:163], v[114:117]
	v_mfma_f32_16x16x32_bf16 v[102:105], v[192:195], v[168:171], v[102:105]
	v_mfma_f32_16x16x32_bf16 v[98:101], v[220:223], v[168:171], v[98:101]
	v_mfma_f32_16x16x32_bf16 v[86:89], v[192:195], v[176:179], v[86:89]
	v_mfma_f32_16x16x32_bf16 v[82:85], v[220:223], v[176:179], v[82:85]
	v_mfma_f32_16x16x32_bf16 v[70:73], v[192:195], v[184:187], v[70:73]
	v_mfma_f32_16x16x32_bf16 v[66:69], v[220:223], v[184:187], v[66:69]
	v_mfma_f32_16x16x32_bf16 v[118:121], v[196:199], v[164:167], v[118:121]
	v_mfma_f32_16x16x32_bf16 v[114:117], v[224:227], v[164:167], v[114:117]
	v_mfma_f32_16x16x32_bf16 v[102:105], v[196:199], v[172:175], v[102:105]
	v_mfma_f32_16x16x32_bf16 v[98:101], v[224:227], v[172:175], v[98:101]
	v_mfma_f32_16x16x32_bf16 v[86:89], v[196:199], v[180:183], v[86:89]
	v_mfma_f32_16x16x32_bf16 v[82:85], v[224:227], v[180:183], v[82:85]
	v_mfma_f32_16x16x32_bf16 v[70:73], v[196:199], v[188:191], v[70:73]
	v_mfma_f32_16x16x32_bf16 v[66:69], v[224:227], v[188:191], v[66:69]
	s_mov_b32 m0, s20
	v_lshl_add_u64 v[232:233], s[2:3], 0, v[134:135]
	s_barrier
	ds_read_b128 v[160:163], v143 offset:16384
	ds_read_b128 v[164:167], v143 offset:17408
	ds_read_b128 v[168:171], v143 offset:18432
	ds_read_b128 v[172:175], v143 offset:19456
	ds_read_b128 v[176:179], v143 offset:20480
	ds_read_b128 v[180:183], v143 offset:21504
	ds_read_b128 v[184:187], v143 offset:22528
	ds_read_b128 v[188:191], v143 offset:23552
	global_load_lds_dwordx4 v[232:233], off
	v_lshl_add_u64 v[234:235], s[2:3], 0, v[132:133]
	s_mov_b32 m0, s21
	s_nop 0
	global_load_lds_dwordx4 v[234:235], off
	s_barrier
	s_waitcnt lgkmcnt(0)
	v_mfma_f32_16x16x32_bf16 v[60:63], v[144:147], v[160:163], v[60:63]
	v_mfma_f32_16x16x32_bf16 v[56:59], v[152:155], v[160:163], v[56:59]
	v_mfma_f32_16x16x32_bf16 v[44:47], v[144:147], v[168:171], v[44:47]
	v_mfma_f32_16x16x32_bf16 v[40:43], v[152:155], v[168:171], v[40:43]
	v_mfma_f32_16x16x32_bf16 v[28:31], v[144:147], v[176:179], v[28:31]
	v_mfma_f32_16x16x32_bf16 v[24:27], v[152:155], v[176:179], v[24:27]
	v_mfma_f32_16x16x32_bf16 v[12:15], v[144:147], v[184:187], v[12:15]
	v_mfma_f32_16x16x32_bf16 v[8:11], v[152:155], v[184:187], v[8:11]
	v_mfma_f32_16x16x32_bf16 v[60:63], v[148:151], v[164:167], v[60:63]
	v_mfma_f32_16x16x32_bf16 v[56:59], v[156:159], v[164:167], v[56:59]
	v_mfma_f32_16x16x32_bf16 v[44:47], v[148:151], v[172:175], v[44:47]
	v_mfma_f32_16x16x32_bf16 v[40:43], v[156:159], v[172:175], v[40:43]
	v_mfma_f32_16x16x32_bf16 v[28:31], v[148:151], v[180:183], v[28:31]
	v_mfma_f32_16x16x32_bf16 v[24:27], v[156:159], v[180:183], v[24:27]
	v_mfma_f32_16x16x32_bf16 v[12:15], v[148:151], v[188:191], v[12:15]
	v_mfma_f32_16x16x32_bf16 v[8:11], v[156:159], v[188:191], v[8:11]
	s_barrier
; #define PG8_STAGE(bufoff, gbase, voff) do { _Pragma("unroll") for (int _i = 0; _i < 2; ++_i) \
;         __builtin_amdgcn_global_load_lds((const unsigned*)((const char*)(gbase) + (voff)[_i]), (LAS unsigned*)(lds + (bufoff) + ldsw + _i * 8192), 16, 0, 0); } while (0)
; #define PG8_LDA(dst, b, h) do { _Pragma("unroll") for (int m = 0; m < 4; ++m) _Pragma("unroll") for (int k = 0; k < 2; ++k) dst[m][k] = *(const LAS bf16x8*)(lds + PG8_SA(b, h) + aoff + m * 2048 + k * 1024); } while (0)
; #define PG8_LDB(dst, b, h) do { _Pragma("unroll") for (int n = 0; n < 2; ++n) _Pragma("unroll") for (int k = 0; k < 2; ++k) dst[n][k] = *(const LAS bf16x8*)(lds + PG8_SB(b, h) + boff + n * 2048 + k * 1024); } while (0)
; #define PG8_MMA(ai, bj, At, Bt) do { __builtin_amdgcn_s_setprio(1); _Pragma("unroll") for (int m = 0; m < 4; ++m) _Pragma("unroll") for (int n = 0; n < 2; ++n) _Pragma("unroll") for (int k = 0; k < 2; ++k) \
;         acc[ai][bj][m][n] = __builtin_amdgcn_mfma_f32_16x16x32_bf16(Bt[n][k], At[m][k], acc[ai][bj][m][n], 0, 0, 0); __builtin_amdgcn_s_setprio(0); } while (0)
; #define PG8_WAIT_V(n) asm volatile("s_waitcnt vmcnt(" #n ")" ::: "memory")
; #define PG8_WAIT_L(n) asm volatile("s_waitcnt lgkmcnt(" #n ")" ::: "memory")
; #define PG8_BAR __builtin_amdgcn_s_barrier()
; #define PG8_SCHED __builtin_amdgcn_sched_barrier(0)
;     ...
;             PG8_STAGE(PG8_SB(0, 1), b2 + hstep, voffB);
;             PG8_WAIT_V(6); PG8_BAR; PG8_MMA(1, 1, At, B1); PG8_BAR;
;             PG8_LDB(B0, 1, 0); PG8_SCHED; PG8_LDA(At, 1, 0); PG8_STAGE(PG8_SA(0, 1), a2 + hstep, voffA);
;             PG8_WAIT_L(8); PG8_BAR; PG8_WAIT_L(0); PG8_MMA(0, 0, At, B0); PG8_BAR; PG8_SCHED;
;             PG8_LDB(B1, 1, 1); PG8_STAGE(PG8_SB(1, 0), b3, voffB);
;             PG8_BAR; PG8_WAIT_L(0); PG8_MMA(0, 1, At, B1); PG8_BAR;
;             PG8_LDA(At, 1, 1); PG8_STAGE(PG8_SA(1, 0), a3, voffA);
;             PG8_BAR; PG8_WAIT_L(0); PG8_MMA(1, 0, At, B0); PG8_BAR; PG8_SCHED;
	s_add_u32 s28, s10, 0x84000
	s_addc_u32 s29, s11, 0
	s_add_i32 s31, s31, s15
	v_lshl_add_u64 v[144:145], s[28:29], 0, v[64:65]
	s_mov_b32 m0, s31
	s_nop 0
	global_load_lds_dwordx4 v[144:145], off
	v_lshl_add_u64 v[144:145], s[28:29], 0, v[130:131]
	s_add_i32 m0, s31, 0x2000
	s_nop 0
	global_load_lds_dwordx4 v[144:145], off
	s_waitcnt vmcnt(6)
	s_barrier
	v_mfma_f32_16x16x32_bf16 v[52:55], v[192:195], v[160:163], v[52:55]
	v_mfma_f32_16x16x32_bf16 v[48:51], v[220:223], v[160:163], v[48:51]
	v_mfma_f32_16x16x32_bf16 v[36:39], v[192:195], v[168:171], v[36:39]
	v_mfma_f32_16x16x32_bf16 v[32:35], v[220:223], v[168:171], v[32:35]
	v_mfma_f32_16x16x32_bf16 v[20:23], v[192:195], v[176:179], v[20:23]
	v_mfma_f32_16x16x32_bf16 v[16:19], v[220:223], v[176:179], v[16:19]
	v_mfma_f32_16x16x32_bf16 v[4:7], v[192:195], v[184:187], v[4:7]
	v_mfma_f32_16x16x32_bf16 v[0:3], v[220:223], v[184:187], v[0:3]
	v_mfma_f32_16x16x32_bf16 v[52:55], v[196:199], v[164:167], v[52:55]
	v_mfma_f32_16x16x32_bf16 v[48:51], v[224:227], v[164:167], v[48:51]
	v_mfma_f32_16x16x32_bf16 v[36:39], v[196:199], v[172:175], v[36:39]
	v_mfma_f32_16x16x32_bf16 v[32:35], v[224:227], v[172:175], v[32:35]
	v_mfma_f32_16x16x32_bf16 v[20:23], v[196:199], v[180:183], v[20:23]
	v_mfma_f32_16x16x32_bf16 v[16:19], v[224:227], v[180:183], v[16:19]
	v_mfma_f32_16x16x32_bf16 v[4:7], v[196:199], v[188:191], v[4:7]
	v_mfma_f32_16x16x32_bf16 v[0:3], v[224:227], v[188:191], v[0:3]
	s_add_i32 s28, 0, 0x18000
	v_add_u32_e32 v156, s28, v142
	s_barrier
	ds_read_b128 v[144:147], v156
	ds_read_b128 v[148:151], v156 offset:1024
	ds_read_b128 v[152:155], v156 offset:2048
	ds_read_b128 v[156:159], v156 offset:3072
	s_add_u32 s2, s2, 0x84000
	s_addc_u32 s3, s3, 0
	s_mov_b32 m0, s22
	v_lshl_add_u64 v[192:193], s[2:3], 0, v[134:135]
	ds_read_b128 v[160:163], v143 offset:32768
	ds_read_b128 v[164:167], v143 offset:33792
	ds_read_b128 v[168:171], v143 offset:34816
	ds_read_b128 v[172:175], v143 offset:35840
	ds_read_b128 v[176:179], v143 offset:36864
	ds_read_b128 v[180:183], v143 offset:37888
	ds_read_b128 v[184:187], v143 offset:38912
	ds_read_b128 v[188:191], v143 offset:39936
	global_load_lds_dwordx4 v[192:193], off
	v_lshl_add_u64 v[192:193], s[2:3], 0, v[132:133]
	s_mov_b32 m0, s23
	s_nop 0
	global_load_lds_dwordx4 v[192:193], off
	s_waitcnt lgkmcnt(8)
	s_barrier
	s_waitcnt lgkmcnt(0)
	v_mfma_f32_16x16x32_bf16 v[126:129], v[144:147], v[160:163], v[126:129]
	v_mfma_f32_16x16x32_bf16 v[122:125], v[152:155], v[160:163], v[122:125]
	v_mfma_f32_16x16x32_bf16 v[110:113], v[144:147], v[168:171], v[110:113]
	v_mfma_f32_16x16x32_bf16 v[106:109], v[152:155], v[168:171], v[106:109]
	v_mfma_f32_16x16x32_bf16 v[94:97], v[144:147], v[176:179], v[94:97]
	v_mfma_f32_16x16x32_bf16 v[90:93], v[152:155], v[176:179], v[90:93]
	v_mfma_f32_16x16x32_bf16 v[78:81], v[144:147], v[184:187], v[78:81]
	v_mfma_f32_16x16x32_bf16 v[74:77], v[152:155], v[184:187], v[74:77]
	v_mfma_f32_16x16x32_bf16 v[126:129], v[148:151], v[164:167], v[126:129]
	v_mfma_f32_16x16x32_bf16 v[122:125], v[156:159], v[164:167], v[122:125]
	v_mfma_f32_16x16x32_bf16 v[110:113], v[148:151], v[172:175], v[110:113]
	v_mfma_f32_16x16x32_bf16 v[106:109], v[156:159], v[172:175], v[106:109]
	v_mfma_f32_16x16x32_bf16 v[94:97], v[148:151], v[180:183], v[94:97]
	v_mfma_f32_16x16x32_bf16 v[90:93], v[156:159], v[180:183], v[90:93]
	v_mfma_f32_16x16x32_bf16 v[78:81], v[148:151], v[188:191], v[78:81]
	v_mfma_f32_16x16x32_bf16 v[74:77], v[156:159], v[188:191], v[74:77]
	s_barrier
	s_add_i32 s29, 0, 0x1c000
	s_add_i32 s2, s28, s15
	v_add_u32_e32 v208, s29, v142
	v_lshl_add_u64 v[228:229], v[228:229], 0, s[16:17]
	s_mov_b32 m0, s2
	ds_read_b128 v[192:195], v208
	ds_read_b128 v[196:199], v208 offset:1024
	ds_read_b128 v[220:223], v208 offset:2048
	ds_read_b128 v[224:227], v208 offset:3072
	global_load_lds_dwordx4 v[228:229], off
	v_lshl_add_u64 v[228:229], v[230:231], 0, s[16:17]
	s_add_i32 m0, s2, 0x2000
	s_nop 0
	global_load_lds_dwordx4 v[228:229], off
	s_barrier
	s_waitcnt lgkmcnt(0)
	v_mfma_f32_16x16x32_bf16 v[118:121], v[192:195], v[160:163], v[118:121]
	v_mfma_f32_16x16x32_bf16 v[114:117], v[220:223], v[160:163], v[114:117]
	v_mfma_f32_16x16x32_bf16 v[102:105], v[192:195], v[168:171], v[102:105]
	v_mfma_f32_16x16x32_bf16 v[98:101], v[220:223], v[168:171], v[98:101]
	v_mfma_f32_16x16x32_bf16 v[86:89], v[192:195], v[176:179], v[86:89]
	v_mfma_f32_16x16x32_bf16 v[82:85], v[220:223], v[176:179], v[82:85]
	v_mfma_f32_16x16x32_bf16 v[70:73], v[192:195], v[184:187], v[70:73]
	v_mfma_f32_16x16x32_bf16 v[66:69], v[220:223], v[184:187], v[66:69]
	v_mfma_f32_16x16x32_bf16 v[118:121], v[196:199], v[164:167], v[118:121]
	v_mfma_f32_16x16x32_bf16 v[114:117], v[224:227], v[164:167], v[114:117]
	v_mfma_f32_16x16x32_bf16 v[102:105], v[196:199], v[172:175], v[102:105]
	v_mfma_f32_16x16x32_bf16 v[98:101], v[224:227], v[172:175], v[98:101]
	v_mfma_f32_16x16x32_bf16 v[86:89], v[196:199], v[180:183], v[86:89]
	v_mfma_f32_16x16x32_bf16 v[82:85], v[224:227], v[180:183], v[82:85]
	v_mfma_f32_16x16x32_bf16 v[70:73], v[196:199], v[188:191], v[70:73]
	v_mfma_f32_16x16x32_bf16 v[66:69], v[224:227], v[188:191], v[66:69]
	s_mov_b32 m0, s25
	v_lshl_add_u64 v[228:229], v[232:233], 0, s[16:17]
	s_barrier
	ds_read_b128 v[160:163], v143 offset:49152
	ds_read_b128 v[164:167], v143 offset:50176
	ds_read_b128 v[168:171], v143 offset:51200
	ds_read_b128 v[172:175], v143 offset:52224
	ds_read_b128 v[176:179], v143 offset:53248
	ds_read_b128 v[180:183], v143 offset:54272
	ds_read_b128 v[184:187], v143 offset:55296
	ds_read_b128 v[188:191], v143 offset:56320
	global_load_lds_dwordx4 v[228:229], off
	v_lshl_add_u64 v[228:229], v[234:235], 0, s[16:17]
	s_mov_b32 m0, s26
	s_nop 0
	global_load_lds_dwordx4 v[228:229], off
	s_barrier
; __device__ __forceinline__ unsigned cvt_pk_bf16(float lo, float hi) { unsigned r; asm volatile("v_cvt_pk_bf16_f32 %0, %1, %2" : "=v"(r) : "v"(lo), "v"(hi)); return r; }
; #define PG8_STAGE(bufoff, gbase, voff) do { _Pragma("unroll") for (int _i = 0; _i < 2; ++_i) \
;         __builtin_amdgcn_global_load_lds((const unsigned*)((const char*)(gbase) + (voff)[_i]), (LAS unsigned*)(lds + (bufoff) + ldsw + _i * 8192), 16, 0, 0); } while (0)
; #define PG8_MMA(ai, bj, At, Bt) do { __builtin_amdgcn_s_setprio(1); _Pragma("unroll") for (int m = 0; m < 4; ++m) _Pragma("unroll") for (int n = 0; n < 2; ++n) _Pragma("unroll") for (int k = 0; k < 2; ++k) \
;         acc[ai][bj][m][n] = __builtin_amdgcn_mfma_f32_16x16x32_bf16(Bt[n][k], At[m][k], acc[ai][bj][m][n], 0, 0, 0); __builtin_amdgcn_s_setprio(0); } while (0)
; #define PG8_WAIT_V(n) asm volatile("s_waitcnt vmcnt(" #n ")" ::: "memory")
; #define PG8_WAIT_L(n) asm volatile("s_waitcnt lgkmcnt(" #n ")" ::: "memory")
; #define PG8_BAR __builtin_amdgcn_s_barrier()
; #define PG8_SCHED __builtin_amdgcn_sched_barrier(0)
;     __device__ __forceinline__ void operator()(const f32x4 (&acc)[2][2][4][2], const Unit& u, int wr, int wc, int fr, int fq) const {
;         const int row0 = u.pm * BM + wr * 64 + fr, col0 = u.pn * BM + wc * 32 + 8 * fq;
; #pragma unroll
;         for (int ai = 0; ai < 2; ++ai)
; #pragma unroll
;             for (int m = 0; m < 4; ++m) { bf16_t* rowp = O + (size_t)(row0 + ai * HALF + m * 16) * LDF + col0;
; #pragma unroll
;                 for (int bj = 0; bj < 2; ++bj) { f32x4 v0 = acc[ai][bj][m][0], v1 = acc[ai][bj][m][1];
; #pragma unroll
;                     for (int j = 0; j < 4; ++j) { const float a = fmaxf(v0[j], 0.f), b = fmaxf(v1[j], 0.f); v0[j] = a * a; v1[j] = b * b; }
;                     u32x4 w; w.x = cvt_pk_bf16(v0[0], v0[1]); w.y = cvt_pk_bf16(v0[2], v0[3]); w.z = cvt_pk_bf16(v1[0], v1[1]); w.w = cvt_pk_bf16(v1[2], v1[3]);
;                     *(u32x4*)(rowp + bj * HALF) = w; } }
;     ...
;             PG8_BAR; PG8_WAIT_L(0); PG8_MMA(1, 0, At, B0); PG8_BAR; PG8_SCHED;
;             PG8_STAGE(PG8_SB(1, 1), b3 + hstep, voffB);
;             PG8_WAIT_V(6); PG8_BAR; PG8_MMA(1, 1, At, B1); PG8_BAR;
;         }
	s_waitcnt lgkmcnt(0)
	v_mfma_f32_16x16x32_bf16 v[60:63], v[144:147], v[160:163], v[60:63]
	v_mfma_f32_16x16x32_bf16 v[56:59], v[152:155], v[160:163], v[56:59]
	v_mfma_f32_16x16x32_bf16 v[44:47], v[144:147], v[168:171], v[44:47]
	v_mfma_f32_16x16x32_bf16 v[40:43], v[152:155], v[168:171], v[40:43]
	v_mfma_f32_16x16x32_bf16 v[28:31], v[144:147], v[176:179], v[28:31]
	v_mfma_f32_16x16x32_bf16 v[24:27], v[152:155], v[176:179], v[24:27]
	v_mfma_f32_16x16x32_bf16 v[12:15], v[144:147], v[184:187], v[12:15]
	v_mfma_f32_16x16x32_bf16 v[8:11], v[152:155], v[184:187], v[8:11]
	v_mfma_f32_16x16x32_bf16 v[60:63], v[148:151], v[164:167], v[60:63]
	v_mfma_f32_16x16x32_bf16 v[56:59], v[156:159], v[164:167], v[56:59]
	v_mfma_f32_16x16x32_bf16 v[44:47], v[148:151], v[172:175], v[44:47]
	v_mfma_f32_16x16x32_bf16 v[40:43], v[156:159], v[172:175], v[40:43]
	v_mfma_f32_16x16x32_bf16 v[28:31], v[148:151], v[180:183], v[28:31]
	v_mfma_f32_16x16x32_bf16 v[24:27], v[156:159], v[180:183], v[24:27]
	v_mfma_f32_16x16x32_bf16 v[12:15], v[148:151], v[188:191], v[12:15]
	v_mfma_f32_16x16x32_bf16 v[8:11], v[156:159], v[188:191], v[8:11]
	s_barrier
	s_add_u32 s2, s10, 0x84080
	s_addc_u32 s3, s11, 0
	s_add_i32 s10, s29, s15
	v_lshl_add_u64 v[144:145], s[2:3], 0, v[64:65]
	s_mov_b32 m0, s10
	s_nop 0
	global_load_lds_dwordx4 v[144:145], off
	v_lshl_add_u64 v[144:145], s[2:3], 0, v[130:131]
	s_add_i32 m0, s10, 0x2000
	s_nop 0
	global_load_lds_dwordx4 v[144:145], off
	s_waitcnt vmcnt(6)
	s_barrier
	v_mfma_f32_16x16x32_bf16 v[52:55], v[192:195], v[160:163], v[52:55]
	v_mfma_f32_16x16x32_bf16 v[48:51], v[220:223], v[160:163], v[48:51]
	v_mfma_f32_16x16x32_bf16 v[36:39], v[192:195], v[168:171], v[36:39]
	v_mfma_f32_16x16x32_bf16 v[32:35], v[220:223], v[168:171], v[32:35]
	v_mfma_f32_16x16x32_bf16 v[20:23], v[192:195], v[176:179], v[20:23]
	v_mfma_f32_16x16x32_bf16 v[16:19], v[220:223], v[176:179], v[16:19]
	v_mfma_f32_16x16x32_bf16 v[4:7], v[192:195], v[184:187], v[4:7]
	v_mfma_f32_16x16x32_bf16 v[0:3], v[220:223], v[184:187], v[0:3]
	v_mfma_f32_16x16x32_bf16 v[52:55], v[196:199], v[164:167], v[52:55]
	v_mfma_f32_16x16x32_bf16 v[48:51], v[224:227], v[164:167], v[48:51]
	v_mfma_f32_16x16x32_bf16 v[36:39], v[196:199], v[172:175], v[36:39]
	v_mfma_f32_16x16x32_bf16 v[32:35], v[224:227], v[172:175], v[32:35]
	v_mfma_f32_16x16x32_bf16 v[20:23], v[196:199], v[180:183], v[20:23]
	v_mfma_f32_16x16x32_bf16 v[16:19], v[224:227], v[180:183], v[16:19]
	v_mfma_f32_16x16x32_bf16 v[4:7], v[196:199], v[188:191], v[4:7]
	v_mfma_f32_16x16x32_bf16 v[0:3], v[224:227], v[188:191], v[0:3]
	s_add_i32 s27, s27, 2
	s_add_u32 s8, s8, 0x100
	s_addc_u32 s9, s9, 0
	s_cmp_gt_u32 s27, 29
	s_barrier
	s_cbranch_scc0 .LBB0_146
	s_lshl_b32 s2, s19, 8
	v_max_f32_e32 v122, 0, v122
	s_or_b32 s2, s24, s2
	v_mul_f32_e32 v135, v122, v122
	v_max_f32_e32 v122, v127, v127
	v_max_f32_e32 v123, 0, v123
	v_max_f32_e32 v124, 0, v124
	v_lshl_add_u32 v134, s18, 8, v141
	v_or_b32_e32 v64, s2, v140
	v_mov_b64_e32 v[130:131], s[80:81]
	s_movk_i32 s4, 0x4080
	v_max_f32_e32 v122, 0, v122
	v_mul_f32_e32 v127, v123, v123
	v_max_f32_e32 v123, v128, v128
	v_mul_f32_e32 v128, v124, v124
	v_max_f32_e32 v124, v129, v129
	v_mad_i64_i32 v[132:133], s[2:3], v134, s4, v[130:131]
	v_lshlrev_b32_e32 v64, 1, v64
	v_max_f32_e32 v126, 0, v126
	v_mul_f32_e32 v122, v122, v122
	v_max_f32_e32 v123, 0, v123
	v_max_f32_e32 v124, 0, v124
	v_max_f32_e32 v125, 0, v125
	v_lshl_add_u64 v[132:133], v[132:133], 0, v[64:65]
	v_mul_f32_e32 v126, v126, v126
	v_mul_f32_e32 v123, v123, v123
	v_mul_f32_e32 v124, v124, v124
	v_mul_f32_e32 v125, v125, v125
	v_cvt_pk_bf16_f32 v122, v126, v122
	v_max_f32_e32 v114, 0, v114
	v_max_f32_e32 v115, 0, v115
	v_max_f32_e32 v116, 0, v116
	v_cvt_pk_bf16_f32 v123, v123, v124
	v_cvt_pk_bf16_f32 v124, v135, v127
	v_cvt_pk_bf16_f32 v125, v128, v125
	global_store_dwordx4 v[132:133], v[122:125], off
	s_nop 1
	v_mul_f32_e32 v122, v114, v114
	v_max_f32_e32 v114, v119, v119
	v_mul_f32_e32 v119, v115, v115
	v_max_f32_e32 v115, v120, v120
	v_mul_f32_e32 v120, v116, v116
	v_max_f32_e32 v116, v121, v121
	v_max_f32_e32 v114, 0, v114
	v_max_f32_e32 v115, 0, v115
	v_max_f32_e32 v116, 0, v116
	v_max_f32_e32 v118, 0, v118
	v_mul_f32_e32 v114, v114, v114
	v_mul_f32_e32 v115, v115, v115
	v_max_f32_e32 v117, 0, v117
	v_mul_f32_e32 v116, v116, v116
	v_mul_f32_e32 v118, v118, v118
	v_mul_f32_e32 v117, v117, v117
	v_cvt_pk_bf16_f32 v114, v118, v114
	v_cvt_pk_bf16_f32 v115, v115, v116
	v_cvt_pk_bf16_f32 v116, v122, v119
	v_max_f32_e32 v106, 0, v106
	v_cvt_pk_bf16_f32 v117, v120, v117
	global_store_dwordx4 v[132:133], v[114:117], off offset:256
	s_nop 1
	v_max_f32_e32 v107, 0, v107
	v_max_f32_e32 v108, 0, v108
	v_mul_f32_e32 v116, v106, v106
	v_max_f32_e32 v106, v111, v111
	v_or_b32_e32 v114, 16, v134
	v_max_f32_e32 v106, 0, v106
	v_mul_f32_e32 v111, v107, v107
	v_max_f32_e32 v107, v112, v112
	v_mul_f32_e32 v112, v108, v108
	v_max_f32_e32 v108, v113, v113
	v_mad_i64_i32 v[114:115], s[2:3], v114, s4, v[130:131]
	v_max_f32_e32 v110, 0, v110
	v_mul_f32_e32 v106, v106, v106
	v_max_f32_e32 v107, 0, v107
	v_max_f32_e32 v108, 0, v108
	v_max_f32_e32 v109, 0, v109
	v_lshl_add_u64 v[114:115], v[114:115], 0, v[64:65]
	v_mul_f32_e32 v110, v110, v110
	v_mul_f32_e32 v107, v107, v107
	v_mul_f32_e32 v108, v108, v108
	v_mul_f32_e32 v109, v109, v109
	v_cvt_pk_bf16_f32 v106, v110, v106
	v_max_f32_e32 v98, 0, v98
	v_max_f32_e32 v99, 0, v99
	v_max_f32_e32 v100, 0, v100
	v_cvt_pk_bf16_f32 v107, v107, v108
	v_cvt_pk_bf16_f32 v108, v116, v111
	v_cvt_pk_bf16_f32 v109, v112, v109
	global_store_dwordx4 v[114:115], v[106:109], off
	s_nop 1
	v_mul_f32_e32 v106, v98, v98
; __device__ __forceinline__ unsigned cvt_pk_bf16(float lo, float hi) { unsigned r; asm volatile("v_cvt_pk_bf16_f32 %0, %1, %2" : "=v"(r) : "v"(lo), "v"(hi)); return r; }
;     __device__ __forceinline__ void operator()(const f32x4 (&acc)[2][2][4][2], const Unit& u, int wr, int wc, int fr, int fq) const {
;         const int row0 = u.pm * BM + wr * 64 + fr, col0 = u.pn * BM + wc * 32 + 8 * fq;
; #pragma unroll
;         for (int ai = 0; ai < 2; ++ai)
; #pragma unroll
;             for (int m = 0; m < 4; ++m) { bf16_t* rowp = O + (size_t)(row0 + ai * HALF + m * 16) * LDF + col0;
; #pragma unroll
;                 for (int bj = 0; bj < 2; ++bj) { f32x4 v0 = acc[ai][bj][m][0], v1 = acc[ai][bj][m][1];
; #pragma unroll
;                     for (int j = 0; j < 4; ++j) { const float a = fmaxf(v0[j], 0.f), b = fmaxf(v1[j], 0.f); v0[j] = a * a; v1[j] = b * b; }
;                     u32x4 w; w.x = cvt_pk_bf16(v0[0], v0[1]); w.y = cvt_pk_bf16(v0[2], v0[3]); w.z = cvt_pk_bf16(v1[0], v1[1]); w.w = cvt_pk_bf16(v1[2], v1[3]);
;                     *(u32x4*)(rowp + bj * HALF) = w; } }
	v_max_f32_e32 v98, v103, v103
	v_mul_f32_e32 v103, v99, v99
	v_max_f32_e32 v99, v104, v104
	v_mul_f32_e32 v104, v100, v100
	v_max_f32_e32 v100, v105, v105
	v_max_f32_e32 v98, 0, v98
	v_max_f32_e32 v99, 0, v99
	v_max_f32_e32 v100, 0, v100
	v_max_f32_e32 v102, 0, v102
	v_mul_f32_e32 v98, v98, v98
	v_mul_f32_e32 v99, v99, v99
	v_max_f32_e32 v101, 0, v101
	v_mul_f32_e32 v100, v100, v100
	v_mul_f32_e32 v102, v102, v102
	v_mul_f32_e32 v101, v101, v101
	v_cvt_pk_bf16_f32 v98, v102, v98
	v_cvt_pk_bf16_f32 v99, v99, v100
	v_cvt_pk_bf16_f32 v100, v106, v103
	v_max_f32_e32 v90, 0, v90
	v_cvt_pk_bf16_f32 v101, v104, v101
	global_store_dwordx4 v[114:115], v[98:101], off offset:256
	s_nop 1
	v_max_f32_e32 v91, 0, v91
	v_max_f32_e32 v92, 0, v92
	v_mul_f32_e32 v100, v90, v90
	v_max_f32_e32 v90, v95, v95
	v_or_b32_e32 v98, 32, v134
	v_max_f32_e32 v90, 0, v90
	v_mul_f32_e32 v95, v91, v91
	v_max_f32_e32 v91, v96, v96
	v_mul_f32_e32 v96, v92, v92
	v_max_f32_e32 v92, v97, v97
	v_mad_i64_i32 v[98:99], s[2:3], v98, s4, v[130:131]
	v_max_f32_e32 v94, 0, v94
	v_mul_f32_e32 v90, v90, v90
	v_max_f32_e32 v91, 0, v91
	v_max_f32_e32 v92, 0, v92
	v_max_f32_e32 v93, 0, v93
	v_lshl_add_u64 v[98:99], v[98:99], 0, v[64:65]
	v_mul_f32_e32 v94, v94, v94
	v_mul_f32_e32 v91, v91, v91
	v_mul_f32_e32 v92, v92, v92
	v_mul_f32_e32 v93, v93, v93
	v_cvt_pk_bf16_f32 v90, v94, v90
	v_max_f32_e32 v82, 0, v82
	v_max_f32_e32 v83, 0, v83
	v_max_f32_e32 v84, 0, v84
	v_cvt_pk_bf16_f32 v91, v91, v92
	v_cvt_pk_bf16_f32 v92, v100, v95
	v_cvt_pk_bf16_f32 v93, v96, v93
	global_store_dwordx4 v[98:99], v[90:93], off
	s_nop 1
	v_mul_f32_e32 v90, v82, v82
	v_max_f32_e32 v82, v87, v87
	v_mul_f32_e32 v87, v83, v83
	v_max_f32_e32 v83, v88, v88
	v_mul_f32_e32 v88, v84, v84
	v_max_f32_e32 v84, v89, v89
	v_max_f32_e32 v82, 0, v82
	v_max_f32_e32 v83, 0, v83
	v_max_f32_e32 v84, 0, v84
	v_max_f32_e32 v86, 0, v86
	v_mul_f32_e32 v82, v82, v82
	v_mul_f32_e32 v83, v83, v83
	v_max_f32_e32 v85, 0, v85
	v_mul_f32_e32 v84, v84, v84
	v_mul_f32_e32 v86, v86, v86
	v_mul_f32_e32 v85, v85, v85
	v_cvt_pk_bf16_f32 v82, v86, v82
	v_cvt_pk_bf16_f32 v83, v83, v84
	v_cvt_pk_bf16_f32 v84, v90, v87
	v_max_f32_e32 v74, 0, v74
	v_cvt_pk_bf16_f32 v85, v88, v85
	global_store_dwordx4 v[98:99], v[82:85], off offset:256
	s_nop 1
	v_max_f32_e32 v75, 0, v75
	v_max_f32_e32 v76, 0, v76
	v_mul_f32_e32 v84, v74, v74
	v_max_f32_e32 v74, v79, v79
	v_or_b32_e32 v82, 48, v134
	v_max_f32_e32 v74, 0, v74
	v_mul_f32_e32 v79, v75, v75
	v_max_f32_e32 v75, v80, v80
	v_mul_f32_e32 v80, v76, v76
	v_max_f32_e32 v76, v81, v81
	v_mad_i64_i32 v[82:83], s[2:3], v82, s4, v[130:131]
	v_max_f32_e32 v78, 0, v78
	v_mul_f32_e32 v74, v74, v74
	v_max_f32_e32 v75, 0, v75
	v_max_f32_e32 v76, 0, v76
	v_max_f32_e32 v77, 0, v77
	v_lshl_add_u64 v[82:83], v[82:83], 0, v[64:65]
	v_mul_f32_e32 v78, v78, v78
	v_mul_f32_e32 v75, v75, v75
	v_mul_f32_e32 v76, v76, v76
	v_mul_f32_e32 v77, v77, v77
	v_cvt_pk_bf16_f32 v74, v78, v74
	v_max_f32_e32 v66, 0, v66
	v_max_f32_e32 v67, 0, v67
	v_max_f32_e32 v68, 0, v68
	v_cvt_pk_bf16_f32 v75, v75, v76
	v_cvt_pk_bf16_f32 v76, v84, v79
	v_cvt_pk_bf16_f32 v77, v80, v77
	global_store_dwordx4 v[82:83], v[74:77], off
	s_nop 1
	v_mul_f32_e32 v74, v66, v66
	v_max_f32_e32 v66, v71, v71
	v_mul_f32_e32 v71, v67, v67
	v_max_f32_e32 v67, v72, v72
	v_mul_f32_e32 v72, v68, v68
	v_max_f32_e32 v68, v73, v73
	v_max_f32_e32 v66, 0, v66
	v_max_f32_e32 v67, 0, v67
	v_max_f32_e32 v68, 0, v68
	v_max_f32_e32 v70, 0, v70
	v_mul_f32_e32 v66, v66, v66
	v_mul_f32_e32 v67, v67, v67
	v_max_f32_e32 v69, 0, v69
	v_mul_f32_e32 v68, v68, v68
	v_mul_f32_e32 v70, v70, v70
	v_mul_f32_e32 v69, v69, v69
	v_cvt_pk_bf16_f32 v66, v70, v66
	v_cvt_pk_bf16_f32 v67, v67, v68
	v_cvt_pk_bf16_f32 v68, v74, v71
	v_max_f32_e32 v56, 0, v56
	v_cvt_pk_bf16_f32 v69, v72, v69
	global_store_dwordx4 v[82:83], v[66:69], off offset:256
	s_nop 1
	v_max_f32_e32 v57, 0, v57
	v_max_f32_e32 v58, 0, v58
	v_mul_f32_e32 v68, v56, v56
	v_max_f32_e32 v56, v61, v61
	v_add_u32_e32 v66, 0x80, v134
	v_max_f32_e32 v56, 0, v56
	v_mul_f32_e32 v61, v57, v57
	v_max_f32_e32 v57, v62, v62
	v_mul_f32_e32 v62, v58, v58
	v_max_f32_e32 v58, v63, v63
	v_mad_i64_i32 v[66:67], s[2:3], v66, s4, v[130:131]
	v_max_f32_e32 v60, 0, v60
	v_mul_f32_e32 v56, v56, v56
	v_max_f32_e32 v57, 0, v57
	v_max_f32_e32 v58, 0, v58
	v_max_f32_e32 v59, 0, v59
	v_lshl_add_u64 v[66:67], v[66:67], 0, v[64:65]
	v_mul_f32_e32 v60, v60, v60
	v_mul_f32_e32 v57, v57, v57
	v_mul_f32_e32 v58, v58, v58
	v_mul_f32_e32 v59, v59, v59
	v_cvt_pk_bf16_f32 v56, v60, v56
	v_max_f32_e32 v48, 0, v48
	v_max_f32_e32 v49, 0, v49
	v_max_f32_e32 v50, 0, v50
	v_cvt_pk_bf16_f32 v57, v57, v58
	v_cvt_pk_bf16_f32 v58, v68, v61
	v_cvt_pk_bf16_f32 v59, v62, v59
	global_store_dwordx4 v[66:67], v[56:59], off
	s_nop 1
	v_mul_f32_e32 v56, v48, v48
	v_max_f32_e32 v48, v53, v53
	v_mul_f32_e32 v53, v49, v49
	v_max_f32_e32 v49, v54, v54
	v_mul_f32_e32 v54, v50, v50
	v_max_f32_e32 v50, v55, v55
	v_max_f32_e32 v48, 0, v48
	v_max_f32_e32 v49, 0, v49
	v_max_f32_e32 v50, 0, v50
	v_max_f32_e32 v52, 0, v52
	v_mul_f32_e32 v48, v48, v48
	v_mul_f32_e32 v49, v49, v49
; __device__ __forceinline__ unsigned cvt_pk_bf16(float lo, float hi) { unsigned r; asm volatile("v_cvt_pk_bf16_f32 %0, %1, %2" : "=v"(r) : "v"(lo), "v"(hi)); return r; }
; #define PG8_WAIT_V(n) asm volatile("s_waitcnt vmcnt(" #n ")" ::: "memory")
; #define PG8_BAR __builtin_amdgcn_s_barrier()
;     __device__ __forceinline__ void operator()(const f32x4 (&acc)[2][2][4][2], const Unit& u, int wr, int wc, int fr, int fq) const {
;     ...
;             for (int m = 0; m < 4; ++m) { bf16_t* rowp = O + (size_t)(row0 + ai * HALF + m * 16) * LDF + col0;
; #pragma unroll
;                 for (int bj = 0; bj < 2; ++bj) { f32x4 v0 = acc[ai][bj][m][0], v1 = acc[ai][bj][m][1];
; #pragma unroll
;                     for (int j = 0; j < 4; ++j) { const float a = fmaxf(v0[j], 0.f), b = fmaxf(v1[j], 0.f); v0[j] = a * a; v1[j] = b * b; }
;                     u32x4 w; w.x = cvt_pk_bf16(v0[0], v0[1]); w.y = cvt_pk_bf16(v0[2], v0[3]); w.z = cvt_pk_bf16(v1[0], v1[1]); w.w = cvt_pk_bf16(v1[2], v1[3]);
;                     *(u32x4*)(rowp + bj * HALF) = w; } }
;     ...
;         cur = nxt; cA = nA; cB = nB; ++ui;
;     }
;     PG8_WAIT_V(0);
;     if (wr == 0) PG8_BAR;
;     PG8_BAR;
	v_max_f32_e32 v51, 0, v51
	v_mul_f32_e32 v50, v50, v50
	v_mul_f32_e32 v52, v52, v52
	v_mul_f32_e32 v51, v51, v51
	v_cvt_pk_bf16_f32 v48, v52, v48
	v_cvt_pk_bf16_f32 v49, v49, v50
	v_cvt_pk_bf16_f32 v50, v56, v53
	v_max_f32_e32 v40, 0, v40
	v_cvt_pk_bf16_f32 v51, v54, v51
	global_store_dwordx4 v[66:67], v[48:51], off offset:256
	s_nop 1
	v_max_f32_e32 v41, 0, v41
	v_max_f32_e32 v42, 0, v42
	v_mul_f32_e32 v50, v40, v40
	v_max_f32_e32 v40, v45, v45
	v_add_u32_e32 v48, 0x90, v134
	v_max_f32_e32 v40, 0, v40
	v_mul_f32_e32 v45, v41, v41
	v_max_f32_e32 v41, v46, v46
	v_mul_f32_e32 v46, v42, v42
	v_max_f32_e32 v42, v47, v47
	v_mad_i64_i32 v[48:49], s[2:3], v48, s4, v[130:131]
	v_max_f32_e32 v44, 0, v44
	v_mul_f32_e32 v40, v40, v40
	v_max_f32_e32 v41, 0, v41
	v_max_f32_e32 v42, 0, v42
	v_max_f32_e32 v43, 0, v43
	v_lshl_add_u64 v[48:49], v[48:49], 0, v[64:65]
	v_mul_f32_e32 v44, v44, v44
	v_mul_f32_e32 v41, v41, v41
	v_mul_f32_e32 v42, v42, v42
	v_mul_f32_e32 v43, v43, v43
	v_cvt_pk_bf16_f32 v40, v44, v40
	v_max_f32_e32 v32, 0, v32
	v_max_f32_e32 v33, 0, v33
	v_max_f32_e32 v34, 0, v34
	v_cvt_pk_bf16_f32 v41, v41, v42
	v_cvt_pk_bf16_f32 v42, v50, v45
	v_cvt_pk_bf16_f32 v43, v46, v43
	global_store_dwordx4 v[48:49], v[40:43], off
	s_nop 1
	v_mul_f32_e32 v40, v32, v32
	v_max_f32_e32 v32, v37, v37
	v_mul_f32_e32 v37, v33, v33
	v_max_f32_e32 v33, v38, v38
	v_mul_f32_e32 v38, v34, v34
	v_max_f32_e32 v34, v39, v39
	v_max_f32_e32 v32, 0, v32
	v_max_f32_e32 v33, 0, v33
	v_max_f32_e32 v34, 0, v34
	v_max_f32_e32 v36, 0, v36
	v_mul_f32_e32 v32, v32, v32
	v_mul_f32_e32 v33, v33, v33
	v_max_f32_e32 v35, 0, v35
	v_mul_f32_e32 v34, v34, v34
	v_mul_f32_e32 v36, v36, v36
	v_mul_f32_e32 v35, v35, v35
	v_cvt_pk_bf16_f32 v32, v36, v32
	v_cvt_pk_bf16_f32 v33, v33, v34
	v_cvt_pk_bf16_f32 v34, v40, v37
	v_max_f32_e32 v24, 0, v24
	v_cvt_pk_bf16_f32 v35, v38, v35
	global_store_dwordx4 v[48:49], v[32:35], off offset:256
	s_nop 1
	v_max_f32_e32 v25, 0, v25
	v_max_f32_e32 v26, 0, v26
	v_mul_f32_e32 v34, v24, v24
	v_max_f32_e32 v24, v29, v29
	v_add_u32_e32 v32, 0xa0, v134
	v_max_f32_e32 v24, 0, v24
	v_mul_f32_e32 v29, v25, v25
	v_max_f32_e32 v25, v30, v30
	v_mul_f32_e32 v30, v26, v26
	v_max_f32_e32 v26, v31, v31
	v_mad_i64_i32 v[32:33], s[2:3], v32, s4, v[130:131]
	v_max_f32_e32 v28, 0, v28
	v_mul_f32_e32 v24, v24, v24
	v_max_f32_e32 v25, 0, v25
	v_max_f32_e32 v26, 0, v26
	v_max_f32_e32 v27, 0, v27
	v_lshl_add_u64 v[32:33], v[32:33], 0, v[64:65]
	v_mul_f32_e32 v28, v28, v28
	v_mul_f32_e32 v25, v25, v25
	v_mul_f32_e32 v26, v26, v26
	v_mul_f32_e32 v27, v27, v27
	v_cvt_pk_bf16_f32 v24, v28, v24
	v_max_f32_e32 v16, 0, v16
	v_max_f32_e32 v17, 0, v17
	v_max_f32_e32 v18, 0, v18
	v_cvt_pk_bf16_f32 v25, v25, v26
	v_cvt_pk_bf16_f32 v26, v34, v29
	v_cvt_pk_bf16_f32 v27, v30, v27
	global_store_dwordx4 v[32:33], v[24:27], off
	s_nop 1
	v_mul_f32_e32 v24, v16, v16
	v_max_f32_e32 v16, v21, v21
	v_mul_f32_e32 v21, v17, v17
	v_max_f32_e32 v17, v22, v22
	v_mul_f32_e32 v22, v18, v18
	v_max_f32_e32 v18, v23, v23
	v_max_f32_e32 v16, 0, v16
	v_max_f32_e32 v17, 0, v17
	v_max_f32_e32 v18, 0, v18
	v_max_f32_e32 v20, 0, v20
	v_mul_f32_e32 v16, v16, v16
	v_mul_f32_e32 v17, v17, v17
	v_max_f32_e32 v19, 0, v19
	v_mul_f32_e32 v18, v18, v18
	v_mul_f32_e32 v20, v20, v20
	v_mul_f32_e32 v19, v19, v19
	v_cvt_pk_bf16_f32 v16, v20, v16
	v_cvt_pk_bf16_f32 v17, v17, v18
	v_cvt_pk_bf16_f32 v18, v24, v21
	v_max_f32_e32 v8, 0, v8
	v_cvt_pk_bf16_f32 v19, v22, v19
	global_store_dwordx4 v[32:33], v[16:19], off offset:256
	s_nop 1
	v_max_f32_e32 v9, 0, v9
	v_max_f32_e32 v10, 0, v10
	v_mul_f32_e32 v18, v8, v8
	v_max_f32_e32 v8, v13, v13
	v_add_u32_e32 v16, 0xb0, v134
	v_max_f32_e32 v8, 0, v8
	v_mul_f32_e32 v13, v9, v9
	v_max_f32_e32 v9, v14, v14
	v_mul_f32_e32 v14, v10, v10
	v_max_f32_e32 v10, v15, v15
	v_mad_i64_i32 v[16:17], s[2:3], v16, s4, v[130:131]
	v_max_f32_e32 v12, 0, v12
	v_mul_f32_e32 v8, v8, v8
	v_max_f32_e32 v9, 0, v9
	v_max_f32_e32 v10, 0, v10
	v_max_f32_e32 v11, 0, v11
	v_lshl_add_u64 v[16:17], v[16:17], 0, v[64:65]
	v_mul_f32_e32 v12, v12, v12
	v_mul_f32_e32 v9, v9, v9
	v_mul_f32_e32 v10, v10, v10
	v_mul_f32_e32 v11, v11, v11
	v_cvt_pk_bf16_f32 v8, v12, v8
	v_max_f32_e32 v0, 0, v0
	v_max_f32_e32 v1, 0, v1
	v_max_f32_e32 v2, 0, v2
	v_cvt_pk_bf16_f32 v9, v9, v10
	v_cvt_pk_bf16_f32 v10, v18, v13
	v_cvt_pk_bf16_f32 v11, v14, v11
	global_store_dwordx4 v[16:17], v[8:11], off
	s_nop 1
	v_mul_f32_e32 v8, v0, v0
	v_max_f32_e32 v0, v5, v5
	v_mul_f32_e32 v5, v1, v1
	v_max_f32_e32 v1, v6, v6
	v_mul_f32_e32 v6, v2, v2
	v_max_f32_e32 v2, v7, v7
	v_max_f32_e32 v0, 0, v0
	v_max_f32_e32 v1, 0, v1
	v_max_f32_e32 v2, 0, v2
	v_max_f32_e32 v3, 0, v3
	v_max_f32_e32 v4, 0, v4
	v_mul_f32_e32 v0, v0, v0
	v_mul_f32_e32 v1, v1, v1
	v_mul_f32_e32 v2, v2, v2
	v_mul_f32_e32 v3, v3, v3
	v_mul_f32_e32 v4, v4, v4
	v_cvt_pk_bf16_f32 v0, v4, v0
	v_cvt_pk_bf16_f32 v1, v1, v2
	v_cvt_pk_bf16_f32 v2, v8, v5
	v_cvt_pk_bf16_f32 v3, v6, v3
	global_store_dwordx4 v[16:17], v[0:3], off offset:256
	s_nop 1
	s_waitcnt vmcnt(0)
	s_cmpk_lt_u32 s14, 0x100
	s_movk_i32 s27, 0x1000
	s_cbranch_scc0 .LBB0_149
	s_barrier

; #define PG8_STAGE(bufoff, gbase, voff) do { _Pragma("unroll") for (int _i = 0; _i < 2; ++_i) \
;         __builtin_amdgcn_global_load_lds((const unsigned*)((const char*)(gbase) + (voff)[_i]), (LAS unsigned*)(lds + (bufoff) + ldsw + _i * 8192), 16, 0, 0); } while (0)
; #define PG8_LDA(dst, b, h) do { _Pragma("unroll") for (int m = 0; m < 4; ++m) _Pragma("unroll") for (int k = 0; k < 2; ++k) dst[m][k] = *(const LAS bf16x8*)(lds + PG8_SA(b, h) + aoff + m * 2048 + k * 1024); } while (0)
; #define PG8_LDB(dst, b, h) do { _Pragma("unroll") for (int n = 0; n < 2; ++n) _Pragma("unroll") for (int k = 0; k < 2; ++k) dst[n][k] = *(const LAS bf16x8*)(lds + PG8_SB(b, h) + boff + n * 2048 + k * 1024); } while (0)
; #define PG8_MMA(ai, bj, At, Bt) do { __builtin_amdgcn_s_setprio(1); _Pragma("unroll") for (int m = 0; m < 4; ++m) _Pragma("unroll") for (int n = 0; n < 2; ++n) _Pragma("unroll") for (int k = 0; k < 2; ++k) \
;         acc[ai][bj][m][n] = __builtin_amdgcn_mfma_f32_16x16x32_bf16(Bt[n][k], At[m][k], acc[ai][bj][m][n], 0, 0, 0); __builtin_amdgcn_s_setprio(0); } while (0)
; #define PG8_WAIT_L(n) asm volatile("s_waitcnt lgkmcnt(" #n ")" ::: "memory")
; #define PG8_BAR __builtin_amdgcn_s_barrier()
; #define PG8_SCHED __builtin_amdgcn_sched_barrier(0)
;     ...
;             const char* a1 = cA + (size_t)(t + 1) * kstep;
;             const char* a2 = last ? nA : cA + (size_t)(t + 2) * kstep; const char* b2 = last ? nB : cB + (size_t)(t + 2) * kstep;
;             const char* a3 = a2 + kstep; const char* b3 = b2 + kstep;
;             PG8_LDB(B0, 0, 0); PG8_SCHED; PG8_LDA(At, 0, 0); PG8_STAGE(PG8_SA(1, 1), a1 + hstep, voffA);
;             PG8_WAIT_L(8); PG8_BAR; PG8_WAIT_L(0); PG8_MMA(0, 0, At, B0); PG8_BAR; PG8_SCHED;
;             PG8_LDB(B1, 0, 1); PG8_STAGE(PG8_SB(0, 0), b2, voffB);
;             PG8_BAR; PG8_WAIT_L(0); PG8_MMA(0, 1, At, B1); PG8_BAR;
;             PG8_LDA(At, 0, 1); PG8_STAGE(PG8_SA(0, 0), a2, voffA);
;             PG8_BAR; PG8_WAIT_L(0); PG8_MMA(1, 0, At, B0); PG8_BAR; PG8_SCHED;
.LBB0_475:
	s_or_b32 s94, s12, 1
	s_add_i32 s12, s12, 2
	s_mov_b32 s13, s95
	s_lshl_b64 s[2:3], s[12:13], 7
	s_add_u32 s7, s24, s2
	s_addc_u32 s13, s25, s3
	s_and_b64 vcc, s[44:45], exec
	s_cselect_b32 vcc_hi, s85, s13
	s_cselect_b32 vcc_lo, s84, s7
	s_add_u32 s7, s42, s2
	s_addc_u32 s13, s43, s3
	s_add_i32 s35, 0, 0x10000
	v_add_u32_e32 v64, s35, v220
	ds_read_b128 v[134:137], v64
	ds_read_b128 v[138:141], v64 offset:1024
	ds_read_b128 v[142:145], v64 offset:2048
	ds_read_b128 v[146:149], v64 offset:3072
	s_and_b64 s[2:3], s[44:45], exec
	s_cselect_b32 s45, s9, s13
	s_cselect_b32 s44, s8, s7
	s_lshl_b64 s[2:3], s[94:95], 7
	s_add_u32 s2, s47, s2
	s_addc_u32 s3, s89, s3
	v_lshl_add_u64 v[182:183], s[2:3], 0, v[130:131]
	s_add_i32 m0, s19, 0xc000
	ds_read_b128 v[150:153], v229
	ds_read_b128 v[154:157], v229 offset:1024
	ds_read_b128 v[158:161], v229 offset:2048
	ds_read_b128 v[162:165], v229 offset:3072
	ds_read_b128 v[166:169], v229 offset:4096
	ds_read_b128 v[170:173], v229 offset:5120
	ds_read_b128 v[174:177], v229 offset:6144
	ds_read_b128 v[178:181], v229 offset:7168
	global_load_lds_dwordx4 v[182:183], off
	v_lshl_add_u64 v[182:183], s[2:3], 0, v[132:133]
	s_add_i32 m0, s19, 0xe000
	s_nop 0
	global_load_lds_dwordx4 v[182:183], off
	s_waitcnt lgkmcnt(8)
	s_barrier
	s_waitcnt lgkmcnt(0)
	v_mfma_f32_16x16x32_bf16 v[118:121], v[134:137], v[150:153], v[118:121]
	v_mfma_f32_16x16x32_bf16 v[114:117], v[142:145], v[150:153], v[114:117]
	v_mfma_f32_16x16x32_bf16 v[102:105], v[134:137], v[158:161], v[102:105]
	v_mfma_f32_16x16x32_bf16 v[98:101], v[142:145], v[158:161], v[98:101]
	v_mfma_f32_16x16x32_bf16 v[86:89], v[134:137], v[166:169], v[86:89]
	v_mfma_f32_16x16x32_bf16 v[82:85], v[142:145], v[166:169], v[82:85]
	v_mfma_f32_16x16x32_bf16 v[70:73], v[134:137], v[174:177], v[70:73]
	v_mfma_f32_16x16x32_bf16 v[66:69], v[142:145], v[174:177], v[66:69]
	v_mfma_f32_16x16x32_bf16 v[118:121], v[138:141], v[154:157], v[118:121]
	v_mfma_f32_16x16x32_bf16 v[114:117], v[146:149], v[154:157], v[114:117]
	v_mfma_f32_16x16x32_bf16 v[102:105], v[138:141], v[162:165], v[102:105]
	v_mfma_f32_16x16x32_bf16 v[98:101], v[146:149], v[162:165], v[98:101]
	v_mfma_f32_16x16x32_bf16 v[86:89], v[138:141], v[170:173], v[86:89]
	v_mfma_f32_16x16x32_bf16 v[82:85], v[146:149], v[170:173], v[82:85]
	v_mfma_f32_16x16x32_bf16 v[70:73], v[138:141], v[178:181], v[70:73]
	v_mfma_f32_16x16x32_bf16 v[66:69], v[146:149], v[178:181], v[66:69]
	s_barrier
	s_add_i32 s7, 0, 0x14000
	s_add_i32 s2, s35, s18
	v_add_u32_e32 v64, s7, v220
	v_lshl_add_u64 v[198:199], s[44:45], 0, v[130:131]
	s_mov_b32 m0, s2
	ds_read_b128 v[182:185], v64
	ds_read_b128 v[186:189], v64 offset:1024
	ds_read_b128 v[190:193], v64 offset:2048
	ds_read_b128 v[194:197], v64 offset:3072
	global_load_lds_dwordx4 v[198:199], off
	v_lshl_add_u64 v[246:247], s[44:45], 0, v[132:133]
	s_add_i32 m0, s2, 0x2000
	s_nop 0
	global_load_lds_dwordx4 v[246:247], off
	s_barrier
	s_waitcnt lgkmcnt(0)
	v_mfma_f32_16x16x32_bf16 v[126:129], v[182:185], v[150:153], v[126:129]
	v_mfma_f32_16x16x32_bf16 v[122:125], v[190:193], v[150:153], v[122:125]
	v_mfma_f32_16x16x32_bf16 v[110:113], v[182:185], v[158:161], v[110:113]
	v_mfma_f32_16x16x32_bf16 v[106:109], v[190:193], v[158:161], v[106:109]
	v_mfma_f32_16x16x32_bf16 v[94:97], v[182:185], v[166:169], v[94:97]
	v_mfma_f32_16x16x32_bf16 v[90:93], v[190:193], v[166:169], v[90:93]
	v_mfma_f32_16x16x32_bf16 v[78:81], v[182:185], v[174:177], v[78:81]
	v_mfma_f32_16x16x32_bf16 v[74:77], v[190:193], v[174:177], v[74:77]
	v_mfma_f32_16x16x32_bf16 v[126:129], v[186:189], v[154:157], v[126:129]
	v_mfma_f32_16x16x32_bf16 v[122:125], v[194:197], v[154:157], v[122:125]
	v_mfma_f32_16x16x32_bf16 v[110:113], v[186:189], v[162:165], v[110:113]
	v_mfma_f32_16x16x32_bf16 v[106:109], v[194:197], v[162:165], v[106:109]
	v_mfma_f32_16x16x32_bf16 v[94:97], v[186:189], v[170:173], v[94:97]
	v_mfma_f32_16x16x32_bf16 v[90:93], v[194:197], v[170:173], v[90:93]
	v_mfma_f32_16x16x32_bf16 v[78:81], v[186:189], v[178:181], v[78:81]
	v_mfma_f32_16x16x32_bf16 v[74:77], v[194:197], v[178:181], v[74:77]
	s_mov_b32 m0, s19
	v_lshl_add_u64 v[212:213], vcc, 0, v[130:131]
	s_barrier
	ds_read_b128 v[150:153], v229 offset:16384
	ds_read_b128 v[154:157], v229 offset:17408
	ds_read_b128 v[158:161], v229 offset:18432
	ds_read_b128 v[162:165], v229 offset:19456
	ds_read_b128 v[166:169], v229 offset:20480
	ds_read_b128 v[170:173], v229 offset:21504
	ds_read_b128 v[174:177], v229 offset:22528
	ds_read_b128 v[178:181], v229 offset:23552
	global_load_lds_dwordx4 v[212:213], off
	v_lshl_add_u64 v[208:209], vcc, 0, v[132:133]
	s_mov_b32 m0, s21
	s_nop 0
	global_load_lds_dwordx4 v[208:209], off
	s_barrier
	s_waitcnt lgkmcnt(0)
	v_mfma_f32_16x16x32_bf16 v[52:55], v[134:137], v[150:153], v[52:55]
	v_mfma_f32_16x16x32_bf16 v[48:51], v[142:145], v[150:153], v[48:51]
	v_mfma_f32_16x16x32_bf16 v[36:39], v[134:137], v[158:161], v[36:39]
	v_mfma_f32_16x16x32_bf16 v[32:35], v[142:145], v[158:161], v[32:35]
	v_mfma_f32_16x16x32_bf16 v[20:23], v[134:137], v[166:169], v[20:23]
	v_mfma_f32_16x16x32_bf16 v[16:19], v[142:145], v[166:169], v[16:19]
	v_mfma_f32_16x16x32_bf16 v[4:7], v[134:137], v[174:177], v[4:7]
	v_mfma_f32_16x16x32_bf16 v[0:3], v[142:145], v[174:177], v[0:3]
	v_mfma_f32_16x16x32_bf16 v[52:55], v[138:141], v[154:157], v[52:55]
	v_mfma_f32_16x16x32_bf16 v[48:51], v[146:149], v[154:157], v[48:51]
	v_mfma_f32_16x16x32_bf16 v[36:39], v[138:141], v[162:165], v[36:39]
	v_mfma_f32_16x16x32_bf16 v[32:35], v[146:149], v[162:165], v[32:35]
	v_mfma_f32_16x16x32_bf16 v[20:23], v[138:141], v[170:173], v[20:23]
	v_mfma_f32_16x16x32_bf16 v[16:19], v[146:149], v[170:173], v[16:19]
	v_mfma_f32_16x16x32_bf16 v[4:7], v[138:141], v[178:181], v[4:7]
	v_mfma_f32_16x16x32_bf16 v[0:3], v[146:149], v[178:181], v[0:3]
	s_barrier
; #define PG8_STAGE(bufoff, gbase, voff) do { _Pragma("unroll") for (int _i = 0; _i < 2; ++_i) \
;         __builtin_amdgcn_global_load_lds((const unsigned*)((const char*)(gbase) + (voff)[_i]), (LAS unsigned*)(lds + (bufoff) + ldsw + _i * 8192), 16, 0, 0); } while (0)
; #define PG8_LDA(dst, b, h) do { _Pragma("unroll") for (int m = 0; m < 4; ++m) _Pragma("unroll") for (int k = 0; k < 2; ++k) dst[m][k] = *(const LAS bf16x8*)(lds + PG8_SA(b, h) + aoff + m * 2048 + k * 1024); } while (0)
; #define PG8_LDB(dst, b, h) do { _Pragma("unroll") for (int n = 0; n < 2; ++n) _Pragma("unroll") for (int k = 0; k < 2; ++k) dst[n][k] = *(const LAS bf16x8*)(lds + PG8_SB(b, h) + boff + n * 2048 + k * 1024); } while (0)
; #define PG8_MMA(ai, bj, At, Bt) do { __builtin_amdgcn_s_setprio(1); _Pragma("unroll") for (int m = 0; m < 4; ++m) _Pragma("unroll") for (int n = 0; n < 2; ++n) _Pragma("unroll") for (int k = 0; k < 2; ++k) \
;         acc[ai][bj][m][n] = __builtin_amdgcn_mfma_f32_16x16x32_bf16(Bt[n][k], At[m][k], acc[ai][bj][m][n], 0, 0, 0); __builtin_amdgcn_s_setprio(0); } while (0)
; #define PG8_WAIT_V(n) asm volatile("s_waitcnt vmcnt(" #n ")" ::: "memory")
; #define PG8_WAIT_L(n) asm volatile("s_waitcnt lgkmcnt(" #n ")" ::: "memory")
; #define PG8_BAR __builtin_amdgcn_s_barrier()
; #define PG8_SCHED __builtin_amdgcn_sched_barrier(0)
;     ...
;             PG8_STAGE(PG8_SB(0, 1), b2 + hstep, voffB);
;             PG8_WAIT_V(6); PG8_BAR; PG8_MMA(1, 1, At, B1); PG8_BAR;
;             PG8_LDB(B0, 1, 0); PG8_SCHED; PG8_LDA(At, 1, 0); PG8_STAGE(PG8_SA(0, 1), a2 + hstep, voffA);
;             PG8_WAIT_L(8); PG8_BAR; PG8_WAIT_L(0); PG8_MMA(0, 0, At, B0); PG8_BAR; PG8_SCHED;
;             PG8_LDB(B1, 1, 1); PG8_STAGE(PG8_SB(1, 0), b3, voffB);
;             PG8_BAR; PG8_WAIT_L(0); PG8_MMA(0, 1, At, B1); PG8_BAR;
;             PG8_LDA(At, 1, 1); PG8_STAGE(PG8_SA(1, 0), a3, voffA);
	s_add_u32 s2, s44, s82
	s_addc_u32 s3, s45, 0
	s_add_i32 s7, s7, s18
	v_lshl_add_u64 v[210:211], s[2:3], 0, v[130:131]
	s_mov_b32 m0, s7
	v_lshl_add_u64 v[214:215], s[2:3], 0, v[132:133]
	global_load_lds_dwordx4 v[210:211], off
	s_add_i32 m0, s7, 0x2000
	s_nop 0
	global_load_lds_dwordx4 v[214:215], off
	s_waitcnt vmcnt(6)
	s_barrier
	v_mfma_f32_16x16x32_bf16 v[60:63], v[182:185], v[150:153], v[60:63]
	v_mfma_f32_16x16x32_bf16 v[56:59], v[190:193], v[150:153], v[56:59]
	v_mfma_f32_16x16x32_bf16 v[44:47], v[182:185], v[158:161], v[44:47]
	v_mfma_f32_16x16x32_bf16 v[40:43], v[190:193], v[158:161], v[40:43]
	v_mfma_f32_16x16x32_bf16 v[28:31], v[182:185], v[166:169], v[28:31]
	v_mfma_f32_16x16x32_bf16 v[24:27], v[190:193], v[166:169], v[24:27]
	v_mfma_f32_16x16x32_bf16 v[12:15], v[182:185], v[174:177], v[12:15]
	v_mfma_f32_16x16x32_bf16 v[8:11], v[190:193], v[174:177], v[8:11]
	v_mfma_f32_16x16x32_bf16 v[60:63], v[186:189], v[154:157], v[60:63]
	v_mfma_f32_16x16x32_bf16 v[56:59], v[194:197], v[154:157], v[56:59]
	v_mfma_f32_16x16x32_bf16 v[44:47], v[186:189], v[162:165], v[44:47]
	v_mfma_f32_16x16x32_bf16 v[40:43], v[194:197], v[162:165], v[40:43]
	v_mfma_f32_16x16x32_bf16 v[28:31], v[186:189], v[170:173], v[28:31]
	v_mfma_f32_16x16x32_bf16 v[24:27], v[194:197], v[170:173], v[24:27]
	v_mfma_f32_16x16x32_bf16 v[12:15], v[186:189], v[178:181], v[12:15]
	v_mfma_f32_16x16x32_bf16 v[8:11], v[194:197], v[178:181], v[8:11]
	s_add_i32 s7, 0, 0x18000
	v_add_u32_e32 v64, s7, v220
	s_barrier
	ds_read_b128 v[134:137], v64
	ds_read_b128 v[138:141], v64 offset:1024
	ds_read_b128 v[142:145], v64 offset:2048
	ds_read_b128 v[146:149], v64 offset:3072
	s_add_u32 s2, vcc_lo, s82
	s_addc_u32 s3, vcc_hi, 0
	s_mov_b32 m0, s31
	v_lshl_add_u64 v[182:183], s[2:3], 0, v[130:131]
	ds_read_b128 v[150:153], v229 offset:32768
	ds_read_b128 v[154:157], v229 offset:33792
	ds_read_b128 v[158:161], v229 offset:34816
	ds_read_b128 v[162:165], v229 offset:35840
	ds_read_b128 v[166:169], v229 offset:36864
	ds_read_b128 v[170:173], v229 offset:37888
	ds_read_b128 v[174:177], v229 offset:38912
	ds_read_b128 v[178:181], v229 offset:39936
	global_load_lds_dwordx4 v[182:183], off
	v_lshl_add_u64 v[182:183], s[2:3], 0, v[132:133]
	s_mov_b32 m0, s83
	s_nop 0
	global_load_lds_dwordx4 v[182:183], off
	s_waitcnt lgkmcnt(8)
	s_barrier
	s_waitcnt lgkmcnt(0)
	v_mfma_f32_16x16x32_bf16 v[118:121], v[134:137], v[150:153], v[118:121]
	v_mfma_f32_16x16x32_bf16 v[114:117], v[142:145], v[150:153], v[114:117]
	v_mfma_f32_16x16x32_bf16 v[102:105], v[134:137], v[158:161], v[102:105]
	v_mfma_f32_16x16x32_bf16 v[98:101], v[142:145], v[158:161], v[98:101]
	v_mfma_f32_16x16x32_bf16 v[86:89], v[134:137], v[166:169], v[86:89]
	v_mfma_f32_16x16x32_bf16 v[82:85], v[142:145], v[166:169], v[82:85]
	v_mfma_f32_16x16x32_bf16 v[70:73], v[134:137], v[174:177], v[70:73]
	v_mfma_f32_16x16x32_bf16 v[66:69], v[142:145], v[174:177], v[66:69]
	v_mfma_f32_16x16x32_bf16 v[118:121], v[138:141], v[154:157], v[118:121]
	v_mfma_f32_16x16x32_bf16 v[114:117], v[146:149], v[154:157], v[114:117]
	v_mfma_f32_16x16x32_bf16 v[102:105], v[138:141], v[162:165], v[102:105]
	v_mfma_f32_16x16x32_bf16 v[98:101], v[146:149], v[162:165], v[98:101]
	v_mfma_f32_16x16x32_bf16 v[86:89], v[138:141], v[170:173], v[86:89]
	v_mfma_f32_16x16x32_bf16 v[82:85], v[146:149], v[170:173], v[82:85]
	v_mfma_f32_16x16x32_bf16 v[70:73], v[138:141], v[178:181], v[70:73]
	v_mfma_f32_16x16x32_bf16 v[66:69], v[146:149], v[178:181], v[66:69]
	s_barrier
	s_add_i32 s2, 0, 0x1c000
	s_add_i32 s3, s7, s18
	v_add_u32_e32 v64, s2, v220
	v_lshl_add_u64 v[198:199], v[198:199], 0, s[16:17]
	s_mov_b32 m0, s3
	ds_read_b128 v[182:185], v64
	ds_read_b128 v[186:189], v64 offset:1024
	ds_read_b128 v[190:193], v64 offset:2048
	ds_read_b128 v[194:197], v64 offset:3072
	global_load_lds_dwordx4 v[198:199], off
	v_lshl_add_u64 v[198:199], v[246:247], 0, s[16:17]
	s_add_i32 m0, s3, 0x2000
	s_nop 0
	global_load_lds_dwordx4 v[198:199], off
	s_barrier
; #define PG8_STAGE(bufoff, gbase, voff) do { _Pragma("unroll") for (int _i = 0; _i < 2; ++_i) \
;         __builtin_amdgcn_global_load_lds((const unsigned*)((const char*)(gbase) + (voff)[_i]), (LAS unsigned*)(lds + (bufoff) + ldsw + _i * 8192), 16, 0, 0); } while (0)
; #define PG8_LDA(dst, b, h) do { _Pragma("unroll") for (int m = 0; m < 4; ++m) _Pragma("unroll") for (int k = 0; k < 2; ++k) dst[m][k] = *(const LAS bf16x8*)(lds + PG8_SA(b, h) + aoff + m * 2048 + k * 1024); } while (0)
; #define PG8_MMA(ai, bj, At, Bt) do { __builtin_amdgcn_s_setprio(1); _Pragma("unroll") for (int m = 0; m < 4; ++m) _Pragma("unroll") for (int n = 0; n < 2; ++n) _Pragma("unroll") for (int k = 0; k < 2; ++k) \
;         acc[ai][bj][m][n] = __builtin_amdgcn_mfma_f32_16x16x32_bf16(Bt[n][k], At[m][k], acc[ai][bj][m][n], 0, 0, 0); __builtin_amdgcn_s_setprio(0); } while (0)
; #define PG8_WAIT_V(n) asm volatile("s_waitcnt vmcnt(" #n ")" ::: "memory")
; #define PG8_WAIT_L(n) asm volatile("s_waitcnt lgkmcnt(" #n ")" ::: "memory")
; #define PG8_BAR __builtin_amdgcn_s_barrier()
; #define PG8_SCHED __builtin_amdgcn_sched_barrier(0)
;     ...
;             PG8_LDA(At, 1, 1); PG8_STAGE(PG8_SA(1, 0), a3, voffA);
;             PG8_BAR; PG8_WAIT_L(0); PG8_MMA(1, 0, At, B0); PG8_BAR; PG8_SCHED;
;             PG8_STAGE(PG8_SB(1, 1), b3 + hstep, voffB);
;             PG8_WAIT_V(6); PG8_BAR; PG8_MMA(1, 1, At, B1); PG8_BAR;
;         }
	s_waitcnt lgkmcnt(0)
	v_mfma_f32_16x16x32_bf16 v[126:129], v[182:185], v[150:153], v[126:129]
	v_mfma_f32_16x16x32_bf16 v[122:125], v[190:193], v[150:153], v[122:125]
	v_mfma_f32_16x16x32_bf16 v[110:113], v[182:185], v[158:161], v[110:113]
	v_mfma_f32_16x16x32_bf16 v[106:109], v[190:193], v[158:161], v[106:109]
	v_mfma_f32_16x16x32_bf16 v[94:97], v[182:185], v[166:169], v[94:97]
	v_mfma_f32_16x16x32_bf16 v[90:93], v[190:193], v[166:169], v[90:93]
	v_mfma_f32_16x16x32_bf16 v[78:81], v[182:185], v[174:177], v[78:81]
	v_mfma_f32_16x16x32_bf16 v[74:77], v[190:193], v[174:177], v[74:77]
	v_mfma_f32_16x16x32_bf16 v[126:129], v[186:189], v[154:157], v[126:129]
	v_mfma_f32_16x16x32_bf16 v[122:125], v[194:197], v[154:157], v[122:125]
	v_mfma_f32_16x16x32_bf16 v[110:113], v[186:189], v[162:165], v[110:113]
	v_mfma_f32_16x16x32_bf16 v[106:109], v[194:197], v[162:165], v[106:109]
	v_mfma_f32_16x16x32_bf16 v[94:97], v[186:189], v[170:173], v[94:97]
	v_mfma_f32_16x16x32_bf16 v[90:93], v[194:197], v[170:173], v[90:93]
	v_mfma_f32_16x16x32_bf16 v[78:81], v[186:189], v[178:181], v[78:81]
	v_mfma_f32_16x16x32_bf16 v[74:77], v[194:197], v[178:181], v[74:77]
	s_mov_b32 m0, s36
	v_lshl_add_u64 v[198:199], v[212:213], 0, s[16:17]
	s_barrier
	ds_read_b128 v[150:153], v229 offset:49152
	ds_read_b128 v[154:157], v229 offset:50176
	ds_read_b128 v[158:161], v229 offset:51200
	ds_read_b128 v[162:165], v229 offset:52224
	ds_read_b128 v[166:169], v229 offset:53248
	ds_read_b128 v[170:173], v229 offset:54272
	ds_read_b128 v[174:177], v229 offset:55296
	ds_read_b128 v[178:181], v229 offset:56320
	global_load_lds_dwordx4 v[198:199], off
	v_lshl_add_u64 v[198:199], v[208:209], 0, s[16:17]
	s_mov_b32 m0, s37
	s_nop 0
	global_load_lds_dwordx4 v[198:199], off
	s_barrier
	s_waitcnt lgkmcnt(0)
	v_mfma_f32_16x16x32_bf16 v[52:55], v[134:137], v[150:153], v[52:55]
	v_mfma_f32_16x16x32_bf16 v[48:51], v[142:145], v[150:153], v[48:51]
	v_mfma_f32_16x16x32_bf16 v[36:39], v[134:137], v[158:161], v[36:39]
	v_mfma_f32_16x16x32_bf16 v[32:35], v[142:145], v[158:161], v[32:35]
	v_mfma_f32_16x16x32_bf16 v[20:23], v[134:137], v[166:169], v[20:23]
	v_mfma_f32_16x16x32_bf16 v[16:19], v[142:145], v[166:169], v[16:19]
	v_mfma_f32_16x16x32_bf16 v[4:7], v[134:137], v[174:177], v[4:7]
	v_mfma_f32_16x16x32_bf16 v[0:3], v[142:145], v[174:177], v[0:3]
	v_mfma_f32_16x16x32_bf16 v[52:55], v[138:141], v[154:157], v[52:55]
	v_mfma_f32_16x16x32_bf16 v[48:51], v[146:149], v[154:157], v[48:51]
	v_mfma_f32_16x16x32_bf16 v[36:39], v[138:141], v[162:165], v[36:39]
	v_mfma_f32_16x16x32_bf16 v[32:35], v[146:149], v[162:165], v[32:35]
	v_mfma_f32_16x16x32_bf16 v[20:23], v[138:141], v[170:173], v[20:23]
	v_mfma_f32_16x16x32_bf16 v[16:19], v[146:149], v[170:173], v[16:19]
	v_mfma_f32_16x16x32_bf16 v[4:7], v[138:141], v[178:181], v[4:7]
	v_mfma_f32_16x16x32_bf16 v[0:3], v[146:149], v[178:181], v[0:3]
	s_barrier
	s_add_i32 s2, s2, s18
	v_lshl_add_u64 v[134:135], v[210:211], 0, s[16:17]
	s_mov_b32 m0, s2
	s_nop 0
	global_load_lds_dwordx4 v[134:135], off
	v_lshl_add_u64 v[134:135], v[214:215], 0, s[16:17]
	s_add_i32 m0, s2, 0x2000
	s_nop 0
	global_load_lds_dwordx4 v[134:135], off
	s_waitcnt vmcnt(6)
	s_barrier
	v_mfma_f32_16x16x32_bf16 v[60:63], v[182:185], v[150:153], v[60:63]
	v_mfma_f32_16x16x32_bf16 v[56:59], v[190:193], v[150:153], v[56:59]
	v_mfma_f32_16x16x32_bf16 v[44:47], v[182:185], v[158:161], v[44:47]
	v_mfma_f32_16x16x32_bf16 v[40:43], v[190:193], v[158:161], v[40:43]
	v_mfma_f32_16x16x32_bf16 v[28:31], v[182:185], v[166:169], v[28:31]
	v_mfma_f32_16x16x32_bf16 v[24:27], v[190:193], v[166:169], v[24:27]
	v_mfma_f32_16x16x32_bf16 v[12:15], v[182:185], v[174:177], v[12:15]
	v_mfma_f32_16x16x32_bf16 v[8:11], v[190:193], v[174:177], v[8:11]
	v_mfma_f32_16x16x32_bf16 v[60:63], v[186:189], v[154:157], v[60:63]
	v_mfma_f32_16x16x32_bf16 v[56:59], v[194:197], v[154:157], v[56:59]
	v_mfma_f32_16x16x32_bf16 v[44:47], v[186:189], v[162:165], v[44:47]
	v_mfma_f32_16x16x32_bf16 v[40:43], v[194:197], v[162:165], v[40:43]
	v_mfma_f32_16x16x32_bf16 v[28:31], v[186:189], v[170:173], v[28:31]
	v_mfma_f32_16x16x32_bf16 v[24:27], v[194:197], v[170:173], v[24:27]
	v_mfma_f32_16x16x32_bf16 v[12:15], v[186:189], v[178:181], v[12:15]
	v_mfma_f32_16x16x32_bf16 v[8:11], v[194:197], v[178:181], v[8:11]
	s_cmp_ge_u32 s12, s6
	s_barrier
	s_cbranch_scc1 .LBB0_482

; #define PG8_STAGE(bufoff, gbase, voff) do { _Pragma("unroll") for (int _i = 0; _i < 2; ++_i) \
;         __builtin_amdgcn_global_load_lds((const unsigned*)((const char*)(gbase) + (voff)[_i]), (LAS unsigned*)(lds + (bufoff) + ldsw + _i * 8192), 16, 0, 0); } while (0)
; #define PG8_LDA(dst, b, h) do { _Pragma("unroll") for (int m = 0; m < 4; ++m) _Pragma("unroll") for (int k = 0; k < 2; ++k) dst[m][k] = *(const LAS bf16x8*)(lds + PG8_SA(b, h) + aoff + m * 2048 + k * 1024); } while (0)
; #define PG8_LDB(dst, b, h) do { _Pragma("unroll") for (int n = 0; n < 2; ++n) _Pragma("unroll") for (int k = 0; k < 2; ++k) dst[n][k] = *(const LAS bf16x8*)(lds + PG8_SB(b, h) + boff + n * 2048 + k * 1024); } while (0)
; #define PG8_MMA(ai, bj, At, Bt) do { __builtin_amdgcn_s_setprio(1); _Pragma("unroll") for (int m = 0; m < 4; ++m) _Pragma("unroll") for (int n = 0; n < 2; ++n) _Pragma("unroll") for (int k = 0; k < 2; ++k) \
;         acc[ai][bj][m][n] = __builtin_amdgcn_mfma_f32_16x16x32_bf16(Bt[n][k], At[m][k], acc[ai][bj][m][n], 0, 0, 0); __builtin_amdgcn_s_setprio(0); } while (0)
; #define PG8_WAIT_L(n) asm volatile("s_waitcnt lgkmcnt(" #n ")" ::: "memory")
; #define PG8_BAR __builtin_amdgcn_s_barrier()
; #define PG8_SCHED __builtin_amdgcn_sched_barrier(0)
;     ...
;             const char* a1 = cA + (size_t)(t + 1) * kstep;
;             const char* a2 = last ? nA : cA + (size_t)(t + 2) * kstep; const char* b2 = last ? nB : cB + (size_t)(t + 2) * kstep;
;             const char* a3 = a2 + kstep; const char* b3 = b2 + kstep;
;             PG8_LDB(B0, 0, 0); PG8_SCHED; PG8_LDA(At, 0, 0); PG8_STAGE(PG8_SA(1, 1), a1 + hstep, voffA);
;             PG8_WAIT_L(8); PG8_BAR; PG8_WAIT_L(0); PG8_MMA(0, 0, At, B0); PG8_BAR; PG8_SCHED;
;             PG8_LDB(B1, 0, 1); PG8_STAGE(PG8_SB(0, 0), b2, voffB);
;             PG8_BAR; PG8_WAIT_L(0); PG8_MMA(0, 1, At, B1); PG8_BAR;
;             PG8_LDA(At, 0, 1); PG8_STAGE(PG8_SA(0, 0), a2, voffA);
;             PG8_BAR; PG8_WAIT_L(0); PG8_MMA(1, 0, At, B0); PG8_BAR; PG8_SCHED;
.LBB0_1275:
	s_add_u32 s2, s6, 0xe767c080
	s_addc_u32 s3, s7, -1
	s_cmp_lg_u32 s23, 28
	s_cselect_b32 s8, s2, 0
	s_cselect_b32 s9, s3, 0
	s_add_u32 s2, s4, s8
	s_addc_u32 s3, s5, s9
	s_add_i32 s24, 0, 0x10000
	v_add_u32_e32 v152, s24, v138
	ds_read_b128 v[140:143], v152
	ds_read_b128 v[144:147], v152 offset:1024
	ds_read_b128 v[148:151], v152 offset:2048
	ds_read_b128 v[152:155], v152 offset:3072
	s_add_u32 s8, s0, s8
	s_addc_u32 s9, s1, s9
	v_lshl_add_u64 v[188:189], v[132:133], 0, s[6:7]
	s_add_i32 m0, s15, 0xc000
	ds_read_b128 v[156:159], v139
	ds_read_b128 v[160:163], v139 offset:1024
	ds_read_b128 v[164:167], v139 offset:2048
	ds_read_b128 v[168:171], v139 offset:3072
	ds_read_b128 v[172:175], v139 offset:4096
	ds_read_b128 v[176:179], v139 offset:5120
	ds_read_b128 v[180:183], v139 offset:6144
	ds_read_b128 v[184:187], v139 offset:7168
	global_load_lds_dwordx4 v[188:189], off
	v_lshl_add_u64 v[188:189], v[134:135], 0, s[6:7]
	s_add_i32 m0, s15, 0xe000
	s_nop 0
	global_load_lds_dwordx4 v[188:189], off
	s_waitcnt lgkmcnt(8)
	s_barrier
	s_waitcnt lgkmcnt(0)
	v_mfma_f32_16x16x32_bf16 v[126:129], v[140:143], v[156:159], v[126:129]
	v_mfma_f32_16x16x32_bf16 v[122:125], v[148:151], v[156:159], v[122:125]
	v_mfma_f32_16x16x32_bf16 v[110:113], v[140:143], v[164:167], v[110:113]
	v_mfma_f32_16x16x32_bf16 v[106:109], v[148:151], v[164:167], v[106:109]
	v_mfma_f32_16x16x32_bf16 v[94:97], v[140:143], v[172:175], v[94:97]
	v_mfma_f32_16x16x32_bf16 v[90:93], v[148:151], v[172:175], v[90:93]
	v_mfma_f32_16x16x32_bf16 v[78:81], v[140:143], v[180:183], v[78:81]
	v_mfma_f32_16x16x32_bf16 v[74:77], v[148:151], v[180:183], v[74:77]
	v_mfma_f32_16x16x32_bf16 v[126:129], v[144:147], v[160:163], v[126:129]
	v_mfma_f32_16x16x32_bf16 v[122:125], v[152:155], v[160:163], v[122:125]
	v_mfma_f32_16x16x32_bf16 v[110:113], v[144:147], v[168:171], v[110:113]
	v_mfma_f32_16x16x32_bf16 v[106:109], v[152:155], v[168:171], v[106:109]
	v_mfma_f32_16x16x32_bf16 v[94:97], v[144:147], v[176:179], v[94:97]
	v_mfma_f32_16x16x32_bf16 v[90:93], v[152:155], v[176:179], v[90:93]
	v_mfma_f32_16x16x32_bf16 v[78:81], v[144:147], v[184:187], v[78:81]
	v_mfma_f32_16x16x32_bf16 v[74:77], v[152:155], v[184:187], v[74:77]
	s_barrier
	s_add_i32 s26, 0, 0x14000
	s_add_i32 s24, s24, s14
	v_add_u32_e32 v208, s26, v138
	v_lshl_add_u64 v[224:225], s[8:9], 0, v[64:65]
	s_mov_b32 m0, s24
	ds_read_b128 v[188:191], v208
	ds_read_b128 v[192:195], v208 offset:1024
	ds_read_b128 v[196:199], v208 offset:2048
	ds_read_b128 v[220:223], v208 offset:3072
	global_load_lds_dwordx4 v[224:225], off
	v_lshl_add_u64 v[226:227], s[8:9], 0, v[130:131]
	s_add_i32 m0, s24, 0x2000
	s_nop 0
	global_load_lds_dwordx4 v[226:227], off
	s_barrier
	s_waitcnt lgkmcnt(0)
	v_mfma_f32_16x16x32_bf16 v[118:121], v[188:191], v[156:159], v[118:121]
	v_mfma_f32_16x16x32_bf16 v[114:117], v[196:199], v[156:159], v[114:117]
	v_mfma_f32_16x16x32_bf16 v[102:105], v[188:191], v[164:167], v[102:105]
	v_mfma_f32_16x16x32_bf16 v[98:101], v[196:199], v[164:167], v[98:101]
	v_mfma_f32_16x16x32_bf16 v[86:89], v[188:191], v[172:175], v[86:89]
	v_mfma_f32_16x16x32_bf16 v[82:85], v[196:199], v[172:175], v[82:85]
	v_mfma_f32_16x16x32_bf16 v[70:73], v[188:191], v[180:183], v[70:73]
	v_mfma_f32_16x16x32_bf16 v[66:69], v[196:199], v[180:183], v[66:69]
	v_mfma_f32_16x16x32_bf16 v[118:121], v[192:195], v[160:163], v[118:121]
	v_mfma_f32_16x16x32_bf16 v[114:117], v[220:223], v[160:163], v[114:117]
	v_mfma_f32_16x16x32_bf16 v[102:105], v[192:195], v[168:171], v[102:105]
	v_mfma_f32_16x16x32_bf16 v[98:101], v[220:223], v[168:171], v[98:101]
	v_mfma_f32_16x16x32_bf16 v[86:89], v[192:195], v[176:179], v[86:89]
	v_mfma_f32_16x16x32_bf16 v[82:85], v[220:223], v[176:179], v[82:85]
	v_mfma_f32_16x16x32_bf16 v[70:73], v[192:195], v[184:187], v[70:73]
	v_mfma_f32_16x16x32_bf16 v[66:69], v[220:223], v[184:187], v[66:69]
	s_mov_b32 m0, s15
	v_lshl_add_u64 v[228:229], s[2:3], 0, v[64:65]
	s_barrier
	ds_read_b128 v[156:159], v139 offset:16384
	ds_read_b128 v[160:163], v139 offset:17408
	ds_read_b128 v[164:167], v139 offset:18432
	ds_read_b128 v[168:171], v139 offset:19456
	ds_read_b128 v[172:175], v139 offset:20480
	ds_read_b128 v[176:179], v139 offset:21504
	ds_read_b128 v[180:183], v139 offset:22528
	ds_read_b128 v[184:187], v139 offset:23552
	global_load_lds_dwordx4 v[228:229], off
	v_lshl_add_u64 v[230:231], s[2:3], 0, v[130:131]
	s_mov_b32 m0, s18
	s_nop 0
	global_load_lds_dwordx4 v[230:231], off
	s_barrier
	s_waitcnt lgkmcnt(0)
	v_mfma_f32_16x16x32_bf16 v[60:63], v[140:143], v[156:159], v[60:63]
	v_mfma_f32_16x16x32_bf16 v[56:59], v[148:151], v[156:159], v[56:59]
	v_mfma_f32_16x16x32_bf16 v[44:47], v[140:143], v[164:167], v[44:47]
	v_mfma_f32_16x16x32_bf16 v[40:43], v[148:151], v[164:167], v[40:43]
	v_mfma_f32_16x16x32_bf16 v[28:31], v[140:143], v[172:175], v[28:31]
	v_mfma_f32_16x16x32_bf16 v[24:27], v[148:151], v[172:175], v[24:27]
	v_mfma_f32_16x16x32_bf16 v[12:15], v[140:143], v[180:183], v[12:15]
	v_mfma_f32_16x16x32_bf16 v[8:11], v[148:151], v[180:183], v[8:11]
	v_mfma_f32_16x16x32_bf16 v[60:63], v[144:147], v[160:163], v[60:63]
	v_mfma_f32_16x16x32_bf16 v[56:59], v[152:155], v[160:163], v[56:59]
	v_mfma_f32_16x16x32_bf16 v[44:47], v[144:147], v[168:171], v[44:47]
	v_mfma_f32_16x16x32_bf16 v[40:43], v[152:155], v[168:171], v[40:43]
	v_mfma_f32_16x16x32_bf16 v[28:31], v[144:147], v[176:179], v[28:31]
	v_mfma_f32_16x16x32_bf16 v[24:27], v[152:155], v[176:179], v[24:27]
	v_mfma_f32_16x16x32_bf16 v[12:15], v[144:147], v[184:187], v[12:15]
	v_mfma_f32_16x16x32_bf16 v[8:11], v[152:155], v[184:187], v[8:11]
	s_barrier
; #define PG8_STAGE(bufoff, gbase, voff) do { _Pragma("unroll") for (int _i = 0; _i < 2; ++_i) \
;         __builtin_amdgcn_global_load_lds((const unsigned*)((const char*)(gbase) + (voff)[_i]), (LAS unsigned*)(lds + (bufoff) + ldsw + _i * 8192), 16, 0, 0); } while (0)
; #define PG8_LDA(dst, b, h) do { _Pragma("unroll") for (int m = 0; m < 4; ++m) _Pragma("unroll") for (int k = 0; k < 2; ++k) dst[m][k] = *(const LAS bf16x8*)(lds + PG8_SA(b, h) + aoff + m * 2048 + k * 1024); } while (0)
; #define PG8_LDB(dst, b, h) do { _Pragma("unroll") for (int n = 0; n < 2; ++n) _Pragma("unroll") for (int k = 0; k < 2; ++k) dst[n][k] = *(const LAS bf16x8*)(lds + PG8_SB(b, h) + boff + n * 2048 + k * 1024); } while (0)
; #define PG8_MMA(ai, bj, At, Bt) do { __builtin_amdgcn_s_setprio(1); _Pragma("unroll") for (int m = 0; m < 4; ++m) _Pragma("unroll") for (int n = 0; n < 2; ++n) _Pragma("unroll") for (int k = 0; k < 2; ++k) \
;         acc[ai][bj][m][n] = __builtin_amdgcn_mfma_f32_16x16x32_bf16(Bt[n][k], At[m][k], acc[ai][bj][m][n], 0, 0, 0); __builtin_amdgcn_s_setprio(0); } while (0)
; #define PG8_WAIT_V(n) asm volatile("s_waitcnt vmcnt(" #n ")" ::: "memory")
; #define PG8_WAIT_L(n) asm volatile("s_waitcnt lgkmcnt(" #n ")" ::: "memory")
; #define PG8_BAR __builtin_amdgcn_s_barrier()
; #define PG8_SCHED __builtin_amdgcn_sched_barrier(0)
;     ...
;             PG8_STAGE(PG8_SB(0, 1), b2 + hstep, voffB);
;             PG8_WAIT_V(6); PG8_BAR; PG8_MMA(1, 1, At, B1); PG8_BAR;
;             PG8_LDB(B0, 1, 0); PG8_SCHED; PG8_LDA(At, 1, 0); PG8_STAGE(PG8_SA(0, 1), a2 + hstep, voffA);
;             PG8_WAIT_L(8); PG8_BAR; PG8_WAIT_L(0); PG8_MMA(0, 0, At, B0); PG8_BAR; PG8_SCHED;
;             PG8_LDB(B1, 1, 1); PG8_STAGE(PG8_SB(1, 0), b3, voffB);
;             PG8_BAR; PG8_WAIT_L(0); PG8_MMA(0, 1, At, B1); PG8_BAR;
;             PG8_LDA(At, 1, 1); PG8_STAGE(PG8_SA(1, 0), a3, voffA);
;             PG8_BAR; PG8_WAIT_L(0); PG8_MMA(1, 0, At, B0); PG8_BAR; PG8_SCHED;
	s_add_u32 s24, s8, 0x84000
	s_addc_u32 s25, s9, 0
	s_add_i32 s26, s26, s14
	v_lshl_add_u64 v[140:141], s[24:25], 0, v[64:65]
	s_mov_b32 m0, s26
	s_nop 0
	global_load_lds_dwordx4 v[140:141], off
	v_lshl_add_u64 v[140:141], s[24:25], 0, v[130:131]
	s_add_i32 m0, s26, 0x2000
	s_nop 0
	global_load_lds_dwordx4 v[140:141], off
	s_waitcnt vmcnt(6)
	s_barrier
	v_mfma_f32_16x16x32_bf16 v[52:55], v[188:191], v[156:159], v[52:55]
	v_mfma_f32_16x16x32_bf16 v[48:51], v[196:199], v[156:159], v[48:51]
	v_mfma_f32_16x16x32_bf16 v[36:39], v[188:191], v[164:167], v[36:39]
	v_mfma_f32_16x16x32_bf16 v[32:35], v[196:199], v[164:167], v[32:35]
	v_mfma_f32_16x16x32_bf16 v[20:23], v[188:191], v[172:175], v[20:23]
	v_mfma_f32_16x16x32_bf16 v[16:19], v[196:199], v[172:175], v[16:19]
	v_mfma_f32_16x16x32_bf16 v[4:7], v[188:191], v[180:183], v[4:7]
	v_mfma_f32_16x16x32_bf16 v[0:3], v[196:199], v[180:183], v[0:3]
	v_mfma_f32_16x16x32_bf16 v[52:55], v[192:195], v[160:163], v[52:55]
	v_mfma_f32_16x16x32_bf16 v[48:51], v[220:223], v[160:163], v[48:51]
	v_mfma_f32_16x16x32_bf16 v[36:39], v[192:195], v[168:171], v[36:39]
	v_mfma_f32_16x16x32_bf16 v[32:35], v[220:223], v[168:171], v[32:35]
	v_mfma_f32_16x16x32_bf16 v[20:23], v[192:195], v[176:179], v[20:23]
	v_mfma_f32_16x16x32_bf16 v[16:19], v[220:223], v[176:179], v[16:19]
	v_mfma_f32_16x16x32_bf16 v[4:7], v[192:195], v[184:187], v[4:7]
	v_mfma_f32_16x16x32_bf16 v[0:3], v[220:223], v[184:187], v[0:3]
	s_add_i32 s24, 0, 0x18000
	v_add_u32_e32 v152, s24, v138
	s_barrier
	ds_read_b128 v[140:143], v152
	ds_read_b128 v[144:147], v152 offset:1024
	ds_read_b128 v[148:151], v152 offset:2048
	ds_read_b128 v[152:155], v152 offset:3072
	s_add_u32 s2, s2, 0x84000
	s_addc_u32 s3, s3, 0
	s_mov_b32 m0, s19
	v_lshl_add_u64 v[188:189], s[2:3], 0, v[64:65]
	ds_read_b128 v[156:159], v139 offset:32768
	ds_read_b128 v[160:163], v139 offset:33792
	ds_read_b128 v[164:167], v139 offset:34816
	ds_read_b128 v[168:171], v139 offset:35840
	ds_read_b128 v[172:175], v139 offset:36864
	ds_read_b128 v[176:179], v139 offset:37888
	ds_read_b128 v[180:183], v139 offset:38912
	ds_read_b128 v[184:187], v139 offset:39936
	global_load_lds_dwordx4 v[188:189], off
	v_lshl_add_u64 v[188:189], s[2:3], 0, v[130:131]
	s_mov_b32 m0, s20
	s_nop 0
	global_load_lds_dwordx4 v[188:189], off
	s_waitcnt lgkmcnt(8)
	s_barrier
	s_waitcnt lgkmcnt(0)
	v_mfma_f32_16x16x32_bf16 v[126:129], v[140:143], v[156:159], v[126:129]
	v_mfma_f32_16x16x32_bf16 v[122:125], v[148:151], v[156:159], v[122:125]
	v_mfma_f32_16x16x32_bf16 v[110:113], v[140:143], v[164:167], v[110:113]
	v_mfma_f32_16x16x32_bf16 v[106:109], v[148:151], v[164:167], v[106:109]
	v_mfma_f32_16x16x32_bf16 v[94:97], v[140:143], v[172:175], v[94:97]
	v_mfma_f32_16x16x32_bf16 v[90:93], v[148:151], v[172:175], v[90:93]
	v_mfma_f32_16x16x32_bf16 v[78:81], v[140:143], v[180:183], v[78:81]
	v_mfma_f32_16x16x32_bf16 v[74:77], v[148:151], v[180:183], v[74:77]
	v_mfma_f32_16x16x32_bf16 v[126:129], v[144:147], v[160:163], v[126:129]
	v_mfma_f32_16x16x32_bf16 v[122:125], v[152:155], v[160:163], v[122:125]
	v_mfma_f32_16x16x32_bf16 v[110:113], v[144:147], v[168:171], v[110:113]
	v_mfma_f32_16x16x32_bf16 v[106:109], v[152:155], v[168:171], v[106:109]
	v_mfma_f32_16x16x32_bf16 v[94:97], v[144:147], v[176:179], v[94:97]
	v_mfma_f32_16x16x32_bf16 v[90:93], v[152:155], v[176:179], v[90:93]
	v_mfma_f32_16x16x32_bf16 v[78:81], v[144:147], v[184:187], v[78:81]
	v_mfma_f32_16x16x32_bf16 v[74:77], v[152:155], v[184:187], v[74:77]
	s_barrier
	s_add_i32 s25, 0, 0x1c000
	s_add_i32 s2, s24, s14
	v_add_u32_e32 v208, s25, v138
	v_lshl_add_u64 v[224:225], v[224:225], 0, s[16:17]
	s_mov_b32 m0, s2
	ds_read_b128 v[188:191], v208
	ds_read_b128 v[192:195], v208 offset:1024
	ds_read_b128 v[196:199], v208 offset:2048
	ds_read_b128 v[220:223], v208 offset:3072
	global_load_lds_dwordx4 v[224:225], off
	v_lshl_add_u64 v[224:225], v[226:227], 0, s[16:17]
	s_add_i32 m0, s2, 0x2000
	s_nop 0
	global_load_lds_dwordx4 v[224:225], off
	s_barrier
	s_waitcnt lgkmcnt(0)
	v_mfma_f32_16x16x32_bf16 v[118:121], v[188:191], v[156:159], v[118:121]
	v_mfma_f32_16x16x32_bf16 v[114:117], v[196:199], v[156:159], v[114:117]
	v_mfma_f32_16x16x32_bf16 v[102:105], v[188:191], v[164:167], v[102:105]
	v_mfma_f32_16x16x32_bf16 v[98:101], v[196:199], v[164:167], v[98:101]
	v_mfma_f32_16x16x32_bf16 v[86:89], v[188:191], v[172:175], v[86:89]
	v_mfma_f32_16x16x32_bf16 v[82:85], v[196:199], v[172:175], v[82:85]
	v_mfma_f32_16x16x32_bf16 v[70:73], v[188:191], v[180:183], v[70:73]
	v_mfma_f32_16x16x32_bf16 v[66:69], v[196:199], v[180:183], v[66:69]
	v_mfma_f32_16x16x32_bf16 v[118:121], v[192:195], v[160:163], v[118:121]
	v_mfma_f32_16x16x32_bf16 v[114:117], v[220:223], v[160:163], v[114:117]
	v_mfma_f32_16x16x32_bf16 v[102:105], v[192:195], v[168:171], v[102:105]
	v_mfma_f32_16x16x32_bf16 v[98:101], v[220:223], v[168:171], v[98:101]
	v_mfma_f32_16x16x32_bf16 v[86:89], v[192:195], v[176:179], v[86:89]
	v_mfma_f32_16x16x32_bf16 v[82:85], v[220:223], v[176:179], v[82:85]
	v_mfma_f32_16x16x32_bf16 v[70:73], v[192:195], v[184:187], v[70:73]
	v_mfma_f32_16x16x32_bf16 v[66:69], v[220:223], v[184:187], v[66:69]
	s_mov_b32 m0, s21
	v_lshl_add_u64 v[224:225], v[228:229], 0, s[16:17]
	s_barrier
; #define PG8_STAGE(bufoff, gbase, voff) do { _Pragma("unroll") for (int _i = 0; _i < 2; ++_i) \
;         __builtin_amdgcn_global_load_lds((const unsigned*)((const char*)(gbase) + (voff)[_i]), (LAS unsigned*)(lds + (bufoff) + ldsw + _i * 8192), 16, 0, 0); } while (0)
; #define PG8_MMA(ai, bj, At, Bt) do { __builtin_amdgcn_s_setprio(1); _Pragma("unroll") for (int m = 0; m < 4; ++m) _Pragma("unroll") for (int n = 0; n < 2; ++n) _Pragma("unroll") for (int k = 0; k < 2; ++k) \
;         acc[ai][bj][m][n] = __builtin_amdgcn_mfma_f32_16x16x32_bf16(Bt[n][k], At[m][k], acc[ai][bj][m][n], 0, 0, 0); __builtin_amdgcn_s_setprio(0); } while (0)
; #define PG8_WAIT_V(n) asm volatile("s_waitcnt vmcnt(" #n ")" ::: "memory")
; #define PG8_WAIT_L(n) asm volatile("s_waitcnt lgkmcnt(" #n ")" ::: "memory")
; #define PG8_BAR __builtin_amdgcn_s_barrier()
; #define PG8_SCHED __builtin_amdgcn_sched_barrier(0)
; __device__ __forceinline__ f32x4 gelu4(const f32x4 x) {
;     const f32x4 t = x * x, a = x * (t * -0.10294324f + -2.3022082f);
;     f32x4 e; e[0] = __builtin_amdgcn_exp2f(a[0]); e[1] = __builtin_amdgcn_exp2f(a[1]); e[2] = __builtin_amdgcn_exp2f(a[2]); e[3] = __builtin_amdgcn_exp2f(a[3]);
;     const f32x4 d = e + 1.0f;
;     f32x4 r; r[0] = __builtin_amdgcn_rcpf(d[0]); r[1] = __builtin_amdgcn_rcpf(d[1]); r[2] = __builtin_amdgcn_rcpf(d[2]); r[3] = __builtin_amdgcn_rcpf(d[3]);
;     return x * r;
;     ...
;             PG8_BAR; PG8_WAIT_L(0); PG8_MMA(1, 0, At, B0); PG8_BAR; PG8_SCHED;
;             PG8_STAGE(PG8_SB(1, 1), b3 + hstep, voffB);
;             PG8_WAIT_V(6); PG8_BAR; PG8_MMA(1, 1, At, B1); PG8_BAR;
;         }
	ds_read_b128 v[156:159], v139 offset:49152
	ds_read_b128 v[160:163], v139 offset:50176
	ds_read_b128 v[164:167], v139 offset:51200
	ds_read_b128 v[168:171], v139 offset:52224
	ds_read_b128 v[172:175], v139 offset:53248
	ds_read_b128 v[176:179], v139 offset:54272
	ds_read_b128 v[180:183], v139 offset:55296
	ds_read_b128 v[184:187], v139 offset:56320
	global_load_lds_dwordx4 v[224:225], off
	v_lshl_add_u64 v[224:225], v[230:231], 0, s[16:17]
	s_mov_b32 m0, s22
	s_nop 0
	global_load_lds_dwordx4 v[224:225], off
	s_barrier
	s_waitcnt lgkmcnt(0)
	v_mfma_f32_16x16x32_bf16 v[60:63], v[140:143], v[156:159], v[60:63]
	v_mfma_f32_16x16x32_bf16 v[56:59], v[148:151], v[156:159], v[56:59]
	v_mfma_f32_16x16x32_bf16 v[44:47], v[140:143], v[164:167], v[44:47]
	v_mfma_f32_16x16x32_bf16 v[40:43], v[148:151], v[164:167], v[40:43]
	v_mfma_f32_16x16x32_bf16 v[28:31], v[140:143], v[172:175], v[28:31]
	v_mfma_f32_16x16x32_bf16 v[24:27], v[148:151], v[172:175], v[24:27]
	v_mfma_f32_16x16x32_bf16 v[12:15], v[140:143], v[180:183], v[12:15]
	v_mfma_f32_16x16x32_bf16 v[8:11], v[148:151], v[180:183], v[8:11]
	v_mfma_f32_16x16x32_bf16 v[60:63], v[144:147], v[160:163], v[60:63]
	v_mfma_f32_16x16x32_bf16 v[56:59], v[152:155], v[160:163], v[56:59]
	v_mfma_f32_16x16x32_bf16 v[44:47], v[144:147], v[168:171], v[44:47]
	v_mfma_f32_16x16x32_bf16 v[40:43], v[152:155], v[168:171], v[40:43]
	v_mfma_f32_16x16x32_bf16 v[28:31], v[144:147], v[176:179], v[28:31]
	v_mfma_f32_16x16x32_bf16 v[24:27], v[152:155], v[176:179], v[24:27]
	v_mfma_f32_16x16x32_bf16 v[12:15], v[144:147], v[184:187], v[12:15]
	v_mfma_f32_16x16x32_bf16 v[8:11], v[152:155], v[184:187], v[8:11]
	s_barrier
	s_add_u32 s2, s8, 0x84080
	s_addc_u32 s3, s9, 0
	s_add_i32 s8, s25, s14
	v_lshl_add_u64 v[140:141], s[2:3], 0, v[64:65]
	s_mov_b32 m0, s8
	s_nop 0
	global_load_lds_dwordx4 v[140:141], off
	v_lshl_add_u64 v[140:141], s[2:3], 0, v[130:131]
	s_add_i32 m0, s8, 0x2000
	s_nop 0
	global_load_lds_dwordx4 v[140:141], off
	s_waitcnt vmcnt(6)
	s_barrier
	v_mfma_f32_16x16x32_bf16 v[52:55], v[188:191], v[156:159], v[52:55]
	v_mfma_f32_16x16x32_bf16 v[48:51], v[196:199], v[156:159], v[48:51]
	v_mfma_f32_16x16x32_bf16 v[36:39], v[188:191], v[164:167], v[36:39]
	v_mfma_f32_16x16x32_bf16 v[32:35], v[196:199], v[164:167], v[32:35]
	v_mfma_f32_16x16x32_bf16 v[20:23], v[188:191], v[172:175], v[20:23]
	v_mfma_f32_16x16x32_bf16 v[16:19], v[196:199], v[172:175], v[16:19]
	v_mfma_f32_16x16x32_bf16 v[4:7], v[188:191], v[180:183], v[4:7]
	v_mfma_f32_16x16x32_bf16 v[0:3], v[196:199], v[180:183], v[0:3]
	v_mfma_f32_16x16x32_bf16 v[52:55], v[192:195], v[160:163], v[52:55]
	v_mfma_f32_16x16x32_bf16 v[48:51], v[220:223], v[160:163], v[48:51]
	v_mfma_f32_16x16x32_bf16 v[36:39], v[192:195], v[168:171], v[36:39]
	v_mfma_f32_16x16x32_bf16 v[32:35], v[220:223], v[168:171], v[32:35]
	v_mfma_f32_16x16x32_bf16 v[20:23], v[192:195], v[176:179], v[20:23]
	v_mfma_f32_16x16x32_bf16 v[16:19], v[220:223], v[176:179], v[16:19]
	v_mfma_f32_16x16x32_bf16 v[4:7], v[192:195], v[184:187], v[4:7]
	v_mfma_f32_16x16x32_bf16 v[0:3], v[220:223], v[184:187], v[0:3]
	s_add_i32 s23, s23, 2
	s_add_u32 s6, s6, 0x100
	s_addc_u32 s7, s7, 0
	s_cmp_gt_u32 s23, 29
	s_barrier
	s_cbranch_scc0 .LBB0_1275
	s_add_i32 s0, s11, -2
	s_cmp_lt_u32 s0, 8
	s_cselect_b64 s[2:3], -1, 0
	s_cmp_gt_u32 s0, 7
	s_cbranch_scc1 .LBB0_1278
	s_mov_b32 s0, 0xc0135761
	v_pk_mul_f32 v[130:131], v[128:129], v[128:129]
	v_pk_mul_f32 v[132:133], v[126:127], v[126:127]
	v_mov_b64_e32 v[134:135], s[0:1]
	s_mov_b32 s0, 0xbdd2d3e8
	v_pk_fma_f32 v[130:131], v[130:131], s[0:1], v[134:135] op_sel_hi:[1,0,0]
	v_pk_fma_f32 v[132:133], v[132:133], s[0:1], v[134:135] op_sel_hi:[1,0,0]
	v_pk_mul_f32 v[130:131], v[128:129], v[130:131]
	v_pk_mul_f32 v[132:133], v[126:127], v[132:133]
	v_exp_f32_e32 v130, v130
	v_exp_f32_e32 v132, v132
	v_exp_f32_e32 v131, v131
	v_exp_f32_e32 v133, v133
	v_pk_add_f32 v[130:131], v[130:131], 1.0 op_sel_hi:[1,0]
	v_pk_add_f32 v[132:133], v[132:133], 1.0 op_sel_hi:[1,0]
	v_rcp_f32_e32 v130, v130
	v_rcp_f32_e32 v132, v132
	v_rcp_f32_e32 v131, v131
	v_rcp_f32_e32 v133, v133
	v_pk_mul_f32 v[128:129], v[128:129], v[130:131]
	v_pk_mul_f32 v[126:127], v[126:127], v[132:133]

; #define PG8_STAGE(bufoff, gbase, voff) do { _Pragma("unroll") for (int _i = 0; _i < 2; ++_i) \
;         __builtin_amdgcn_global_load_lds((const unsigned*)((const char*)(gbase) + (voff)[_i]), (LAS unsigned*)(lds + (bufoff) + ldsw + _i * 8192), 16, 0, 0); } while (0)
; #define PG8_LDA(dst, b, h) do { _Pragma("unroll") for (int m = 0; m < 4; ++m) _Pragma("unroll") for (int k = 0; k < 2; ++k) dst[m][k] = *(const LAS bf16x8*)(lds + PG8_SA(b, h) + aoff + m * 2048 + k * 1024); } while (0)
; #define PG8_LDB(dst, b, h) do { _Pragma("unroll") for (int n = 0; n < 2; ++n) _Pragma("unroll") for (int k = 0; k < 2; ++k) dst[n][k] = *(const LAS bf16x8*)(lds + PG8_SB(b, h) + boff + n * 2048 + k * 1024); } while (0)
; #define PG8_MMA(ai, bj, At, Bt) do { __builtin_amdgcn_s_setprio(1); _Pragma("unroll") for (int m = 0; m < 4; ++m) _Pragma("unroll") for (int n = 0; n < 2; ++n) _Pragma("unroll") for (int k = 0; k < 2; ++k) \
;         acc[ai][bj][m][n] = __builtin_amdgcn_mfma_f32_16x16x32_bf16(Bt[n][k], At[m][k], acc[ai][bj][m][n], 0, 0, 0); __builtin_amdgcn_s_setprio(0); } while (0)
; #define PG8_WAIT_L(n) asm volatile("s_waitcnt lgkmcnt(" #n ")" ::: "memory")
; #define PG8_BAR __builtin_amdgcn_s_barrier()
; #define PG8_SCHED __builtin_amdgcn_sched_barrier(0)
;     ...
;             const char* a1 = cA + (size_t)(t + 1) * kstep;
;             const char* a2 = last ? nA : cA + (size_t)(t + 2) * kstep; const char* b2 = last ? nB : cB + (size_t)(t + 2) * kstep;
;             const char* a3 = a2 + kstep; const char* b3 = b2 + kstep;
;             PG8_LDB(B0, 0, 0); PG8_SCHED; PG8_LDA(At, 0, 0); PG8_STAGE(PG8_SA(1, 1), a1 + hstep, voffA);
;             PG8_WAIT_L(8); PG8_BAR; PG8_WAIT_L(0); PG8_MMA(0, 0, At, B0); PG8_BAR; PG8_SCHED;
;             PG8_LDB(B1, 0, 1); PG8_STAGE(PG8_SB(0, 0), b2, voffB);
;             PG8_BAR; PG8_WAIT_L(0); PG8_MMA(0, 1, At, B1); PG8_BAR;
;             PG8_LDA(At, 0, 1); PG8_STAGE(PG8_SA(0, 0), a2, voffA);
;             PG8_BAR; PG8_WAIT_L(0); PG8_MMA(1, 0, At, B0); PG8_BAR; PG8_SCHED;
.LBB0_1441:
	s_add_u32 s4, s0, 0x100
	s_addc_u32 s5, s1, 0
	s_add_i32 s43, 0, 0x10000
	v_add_u32_e32 v140, s43, v143
	ds_read_b128 v[136:139], v140
	ds_read_b128 v[146:149], v140 offset:1024
	ds_read_b128 v[150:153], v140 offset:2048
	ds_read_b128 v[154:157], v140 offset:3072
	s_cmp_eq_u32 s42, 28
	s_cselect_b32 s3, s21, s5
	s_cselect_b32 s2, s20, s4
	s_cselect_b32 s9, s23, s41
	s_cselect_b32 s8, s22, s40
	v_lshl_add_u64 v[140:141], s[0:1], 0, v[132:133]
	s_add_i32 m0, s12, 0xc000
	ds_read_b128 v[158:161], v145
	ds_read_b128 v[162:165], v145 offset:1024
	ds_read_b128 v[166:169], v145 offset:2048
	ds_read_b128 v[170:173], v145 offset:3072
	ds_read_b128 v[174:177], v145 offset:4096
	ds_read_b128 v[178:181], v145 offset:5120
	ds_read_b128 v[182:185], v145 offset:6144
	ds_read_b128 v[186:189], v145 offset:7168
	global_load_lds_dwordx4 v[140:141], off
	v_lshl_add_u64 v[140:141], s[0:1], 0, v[134:135]
	s_add_i32 m0, s12, 0xe000
	s_nop 0
	global_load_lds_dwordx4 v[140:141], off
	s_waitcnt lgkmcnt(8)
	s_barrier
	s_waitcnt lgkmcnt(0)
	v_mfma_f32_16x16x32_bf16 v[126:129], v[136:139], v[158:161], v[126:129]
	v_mfma_f32_16x16x32_bf16 v[122:125], v[150:153], v[158:161], v[122:125]
	v_mfma_f32_16x16x32_bf16 v[110:113], v[136:139], v[166:169], v[110:113]
	v_mfma_f32_16x16x32_bf16 v[106:109], v[150:153], v[166:169], v[106:109]
	v_mfma_f32_16x16x32_bf16 v[94:97], v[136:139], v[174:177], v[94:97]
	v_mfma_f32_16x16x32_bf16 v[90:93], v[150:153], v[174:177], v[90:93]
	v_mfma_f32_16x16x32_bf16 v[78:81], v[136:139], v[182:185], v[78:81]
	v_mfma_f32_16x16x32_bf16 v[74:77], v[150:153], v[182:185], v[74:77]
	v_mfma_f32_16x16x32_bf16 v[126:129], v[146:149], v[162:165], v[126:129]
	v_mfma_f32_16x16x32_bf16 v[122:125], v[154:157], v[162:165], v[122:125]
	v_mfma_f32_16x16x32_bf16 v[110:113], v[146:149], v[170:173], v[110:113]
	v_mfma_f32_16x16x32_bf16 v[106:109], v[154:157], v[170:173], v[106:109]
	v_mfma_f32_16x16x32_bf16 v[94:97], v[146:149], v[178:181], v[94:97]
	v_mfma_f32_16x16x32_bf16 v[90:93], v[154:157], v[178:181], v[90:93]
	v_mfma_f32_16x16x32_bf16 v[78:81], v[146:149], v[186:189], v[78:81]
	v_mfma_f32_16x16x32_bf16 v[74:77], v[154:157], v[186:189], v[74:77]
	s_barrier
	s_add_i32 s44, 0, 0x14000
	v_add_u32_e32 v140, s44, v143
	s_add_i32 s0, s43, s11
	ds_read_b128 v[190:193], v140
	ds_read_b128 v[194:197], v140 offset:1024
	ds_read_b128 v[220:223], v140 offset:2048
	ds_read_b128 v[224:227], v140 offset:3072
	v_lshl_add_u64 v[140:141], s[8:9], 0, v[64:65]
	s_mov_b32 m0, s0
	v_lshl_add_u64 v[198:199], s[8:9], 0, v[130:131]
	global_load_lds_dwordx4 v[140:141], off
	s_add_i32 m0, s0, 0x2000
	s_nop 0
	global_load_lds_dwordx4 v[198:199], off
	s_barrier
	s_waitcnt lgkmcnt(0)
	v_mfma_f32_16x16x32_bf16 v[118:121], v[190:193], v[158:161], v[118:121]
	v_mfma_f32_16x16x32_bf16 v[114:117], v[220:223], v[158:161], v[114:117]
	v_mfma_f32_16x16x32_bf16 v[102:105], v[190:193], v[166:169], v[102:105]
	v_mfma_f32_16x16x32_bf16 v[98:101], v[220:223], v[166:169], v[98:101]
	v_mfma_f32_16x16x32_bf16 v[86:89], v[190:193], v[174:177], v[86:89]
	v_mfma_f32_16x16x32_bf16 v[82:85], v[220:223], v[174:177], v[82:85]
	v_mfma_f32_16x16x32_bf16 v[70:73], v[190:193], v[182:185], v[70:73]
	v_mfma_f32_16x16x32_bf16 v[66:69], v[220:223], v[182:185], v[66:69]
	v_mfma_f32_16x16x32_bf16 v[118:121], v[194:197], v[162:165], v[118:121]
	v_mfma_f32_16x16x32_bf16 v[114:117], v[224:227], v[162:165], v[114:117]
	v_mfma_f32_16x16x32_bf16 v[102:105], v[194:197], v[170:173], v[102:105]
	v_mfma_f32_16x16x32_bf16 v[98:101], v[224:227], v[170:173], v[98:101]
	v_mfma_f32_16x16x32_bf16 v[86:89], v[194:197], v[178:181], v[86:89]
	v_mfma_f32_16x16x32_bf16 v[82:85], v[224:227], v[178:181], v[82:85]
	v_mfma_f32_16x16x32_bf16 v[70:73], v[194:197], v[186:189], v[70:73]
	v_mfma_f32_16x16x32_bf16 v[66:69], v[224:227], v[186:189], v[66:69]
	s_mov_b32 m0, s12
	v_lshl_add_u64 v[228:229], s[2:3], 0, v[64:65]
	s_barrier
	ds_read_b128 v[158:161], v145 offset:16384
	ds_read_b128 v[162:165], v145 offset:17408
	ds_read_b128 v[166:169], v145 offset:18432
	ds_read_b128 v[170:173], v145 offset:19456
	ds_read_b128 v[174:177], v145 offset:20480
	ds_read_b128 v[178:181], v145 offset:21504
	ds_read_b128 v[182:185], v145 offset:22528
	ds_read_b128 v[186:189], v145 offset:23552
	global_load_lds_dwordx4 v[228:229], off
	v_lshl_add_u64 v[230:231], s[2:3], 0, v[130:131]
	s_mov_b32 m0, s13
	s_nop 0
	global_load_lds_dwordx4 v[230:231], off
	s_barrier
	s_waitcnt lgkmcnt(0)
	v_mfma_f32_16x16x32_bf16 v[60:63], v[136:139], v[158:161], v[60:63]
	v_mfma_f32_16x16x32_bf16 v[56:59], v[150:153], v[158:161], v[56:59]
	v_mfma_f32_16x16x32_bf16 v[44:47], v[136:139], v[166:169], v[44:47]
	v_mfma_f32_16x16x32_bf16 v[40:43], v[150:153], v[166:169], v[40:43]
	v_mfma_f32_16x16x32_bf16 v[28:31], v[136:139], v[174:177], v[28:31]
	v_mfma_f32_16x16x32_bf16 v[24:27], v[150:153], v[174:177], v[24:27]
	v_mfma_f32_16x16x32_bf16 v[12:15], v[136:139], v[182:185], v[12:15]
	v_mfma_f32_16x16x32_bf16 v[8:11], v[150:153], v[182:185], v[8:11]
	v_mfma_f32_16x16x32_bf16 v[60:63], v[146:149], v[162:165], v[60:63]
	v_mfma_f32_16x16x32_bf16 v[56:59], v[154:157], v[162:165], v[56:59]
	v_mfma_f32_16x16x32_bf16 v[44:47], v[146:149], v[170:173], v[44:47]
	v_mfma_f32_16x16x32_bf16 v[40:43], v[154:157], v[170:173], v[40:43]
	v_mfma_f32_16x16x32_bf16 v[28:31], v[146:149], v[178:181], v[28:31]
	v_mfma_f32_16x16x32_bf16 v[24:27], v[154:157], v[178:181], v[24:27]
	v_mfma_f32_16x16x32_bf16 v[12:15], v[146:149], v[186:189], v[12:15]
	v_mfma_f32_16x16x32_bf16 v[8:11], v[154:157], v[186:189], v[8:11]
	s_barrier
; #define PG8_STAGE(bufoff, gbase, voff) do { _Pragma("unroll") for (int _i = 0; _i < 2; ++_i) \
;         __builtin_amdgcn_global_load_lds((const unsigned*)((const char*)(gbase) + (voff)[_i]), (LAS unsigned*)(lds + (bufoff) + ldsw + _i * 8192), 16, 0, 0); } while (0)
; #define PG8_LDA(dst, b, h) do { _Pragma("unroll") for (int m = 0; m < 4; ++m) _Pragma("unroll") for (int k = 0; k < 2; ++k) dst[m][k] = *(const LAS bf16x8*)(lds + PG8_SA(b, h) + aoff + m * 2048 + k * 1024); } while (0)
; #define PG8_LDB(dst, b, h) do { _Pragma("unroll") for (int n = 0; n < 2; ++n) _Pragma("unroll") for (int k = 0; k < 2; ++k) dst[n][k] = *(const LAS bf16x8*)(lds + PG8_SB(b, h) + boff + n * 2048 + k * 1024); } while (0)
; #define PG8_MMA(ai, bj, At, Bt) do { __builtin_amdgcn_s_setprio(1); _Pragma("unroll") for (int m = 0; m < 4; ++m) _Pragma("unroll") for (int n = 0; n < 2; ++n) _Pragma("unroll") for (int k = 0; k < 2; ++k) \
;         acc[ai][bj][m][n] = __builtin_amdgcn_mfma_f32_16x16x32_bf16(Bt[n][k], At[m][k], acc[ai][bj][m][n], 0, 0, 0); __builtin_amdgcn_s_setprio(0); } while (0)
; #define PG8_WAIT_V(n) asm volatile("s_waitcnt vmcnt(" #n ")" ::: "memory")
; #define PG8_WAIT_L(n) asm volatile("s_waitcnt lgkmcnt(" #n ")" ::: "memory")
; #define PG8_BAR __builtin_amdgcn_s_barrier()
; #define PG8_SCHED __builtin_amdgcn_sched_barrier(0)
;     ...
;             PG8_STAGE(PG8_SB(0, 1), b2 + hstep, voffB);
;             PG8_WAIT_V(6); PG8_BAR; PG8_MMA(1, 1, At, B1); PG8_BAR;
;             PG8_LDB(B0, 1, 0); PG8_SCHED; PG8_LDA(At, 1, 0); PG8_STAGE(PG8_SA(0, 1), a2 + hstep, voffA);
;             PG8_WAIT_L(8); PG8_BAR; PG8_WAIT_L(0); PG8_MMA(0, 0, At, B0); PG8_BAR; PG8_SCHED;
;             PG8_LDB(B1, 1, 1); PG8_STAGE(PG8_SB(1, 0), b3, voffB);
;             PG8_BAR; PG8_WAIT_L(0); PG8_MMA(0, 1, At, B1); PG8_BAR;
;             PG8_LDA(At, 1, 1); PG8_STAGE(PG8_SA(1, 0), a3, voffA);
;             PG8_BAR; PG8_WAIT_L(0); PG8_MMA(1, 0, At, B0); PG8_BAR; PG8_SCHED;
	s_add_u32 s0, s8, 0x84000
	s_addc_u32 s1, s9, 0
	s_add_i32 s43, s44, s11
	v_lshl_add_u64 v[136:137], s[0:1], 0, v[64:65]
	s_mov_b32 m0, s43
	s_nop 0
	global_load_lds_dwordx4 v[136:137], off
	v_lshl_add_u64 v[136:137], s[0:1], 0, v[130:131]
	s_add_i32 m0, s43, 0x2000
	s_nop 0
	global_load_lds_dwordx4 v[136:137], off
	s_waitcnt vmcnt(6)
	s_barrier
	v_mfma_f32_16x16x32_bf16 v[52:55], v[190:193], v[158:161], v[52:55]
	v_mfma_f32_16x16x32_bf16 v[48:51], v[220:223], v[158:161], v[48:51]
	v_mfma_f32_16x16x32_bf16 v[36:39], v[190:193], v[166:169], v[36:39]
	v_mfma_f32_16x16x32_bf16 v[32:35], v[220:223], v[166:169], v[32:35]
	v_mfma_f32_16x16x32_bf16 v[20:23], v[190:193], v[174:177], v[20:23]
	v_mfma_f32_16x16x32_bf16 v[16:19], v[220:223], v[174:177], v[16:19]
	v_mfma_f32_16x16x32_bf16 v[4:7], v[190:193], v[182:185], v[4:7]
	v_mfma_f32_16x16x32_bf16 v[0:3], v[220:223], v[182:185], v[0:3]
	v_mfma_f32_16x16x32_bf16 v[52:55], v[194:197], v[162:165], v[52:55]
	v_mfma_f32_16x16x32_bf16 v[48:51], v[224:227], v[162:165], v[48:51]
	v_mfma_f32_16x16x32_bf16 v[36:39], v[194:197], v[170:173], v[36:39]
	v_mfma_f32_16x16x32_bf16 v[32:35], v[224:227], v[170:173], v[32:35]
	v_mfma_f32_16x16x32_bf16 v[20:23], v[194:197], v[178:181], v[20:23]
	v_mfma_f32_16x16x32_bf16 v[16:19], v[224:227], v[178:181], v[16:19]
	v_mfma_f32_16x16x32_bf16 v[4:7], v[194:197], v[186:189], v[4:7]
	v_mfma_f32_16x16x32_bf16 v[0:3], v[224:227], v[186:189], v[0:3]
	s_add_i32 s43, 0, 0x18000
	v_add_u32_e32 v154, s43, v143
	s_barrier
	ds_read_b128 v[136:139], v154
	ds_read_b128 v[146:149], v154 offset:1024
	ds_read_b128 v[150:153], v154 offset:2048
	ds_read_b128 v[154:157], v154 offset:3072
	s_add_u32 s0, s2, 0x84000
	s_addc_u32 s1, s3, 0
	s_mov_b32 m0, s14
	v_lshl_add_u64 v[190:191], s[0:1], 0, v[64:65]
	ds_read_b128 v[158:161], v145 offset:32768
	ds_read_b128 v[162:165], v145 offset:33792
	ds_read_b128 v[166:169], v145 offset:34816
	ds_read_b128 v[170:173], v145 offset:35840
	ds_read_b128 v[174:177], v145 offset:36864
	ds_read_b128 v[178:181], v145 offset:37888
	ds_read_b128 v[182:185], v145 offset:38912
	ds_read_b128 v[186:189], v145 offset:39936
	global_load_lds_dwordx4 v[190:191], off
	v_lshl_add_u64 v[190:191], s[0:1], 0, v[130:131]
	s_mov_b32 m0, s15
	s_nop 0
	global_load_lds_dwordx4 v[190:191], off
	s_waitcnt lgkmcnt(8)
	s_barrier
	s_waitcnt lgkmcnt(0)
	v_mfma_f32_16x16x32_bf16 v[126:129], v[136:139], v[158:161], v[126:129]
	v_mfma_f32_16x16x32_bf16 v[122:125], v[150:153], v[158:161], v[122:125]
	v_mfma_f32_16x16x32_bf16 v[110:113], v[136:139], v[166:169], v[110:113]
	v_mfma_f32_16x16x32_bf16 v[106:109], v[150:153], v[166:169], v[106:109]
	v_mfma_f32_16x16x32_bf16 v[94:97], v[136:139], v[174:177], v[94:97]
	v_mfma_f32_16x16x32_bf16 v[90:93], v[150:153], v[174:177], v[90:93]
	v_mfma_f32_16x16x32_bf16 v[78:81], v[136:139], v[182:185], v[78:81]
	v_mfma_f32_16x16x32_bf16 v[74:77], v[150:153], v[182:185], v[74:77]
	v_mfma_f32_16x16x32_bf16 v[126:129], v[146:149], v[162:165], v[126:129]
	v_mfma_f32_16x16x32_bf16 v[122:125], v[154:157], v[162:165], v[122:125]
	v_mfma_f32_16x16x32_bf16 v[110:113], v[146:149], v[170:173], v[110:113]
	v_mfma_f32_16x16x32_bf16 v[106:109], v[154:157], v[170:173], v[106:109]
	v_mfma_f32_16x16x32_bf16 v[94:97], v[146:149], v[178:181], v[94:97]
	v_mfma_f32_16x16x32_bf16 v[90:93], v[154:157], v[178:181], v[90:93]
	v_mfma_f32_16x16x32_bf16 v[78:81], v[146:149], v[186:189], v[78:81]
	v_mfma_f32_16x16x32_bf16 v[74:77], v[154:157], v[186:189], v[74:77]
	s_barrier
	s_add_i32 s2, 0, 0x1c000
	s_add_i32 s0, s43, s11
	v_add_u32_e32 v208, s2, v143
	v_lshl_add_u64 v[140:141], v[140:141], 0, s[16:17]
	s_mov_b32 m0, s0
	ds_read_b128 v[190:193], v208
	ds_read_b128 v[194:197], v208 offset:1024
	ds_read_b128 v[220:223], v208 offset:2048
	ds_read_b128 v[224:227], v208 offset:3072
	global_load_lds_dwordx4 v[140:141], off
	v_lshl_add_u64 v[140:141], v[198:199], 0, s[16:17]
	s_add_i32 m0, s0, 0x2000
	s_nop 0
	global_load_lds_dwordx4 v[140:141], off
	s_barrier
	s_waitcnt lgkmcnt(0)
	v_mfma_f32_16x16x32_bf16 v[118:121], v[190:193], v[158:161], v[118:121]
	v_mfma_f32_16x16x32_bf16 v[114:117], v[220:223], v[158:161], v[114:117]
	v_mfma_f32_16x16x32_bf16 v[102:105], v[190:193], v[166:169], v[102:105]
	v_mfma_f32_16x16x32_bf16 v[98:101], v[220:223], v[166:169], v[98:101]
	v_mfma_f32_16x16x32_bf16 v[86:89], v[190:193], v[174:177], v[86:89]
	v_mfma_f32_16x16x32_bf16 v[82:85], v[220:223], v[174:177], v[82:85]
	v_mfma_f32_16x16x32_bf16 v[70:73], v[190:193], v[182:185], v[70:73]
	v_mfma_f32_16x16x32_bf16 v[66:69], v[220:223], v[182:185], v[66:69]
	v_mfma_f32_16x16x32_bf16 v[118:121], v[194:197], v[162:165], v[118:121]
	v_mfma_f32_16x16x32_bf16 v[114:117], v[224:227], v[162:165], v[114:117]
	v_mfma_f32_16x16x32_bf16 v[102:105], v[194:197], v[170:173], v[102:105]
	v_mfma_f32_16x16x32_bf16 v[98:101], v[224:227], v[170:173], v[98:101]
	v_mfma_f32_16x16x32_bf16 v[86:89], v[194:197], v[178:181], v[86:89]
	v_mfma_f32_16x16x32_bf16 v[82:85], v[224:227], v[178:181], v[82:85]
	v_mfma_f32_16x16x32_bf16 v[70:73], v[194:197], v[186:189], v[70:73]
	v_mfma_f32_16x16x32_bf16 v[66:69], v[224:227], v[186:189], v[66:69]
	s_mov_b32 m0, s24
	v_lshl_add_u64 v[140:141], v[228:229], 0, s[16:17]
	s_barrier
; #define PG8_STAGE(bufoff, gbase, voff) do { _Pragma("unroll") for (int _i = 0; _i < 2; ++_i) \
;         __builtin_amdgcn_global_load_lds((const unsigned*)((const char*)(gbase) + (voff)[_i]), (LAS unsigned*)(lds + (bufoff) + ldsw + _i * 8192), 16, 0, 0); } while (0)
; #define PG8_MMA(ai, bj, At, Bt) do { __builtin_amdgcn_s_setprio(1); _Pragma("unroll") for (int m = 0; m < 4; ++m) _Pragma("unroll") for (int n = 0; n < 2; ++n) _Pragma("unroll") for (int k = 0; k < 2; ++k) \
;         acc[ai][bj][m][n] = __builtin_amdgcn_mfma_f32_16x16x32_bf16(Bt[n][k], At[m][k], acc[ai][bj][m][n], 0, 0, 0); __builtin_amdgcn_s_setprio(0); } while (0)
; #define PG8_WAIT_V(n) asm volatile("s_waitcnt vmcnt(" #n ")" ::: "memory")
; #define PG8_WAIT_L(n) asm volatile("s_waitcnt lgkmcnt(" #n ")" ::: "memory")
; #define PG8_BAR __builtin_amdgcn_s_barrier()
; #define PG8_SCHED __builtin_amdgcn_sched_barrier(0)
; __device__ __forceinline__ f32x4 gelu4(const f32x4 x) {
;     const f32x4 t = x * x, a = x * (t * -0.10294324f + -2.3022082f);
;     f32x4 e; e[0] = __builtin_amdgcn_exp2f(a[0]); e[1] = __builtin_amdgcn_exp2f(a[1]); e[2] = __builtin_amdgcn_exp2f(a[2]); e[3] = __builtin_amdgcn_exp2f(a[3]);
;     const f32x4 d = e + 1.0f;
;     f32x4 r; r[0] = __builtin_amdgcn_rcpf(d[0]); r[1] = __builtin_amdgcn_rcpf(d[1]); r[2] = __builtin_amdgcn_rcpf(d[2]); r[3] = __builtin_amdgcn_rcpf(d[3]);
;     return x * r;
;     ...
;             PG8_BAR; PG8_WAIT_L(0); PG8_MMA(1, 0, At, B0); PG8_BAR; PG8_SCHED;
;             PG8_STAGE(PG8_SB(1, 1), b3 + hstep, voffB);
;             PG8_WAIT_V(6); PG8_BAR; PG8_MMA(1, 1, At, B1); PG8_BAR;
;         }
	ds_read_b128 v[158:161], v145 offset:49152
	ds_read_b128 v[162:165], v145 offset:50176
	ds_read_b128 v[166:169], v145 offset:51200
	ds_read_b128 v[170:173], v145 offset:52224
	ds_read_b128 v[174:177], v145 offset:53248
	ds_read_b128 v[178:181], v145 offset:54272
	ds_read_b128 v[182:185], v145 offset:55296
	ds_read_b128 v[186:189], v145 offset:56320
	global_load_lds_dwordx4 v[140:141], off
	v_lshl_add_u64 v[140:141], v[230:231], 0, s[16:17]
	s_mov_b32 m0, s25
	s_nop 0
	global_load_lds_dwordx4 v[140:141], off
	s_barrier
	s_waitcnt lgkmcnt(0)
	v_mfma_f32_16x16x32_bf16 v[60:63], v[136:139], v[158:161], v[60:63]
	v_mfma_f32_16x16x32_bf16 v[56:59], v[150:153], v[158:161], v[56:59]
	v_mfma_f32_16x16x32_bf16 v[44:47], v[136:139], v[166:169], v[44:47]
	v_mfma_f32_16x16x32_bf16 v[40:43], v[150:153], v[166:169], v[40:43]
	v_mfma_f32_16x16x32_bf16 v[28:31], v[136:139], v[174:177], v[28:31]
	v_mfma_f32_16x16x32_bf16 v[24:27], v[150:153], v[174:177], v[24:27]
	v_mfma_f32_16x16x32_bf16 v[12:15], v[136:139], v[182:185], v[12:15]
	v_mfma_f32_16x16x32_bf16 v[8:11], v[150:153], v[182:185], v[8:11]
	v_mfma_f32_16x16x32_bf16 v[60:63], v[146:149], v[162:165], v[60:63]
	v_mfma_f32_16x16x32_bf16 v[56:59], v[154:157], v[162:165], v[56:59]
	v_mfma_f32_16x16x32_bf16 v[44:47], v[146:149], v[170:173], v[44:47]
	v_mfma_f32_16x16x32_bf16 v[40:43], v[154:157], v[170:173], v[40:43]
	v_mfma_f32_16x16x32_bf16 v[28:31], v[146:149], v[178:181], v[28:31]
	v_mfma_f32_16x16x32_bf16 v[24:27], v[154:157], v[178:181], v[24:27]
	v_mfma_f32_16x16x32_bf16 v[12:15], v[146:149], v[186:189], v[12:15]
	v_mfma_f32_16x16x32_bf16 v[8:11], v[154:157], v[186:189], v[8:11]
	s_barrier
	s_add_u32 s0, s8, 0x84080
	s_addc_u32 s1, s9, 0
	s_add_i32 s2, s2, s11
	v_lshl_add_u64 v[136:137], s[0:1], 0, v[64:65]
	s_mov_b32 m0, s2
	s_nop 0
	global_load_lds_dwordx4 v[136:137], off
	v_lshl_add_u64 v[136:137], s[0:1], 0, v[130:131]
	s_add_i32 m0, s2, 0x2000
	s_nop 0
	global_load_lds_dwordx4 v[136:137], off
	s_waitcnt vmcnt(6)
	s_barrier
	v_mfma_f32_16x16x32_bf16 v[52:55], v[190:193], v[158:161], v[52:55]
	v_mfma_f32_16x16x32_bf16 v[48:51], v[220:223], v[158:161], v[48:51]
	v_mfma_f32_16x16x32_bf16 v[36:39], v[190:193], v[166:169], v[36:39]
	v_mfma_f32_16x16x32_bf16 v[32:35], v[220:223], v[166:169], v[32:35]
	v_mfma_f32_16x16x32_bf16 v[20:23], v[190:193], v[174:177], v[20:23]
	v_mfma_f32_16x16x32_bf16 v[16:19], v[220:223], v[174:177], v[16:19]
	v_mfma_f32_16x16x32_bf16 v[4:7], v[190:193], v[182:185], v[4:7]
	v_mfma_f32_16x16x32_bf16 v[0:3], v[220:223], v[182:185], v[0:3]
	v_mfma_f32_16x16x32_bf16 v[52:55], v[194:197], v[162:165], v[52:55]
	v_mfma_f32_16x16x32_bf16 v[48:51], v[224:227], v[162:165], v[48:51]
	v_mfma_f32_16x16x32_bf16 v[36:39], v[194:197], v[170:173], v[36:39]
	v_mfma_f32_16x16x32_bf16 v[32:35], v[224:227], v[170:173], v[32:35]
	v_mfma_f32_16x16x32_bf16 v[20:23], v[194:197], v[178:181], v[20:23]
	v_mfma_f32_16x16x32_bf16 v[16:19], v[224:227], v[178:181], v[16:19]
	v_mfma_f32_16x16x32_bf16 v[4:7], v[194:197], v[186:189], v[4:7]
	v_mfma_f32_16x16x32_bf16 v[0:3], v[224:227], v[186:189], v[0:3]
	s_add_i32 s42, s42, 2
	s_add_u32 s40, s40, 0x100
	s_addc_u32 s41, s41, 0
	s_cmp_gt_u32 s42, 29
	s_mov_b64 s[0:1], s[4:5]
	s_barrier
	s_cbranch_scc0 .LBB0_1441
	s_add_i32 s0, s38, -2
	s_cmp_lt_u32 s0, 8
	s_cselect_b64 s[2:3], -1, 0
	s_cmp_gt_u32 s0, 7
	s_cbranch_scc1 .LBB0_1444
	s_mov_b32 s40, 0xc0135761
	v_pk_mul_f32 v[136:137], v[128:129], v[128:129]
	v_pk_mul_f32 v[138:139], v[126:127], v[126:127]
	v_mov_b64_e32 v[140:141], s[40:41]
	s_mov_b32 s0, 0xbdd2d3e8
	v_pk_fma_f32 v[136:137], v[136:137], s[0:1], v[140:141] op_sel_hi:[1,0,0]
	v_pk_fma_f32 v[138:139], v[138:139], s[0:1], v[140:141] op_sel_hi:[1,0,0]
	v_pk_mul_f32 v[136:137], v[128:129], v[136:137]
	v_pk_mul_f32 v[138:139], v[126:127], v[138:139]
	v_exp_f32_e32 v136, v136
	v_exp_f32_e32 v138, v138
	v_exp_f32_e32 v137, v137
	v_exp_f32_e32 v139, v139
	v_pk_add_f32 v[136:137], v[136:137], 1.0 op_sel_hi:[1,0]
	v_pk_add_f32 v[138:139], v[138:139], 1.0 op_sel_hi:[1,0]
	v_rcp_f32_e32 v136, v136
	v_rcp_f32_e32 v138, v138
	v_rcp_f32_e32 v137, v137
	v_rcp_f32_e32 v139, v139
	v_pk_mul_f32 v[128:129], v[128:129], v[136:137]
	v_pk_mul_f32 v[126:127], v[126:127], v[138:139]
	s_branch .LBB0_1445
